# GEMM MFMA blocks reordered so one fragment operand stays constant over 4 consecutive MFMAs (snake order); plus global_* ops and deferred SSQ atomics
# baseline (speedup 1.0000x reference)
; #define PG8_STAGE(bufoff, gbase, voff) do { _Pragma("unroll") for (int _i = 0; _i < 2; ++_i) \
;         __builtin_amdgcn_global_load_lds((const unsigned*)((const char*)(gbase) + (voff)[_i]), (PG8_LAS unsigned*)(lds + (bufoff) + ldsw + _i * 8192), 16, 0, 0); } while (0)
; #define PG8_LDA(dst, b, h) do { _Pragma("unroll") for (int m = 0; m < 4; ++m) _Pragma("unroll") for (int k = 0; k < 2; ++k) dst[m][k] = *(const PG8_LAS bf16x8*)(lds + PG8_SA(b, h) + aoff + m * 2048 + k * 1024); } while (0)
; #define PG8_LDB(dst, b, h) do { _Pragma("unroll") for (int n = 0; n < 2; ++n) _Pragma("unroll") for (int k = 0; k < 2; ++k) dst[n][k] = *(const PG8_LAS bf16x8*)(lds + PG8_SB(b, h) + boff + n * 2048 + k * 1024); } while (0)
; #define PG8_MMA(ai, bj, At, Bt) do { __builtin_amdgcn_s_setprio(1); _Pragma("unroll") for (int m = 0; m < 4; ++m) _Pragma("unroll") for (int n = 0; n < 2; ++n) _Pragma("unroll") for (int k = 0; k < 2; ++k) \
;         acc[ai][bj][m][n] = __builtin_amdgcn_mfma_f32_16x16x32_bf16(Bt[n][k], At[m][k], acc[ai][bj][m][n], 0, 0, 0); __builtin_amdgcn_s_setprio(0); } while (0)
; #define PG8_BAR __builtin_amdgcn_s_barrier()
; template <class Epi, class Sched, bool ALIGN_EPI = false, bool SP2 = false>
; __device__ __forceinline__ void gemm_phase(PG8_LAS unsigned char* lds, const Gemm g, const Sched& S, const Epi& E, const int wid) {
;     ...
;             PG8_LDB(B0, 0, 0); PG8_LDB(B1, 0, 1); PG8_SCHED; PG8_LDA(At, 0, 0); PG8_STAGE(PG8_SA(1, 1), a1 + hsA, voffA);
;             PG8_WAIT_V(8); PG8_WAIT_L(0); PG8_BAR; PG8_MMA(0, 0, At, B0); PG8_MMA(0, 1, At, B1); PG8_BAR; PG8_SCHED;
;             PG8_LDA(At, 0, 1); PG8_STAGE(PG8_SB(0, 0), b2, voffB); PG8_STAGE(PG8_SB(0, 1), b2 + hsB, voffB); PG8_STAGE(PG8_SA(0, 0), a2, voffA);
;             PG8_WAIT_V(8); PG8_WAIT_L(0); PG8_BAR; PG8_MMA(1, 0, At, B0); PG8_MMA(1, 1, At, B1); PG8_BAR; PG8_SCHED;
;             PG8_LDB(B0, 1, 0); PG8_LDB(B1, 1, 1); PG8_SCHED; PG8_LDA(At, 1, 0); PG8_STAGE(PG8_SA(0, 1), a2 + hsA, voffA);
;             PG8_WAIT_V(8); PG8_WAIT_L(0); PG8_BAR; PG8_MMA(0, 0, At, B0); PG8_MMA(0, 1, At, B1); PG8_BAR; PG8_SCHED;
;             PG8_LDA(At, 1, 1); PG8_STAGE(PG8_SB(1, 0), b3, voffB); PG8_STAGE(PG8_SB(1, 1), b3 + hsB, voffB); PG8_STAGE(PG8_SA(1, 0), a3, voffA);
;             PG8_WAIT_V(8); PG8_WAIT_L(0); PG8_BAR; PG8_MMA(1, 0, At, B0); PG8_MMA(1, 1, At, B1); PG8_BAR; PG8_SCHED;
.LBB0_418:
	ds_read_b128 v[144:147], v149
	ds_read_b128 v[152:155], v149 offset:1024
	ds_read_b128 v[156:159], v149 offset:2048
	ds_read_b128 v[160:163], v149 offset:3072
	ds_read_b128 v[164:167], v150
	ds_read_b128 v[168:171], v150 offset:1024
	ds_read_b128 v[172:175], v150 offset:2048
	ds_read_b128 v[176:179], v150 offset:3072
	s_add_u32 s26, s24, 0xfff80080
	s_addc_u32 s27, s25, -1
	s_cmp_eq_u32 s55, 28
	s_cselect_b32 s29, s17, s27
	s_cselect_b32 s28, s51, s26
	s_cselect_b32 s27, s15, s54
	s_cselect_b32 s26, s52, s53
	v_lshl_add_u64 v[212:213], s[24:25], 0, v[138:139]
	s_add_i32 m0, s23, 0xc000
	ds_read_b128 v[180:183], v151
	ds_read_b128 v[184:187], v151 offset:1024
	ds_read_b128 v[188:191], v151 offset:2048
	ds_read_b128 v[192:195], v151 offset:3072
	ds_read_b128 v[196:199], v151 offset:4096
	ds_read_b128 v[200:203], v151 offset:5120
	ds_read_b128 v[204:207], v151 offset:6144
	ds_read_b128 v[208:211], v151 offset:7168
	global_load_lds_dwordx4 v[212:213], off
	v_lshl_add_u64 v[212:213], s[24:25], 0, v[136:137]
	s_add_i32 m0, s23, 0xe000
	s_nop 0
	global_load_lds_dwordx4 v[212:213], off
	s_waitcnt vmcnt(8)
	s_waitcnt lgkmcnt(0)
	s_barrier
	s_setprio 1
	s_waitcnt lgkmcnt(0)
	v_mfma_f32_16x16x32_bf16 v[124:127], v[144:147], v[180:183], v[124:127]
	v_mfma_f32_16x16x32_bf16 v[108:111], v[144:147], v[188:191], v[108:111]
	v_mfma_f32_16x16x32_bf16 v[92:95], v[144:147], v[196:199], v[92:95]
	v_mfma_f32_16x16x32_bf16 v[76:79], v[144:147], v[204:207], v[76:79]
	v_mfma_f32_16x16x32_bf16 v[72:75], v[156:159], v[204:207], v[72:75]
	v_mfma_f32_16x16x32_bf16 v[88:91], v[156:159], v[196:199], v[88:91]
	v_mfma_f32_16x16x32_bf16 v[104:107], v[156:159], v[188:191], v[104:107]
	v_mfma_f32_16x16x32_bf16 v[120:123], v[156:159], v[180:183], v[120:123]
	v_mfma_f32_16x16x32_bf16 v[124:127], v[152:155], v[184:187], v[124:127]
	v_mfma_f32_16x16x32_bf16 v[108:111], v[152:155], v[192:195], v[108:111]
	v_mfma_f32_16x16x32_bf16 v[92:95], v[152:155], v[200:203], v[92:95]
	v_mfma_f32_16x16x32_bf16 v[76:79], v[152:155], v[208:211], v[76:79]
	v_mfma_f32_16x16x32_bf16 v[72:75], v[160:163], v[208:211], v[72:75]
	v_mfma_f32_16x16x32_bf16 v[88:91], v[160:163], v[200:203], v[88:91]
	v_mfma_f32_16x16x32_bf16 v[104:107], v[160:163], v[192:195], v[104:107]
	v_mfma_f32_16x16x32_bf16 v[120:123], v[160:163], v[184:187], v[120:123]
	s_setprio 0
	s_setprio 1
	v_mfma_f32_16x16x32_bf16 v[116:119], v[164:167], v[180:183], v[116:119]
	v_mfma_f32_16x16x32_bf16 v[100:103], v[164:167], v[188:191], v[100:103]
	v_mfma_f32_16x16x32_bf16 v[84:87], v[164:167], v[196:199], v[84:87]
	v_mfma_f32_16x16x32_bf16 v[68:71], v[164:167], v[204:207], v[68:71]
	v_mfma_f32_16x16x32_bf16 v[64:67], v[172:175], v[204:207], v[64:67]
	v_mfma_f32_16x16x32_bf16 v[80:83], v[172:175], v[196:199], v[80:83]
	v_mfma_f32_16x16x32_bf16 v[96:99], v[172:175], v[188:191], v[96:99]
	v_mfma_f32_16x16x32_bf16 v[112:115], v[172:175], v[180:183], v[112:115]
	v_mfma_f32_16x16x32_bf16 v[116:119], v[168:171], v[184:187], v[116:119]
	v_mfma_f32_16x16x32_bf16 v[100:103], v[168:171], v[192:195], v[100:103]
	v_mfma_f32_16x16x32_bf16 v[84:87], v[168:171], v[200:203], v[84:87]
	v_mfma_f32_16x16x32_bf16 v[68:71], v[168:171], v[208:211], v[68:71]
	v_mfma_f32_16x16x32_bf16 v[64:67], v[176:179], v[208:211], v[64:67]
	v_mfma_f32_16x16x32_bf16 v[80:83], v[176:179], v[200:203], v[80:83]
	v_mfma_f32_16x16x32_bf16 v[96:99], v[176:179], v[192:195], v[96:99]
	v_mfma_f32_16x16x32_bf16 v[112:115], v[176:179], v[184:187], v[112:115]
	s_setprio 0
	s_barrier
	s_add_i32 s56, s47, s34
	v_lshl_add_u64 v[212:213], s[26:27], 0, v[132:133]
	s_mov_b32 m0, s56
	ds_read_b128 v[180:183], v151 offset:16384
	ds_read_b128 v[184:187], v151 offset:17408
	ds_read_b128 v[188:191], v151 offset:18432
	ds_read_b128 v[192:195], v151 offset:19456
	ds_read_b128 v[196:199], v151 offset:20480
	ds_read_b128 v[200:203], v151 offset:21504
	ds_read_b128 v[204:207], v151 offset:22528
	ds_read_b128 v[208:211], v151 offset:23552
	global_load_lds_dwordx4 v[212:213], off
	s_add_i32 m0, s56, 0x2000
	s_add_u32 s56, s26, 0x80000
	v_lshl_add_u64 v[214:215], s[26:27], 0, v[128:129]
	s_addc_u32 s57, s27, 0
	s_add_i32 s58, s48, s34
	global_load_lds_dwordx4 v[214:215], off
	v_lshl_add_u64 v[216:217], s[56:57], 0, v[132:133]
	s_mov_b32 m0, s58
	v_lshl_add_u64 v[218:219], s[28:29], 0, v[130:131]
	global_load_lds_dwordx4 v[216:217], off
	v_lshl_add_u64 v[216:217], s[56:57], 0, v[128:129]
	s_add_i32 m0, s58, 0x2000
	s_nop 0
	global_load_lds_dwordx4 v[216:217], off
	v_lshl_add_u64 v[216:217], s[28:29], 0, v[134:135]
	s_mov_b32 m0, s23
	s_nop 0
	global_load_lds_dwordx4 v[216:217], off
	s_mov_b32 m0, s37
	s_nop 0
	global_load_lds_dwordx4 v[218:219], off
	s_waitcnt vmcnt(8)
	s_waitcnt lgkmcnt(0)
	s_barrier
; #define PG8_STAGE(bufoff, gbase, voff) do { _Pragma("unroll") for (int _i = 0; _i < 2; ++_i) \
;         __builtin_amdgcn_global_load_lds((const unsigned*)((const char*)(gbase) + (voff)[_i]), (PG8_LAS unsigned*)(lds + (bufoff) + ldsw + _i * 8192), 16, 0, 0); } while (0)
; #define PG8_LDA(dst, b, h) do { _Pragma("unroll") for (int m = 0; m < 4; ++m) _Pragma("unroll") for (int k = 0; k < 2; ++k) dst[m][k] = *(const PG8_LAS bf16x8*)(lds + PG8_SA(b, h) + aoff + m * 2048 + k * 1024); } while (0)
; #define PG8_LDB(dst, b, h) do { _Pragma("unroll") for (int n = 0; n < 2; ++n) _Pragma("unroll") for (int k = 0; k < 2; ++k) dst[n][k] = *(const PG8_LAS bf16x8*)(lds + PG8_SB(b, h) + boff + n * 2048 + k * 1024); } while (0)
; #define PG8_MMA(ai, bj, At, Bt) do { __builtin_amdgcn_s_setprio(1); _Pragma("unroll") for (int m = 0; m < 4; ++m) _Pragma("unroll") for (int n = 0; n < 2; ++n) _Pragma("unroll") for (int k = 0; k < 2; ++k) \
;         acc[ai][bj][m][n] = __builtin_amdgcn_mfma_f32_16x16x32_bf16(Bt[n][k], At[m][k], acc[ai][bj][m][n], 0, 0, 0); __builtin_amdgcn_s_setprio(0); } while (0)
; #define PG8_BAR __builtin_amdgcn_s_barrier()
; template <class Epi, class Sched, bool ALIGN_EPI = false, bool SP2 = false>
; __device__ __forceinline__ void gemm_phase(PG8_LAS unsigned char* lds, const Gemm g, const Sched& S, const Epi& E, const int wid) {
;     ...
;             PG8_LDB(B0, 0, 0); PG8_LDB(B1, 0, 1); PG8_SCHED; PG8_LDA(At, 0, 0); PG8_STAGE(PG8_SA(1, 1), a1 + hsA, voffA);
;             PG8_WAIT_V(8); PG8_WAIT_L(0); PG8_BAR; PG8_MMA(0, 0, At, B0); PG8_MMA(0, 1, At, B1); PG8_BAR; PG8_SCHED;
;             PG8_LDA(At, 0, 1); PG8_STAGE(PG8_SB(0, 0), b2, voffB); PG8_STAGE(PG8_SB(0, 1), b2 + hsB, voffB); PG8_STAGE(PG8_SA(0, 0), a2, voffA);
;             PG8_WAIT_V(8); PG8_WAIT_L(0); PG8_BAR; PG8_MMA(1, 0, At, B0); PG8_MMA(1, 1, At, B1); PG8_BAR; PG8_SCHED;
;             PG8_LDB(B0, 1, 0); PG8_LDB(B1, 1, 1); PG8_SCHED; PG8_LDA(At, 1, 0); PG8_STAGE(PG8_SA(0, 1), a2 + hsA, voffA);
;             PG8_WAIT_V(8); PG8_WAIT_L(0); PG8_BAR; PG8_MMA(0, 0, At, B0); PG8_MMA(0, 1, At, B1); PG8_BAR; PG8_SCHED;
;             PG8_LDA(At, 1, 1); PG8_STAGE(PG8_SB(1, 0), b3, voffB); PG8_STAGE(PG8_SB(1, 1), b3 + hsB, voffB); PG8_STAGE(PG8_SA(1, 0), a3, voffA);
;             PG8_WAIT_V(8); PG8_WAIT_L(0); PG8_BAR; PG8_MMA(1, 0, At, B0); PG8_MMA(1, 1, At, B1); PG8_BAR; PG8_SCHED;
	s_setprio 1
	s_waitcnt lgkmcnt(0)
	v_mfma_f32_16x16x32_bf16 v[60:63], v[144:147], v[180:183], v[60:63]
	v_mfma_f32_16x16x32_bf16 v[44:47], v[144:147], v[188:191], v[44:47]
	v_mfma_f32_16x16x32_bf16 v[28:31], v[144:147], v[196:199], v[28:31]
	v_mfma_f32_16x16x32_bf16 v[12:15], v[144:147], v[204:207], v[12:15]
	v_mfma_f32_16x16x32_bf16 v[8:11], v[156:159], v[204:207], v[8:11]
	v_mfma_f32_16x16x32_bf16 v[24:27], v[156:159], v[196:199], v[24:27]
	v_mfma_f32_16x16x32_bf16 v[40:43], v[156:159], v[188:191], v[40:43]
	v_mfma_f32_16x16x32_bf16 v[56:59], v[156:159], v[180:183], v[56:59]
	v_mfma_f32_16x16x32_bf16 v[60:63], v[152:155], v[184:187], v[60:63]
	v_mfma_f32_16x16x32_bf16 v[44:47], v[152:155], v[192:195], v[44:47]
	v_mfma_f32_16x16x32_bf16 v[28:31], v[152:155], v[200:203], v[28:31]
	v_mfma_f32_16x16x32_bf16 v[12:15], v[152:155], v[208:211], v[12:15]
	v_mfma_f32_16x16x32_bf16 v[8:11], v[160:163], v[208:211], v[8:11]
	v_mfma_f32_16x16x32_bf16 v[24:27], v[160:163], v[200:203], v[24:27]
	v_mfma_f32_16x16x32_bf16 v[40:43], v[160:163], v[192:195], v[40:43]
	v_mfma_f32_16x16x32_bf16 v[56:59], v[160:163], v[184:187], v[56:59]
	s_setprio 0
	s_setprio 1
	v_mfma_f32_16x16x32_bf16 v[52:55], v[164:167], v[180:183], v[52:55]
	v_mfma_f32_16x16x32_bf16 v[36:39], v[164:167], v[188:191], v[36:39]
	v_mfma_f32_16x16x32_bf16 v[20:23], v[164:167], v[196:199], v[20:23]
	v_mfma_f32_16x16x32_bf16 v[4:7], v[164:167], v[204:207], v[4:7]
	v_mfma_f32_16x16x32_bf16 v[0:3], v[172:175], v[204:207], v[0:3]
	v_mfma_f32_16x16x32_bf16 v[16:19], v[172:175], v[196:199], v[16:19]
	v_mfma_f32_16x16x32_bf16 v[32:35], v[172:175], v[188:191], v[32:35]
	v_mfma_f32_16x16x32_bf16 v[48:51], v[172:175], v[180:183], v[48:51]
	v_mfma_f32_16x16x32_bf16 v[52:55], v[168:171], v[184:187], v[52:55]
	v_mfma_f32_16x16x32_bf16 v[36:39], v[168:171], v[192:195], v[36:39]
	v_mfma_f32_16x16x32_bf16 v[20:23], v[168:171], v[200:203], v[20:23]
	v_mfma_f32_16x16x32_bf16 v[4:7], v[168:171], v[208:211], v[4:7]
	v_mfma_f32_16x16x32_bf16 v[0:3], v[176:179], v[208:211], v[0:3]
	v_mfma_f32_16x16x32_bf16 v[16:19], v[176:179], v[200:203], v[16:19]
	v_mfma_f32_16x16x32_bf16 v[32:35], v[176:179], v[192:195], v[32:35]
	v_mfma_f32_16x16x32_bf16 v[48:51], v[176:179], v[184:187], v[48:51]
	s_setprio 0
	s_barrier
	s_add_i32 s56, 0, 0x18000
	s_add_i32 s57, 0, 0x1c000
	v_add_u32_e32 v160, s56, v148
	v_add_u32_e32 v176, s57, v148
	ds_read_b128 v[144:147], v160
	ds_read_b128 v[152:155], v160 offset:1024
	ds_read_b128 v[156:159], v160 offset:2048
	ds_read_b128 v[160:163], v160 offset:3072
	ds_read_b128 v[164:167], v176
	ds_read_b128 v[168:171], v176 offset:1024
	ds_read_b128 v[172:175], v176 offset:2048
	ds_read_b128 v[176:179], v176 offset:3072
	s_add_u32 s28, s28, 0x80000
	s_addc_u32 s29, s29, 0
	s_mov_b32 m0, s38
	v_lshl_add_u64 v[220:221], s[28:29], 0, v[134:135]
	ds_read_b128 v[180:183], v151 offset:32768
	ds_read_b128 v[184:187], v151 offset:33792
	ds_read_b128 v[188:191], v151 offset:34816
	ds_read_b128 v[192:195], v151 offset:35840
	ds_read_b128 v[196:199], v151 offset:36864
	ds_read_b128 v[200:203], v151 offset:37888
	ds_read_b128 v[204:207], v151 offset:38912
	ds_read_b128 v[208:211], v151 offset:39936
	global_load_lds_dwordx4 v[220:221], off
	v_lshl_add_u64 v[220:221], s[28:29], 0, v[130:131]
	s_mov_b32 m0, s39
	s_nop 0
	global_load_lds_dwordx4 v[220:221], off
	s_waitcnt vmcnt(8)
	s_waitcnt lgkmcnt(0)
	s_barrier
	s_setprio 1
	s_waitcnt lgkmcnt(0)
	v_mfma_f32_16x16x32_bf16 v[124:127], v[144:147], v[180:183], v[124:127]
	v_mfma_f32_16x16x32_bf16 v[108:111], v[144:147], v[188:191], v[108:111]
	v_mfma_f32_16x16x32_bf16 v[92:95], v[144:147], v[196:199], v[92:95]
	v_mfma_f32_16x16x32_bf16 v[76:79], v[144:147], v[204:207], v[76:79]
	v_mfma_f32_16x16x32_bf16 v[72:75], v[156:159], v[204:207], v[72:75]
	v_mfma_f32_16x16x32_bf16 v[88:91], v[156:159], v[196:199], v[88:91]
	v_mfma_f32_16x16x32_bf16 v[104:107], v[156:159], v[188:191], v[104:107]
	v_mfma_f32_16x16x32_bf16 v[120:123], v[156:159], v[180:183], v[120:123]
	v_mfma_f32_16x16x32_bf16 v[124:127], v[152:155], v[184:187], v[124:127]
	v_mfma_f32_16x16x32_bf16 v[108:111], v[152:155], v[192:195], v[108:111]
	v_mfma_f32_16x16x32_bf16 v[92:95], v[152:155], v[200:203], v[92:95]
	v_mfma_f32_16x16x32_bf16 v[76:79], v[152:155], v[208:211], v[76:79]
	v_mfma_f32_16x16x32_bf16 v[72:75], v[160:163], v[208:211], v[72:75]
	v_mfma_f32_16x16x32_bf16 v[88:91], v[160:163], v[200:203], v[88:91]
	v_mfma_f32_16x16x32_bf16 v[104:107], v[160:163], v[192:195], v[104:107]
	v_mfma_f32_16x16x32_bf16 v[120:123], v[160:163], v[184:187], v[120:123]
	s_setprio 0
	s_setprio 1
	v_mfma_f32_16x16x32_bf16 v[116:119], v[164:167], v[180:183], v[116:119]
	v_mfma_f32_16x16x32_bf16 v[100:103], v[164:167], v[188:191], v[100:103]
	v_mfma_f32_16x16x32_bf16 v[84:87], v[164:167], v[196:199], v[84:87]
	v_mfma_f32_16x16x32_bf16 v[68:71], v[164:167], v[204:207], v[68:71]
	v_mfma_f32_16x16x32_bf16 v[64:67], v[172:175], v[204:207], v[64:67]
	v_mfma_f32_16x16x32_bf16 v[80:83], v[172:175], v[196:199], v[80:83]
	v_mfma_f32_16x16x32_bf16 v[96:99], v[172:175], v[188:191], v[96:99]
	v_mfma_f32_16x16x32_bf16 v[112:115], v[172:175], v[180:183], v[112:115]
	v_mfma_f32_16x16x32_bf16 v[116:119], v[168:171], v[184:187], v[116:119]
	v_mfma_f32_16x16x32_bf16 v[100:103], v[168:171], v[192:195], v[100:103]
	v_mfma_f32_16x16x32_bf16 v[84:87], v[168:171], v[200:203], v[84:87]
	v_mfma_f32_16x16x32_bf16 v[68:71], v[168:171], v[208:211], v[68:71]
	v_mfma_f32_16x16x32_bf16 v[64:67], v[176:179], v[208:211], v[64:67]
	v_mfma_f32_16x16x32_bf16 v[80:83], v[176:179], v[200:203], v[80:83]
	v_mfma_f32_16x16x32_bf16 v[96:99], v[176:179], v[192:195], v[96:99]
	v_mfma_f32_16x16x32_bf16 v[112:115], v[176:179], v[184:187], v[112:115]
	s_setprio 0
	s_barrier
; #define PG8_STAGE(bufoff, gbase, voff) do { _Pragma("unroll") for (int _i = 0; _i < 2; ++_i) \
;         __builtin_amdgcn_global_load_lds((const unsigned*)((const char*)(gbase) + (voff)[_i]), (PG8_LAS unsigned*)(lds + (bufoff) + ldsw + _i * 8192), 16, 0, 0); } while (0)
; #define PG8_LDA(dst, b, h) do { _Pragma("unroll") for (int m = 0; m < 4; ++m) _Pragma("unroll") for (int k = 0; k < 2; ++k) dst[m][k] = *(const PG8_LAS bf16x8*)(lds + PG8_SA(b, h) + aoff + m * 2048 + k * 1024); } while (0)
; #define PG8_LDB(dst, b, h) do { _Pragma("unroll") for (int n = 0; n < 2; ++n) _Pragma("unroll") for (int k = 0; k < 2; ++k) dst[n][k] = *(const PG8_LAS bf16x8*)(lds + PG8_SB(b, h) + boff + n * 2048 + k * 1024); } while (0)
; #define PG8_MMA(ai, bj, At, Bt) do { __builtin_amdgcn_s_setprio(1); _Pragma("unroll") for (int m = 0; m < 4; ++m) _Pragma("unroll") for (int n = 0; n < 2; ++n) _Pragma("unroll") for (int k = 0; k < 2; ++k) \
;         acc[ai][bj][m][n] = __builtin_amdgcn_mfma_f32_16x16x32_bf16(Bt[n][k], At[m][k], acc[ai][bj][m][n], 0, 0, 0); __builtin_amdgcn_s_setprio(0); } while (0)
; #define PG8_BAR __builtin_amdgcn_s_barrier()
; template <class Epi, class Sched, bool ALIGN_EPI = false, bool SP2 = false>
; __device__ __forceinline__ void gemm_phase(PG8_LAS unsigned char* lds, const Gemm g, const Sched& S, const Epi& E, const int wid) {
;     ...
;             PG8_LDB(B0, 0, 0); PG8_LDB(B1, 0, 1); PG8_SCHED; PG8_LDA(At, 0, 0); PG8_STAGE(PG8_SA(1, 1), a1 + hsA, voffA);
;             PG8_WAIT_V(8); PG8_WAIT_L(0); PG8_BAR; PG8_MMA(0, 0, At, B0); PG8_MMA(0, 1, At, B1); PG8_BAR; PG8_SCHED;
;             PG8_LDA(At, 0, 1); PG8_STAGE(PG8_SB(0, 0), b2, voffB); PG8_STAGE(PG8_SB(0, 1), b2 + hsB, voffB); PG8_STAGE(PG8_SA(0, 0), a2, voffA);
;             PG8_WAIT_V(8); PG8_WAIT_L(0); PG8_BAR; PG8_MMA(1, 0, At, B0); PG8_MMA(1, 1, At, B1); PG8_BAR; PG8_SCHED;
;             PG8_LDB(B0, 1, 0); PG8_LDB(B1, 1, 1); PG8_SCHED; PG8_LDA(At, 1, 0); PG8_STAGE(PG8_SA(0, 1), a2 + hsA, voffA);
;             PG8_WAIT_V(8); PG8_WAIT_L(0); PG8_BAR; PG8_MMA(0, 0, At, B0); PG8_MMA(0, 1, At, B1); PG8_BAR; PG8_SCHED;
;             PG8_LDA(At, 1, 1); PG8_STAGE(PG8_SB(1, 0), b3, voffB); PG8_STAGE(PG8_SB(1, 1), b3 + hsB, voffB); PG8_STAGE(PG8_SA(1, 0), a3, voffA);
;             PG8_WAIT_V(8); PG8_WAIT_L(0); PG8_BAR; PG8_MMA(1, 0, At, B0); PG8_MMA(1, 1, At, B1); PG8_BAR; PG8_SCHED;
	s_add_i32 s28, s56, s34
	v_lshl_add_u64 v[212:213], v[212:213], 0, s[10:11]
	s_mov_b32 m0, s28
	ds_read_b128 v[180:183], v151 offset:49152
	ds_read_b128 v[184:187], v151 offset:50176
	ds_read_b128 v[188:191], v151 offset:51200
	ds_read_b128 v[192:195], v151 offset:52224
	ds_read_b128 v[196:199], v151 offset:53248
	ds_read_b128 v[200:203], v151 offset:54272
	ds_read_b128 v[204:207], v151 offset:55296
	ds_read_b128 v[208:211], v151 offset:56320
	global_load_lds_dwordx4 v[212:213], off
	s_add_i32 m0, s28, 0x2000
	s_add_u32 s26, s26, 0x80080
	v_lshl_add_u64 v[212:213], v[214:215], 0, s[10:11]
	s_addc_u32 s27, s27, 0
	s_add_i32 s28, s57, s34
	global_load_lds_dwordx4 v[212:213], off
	v_lshl_add_u64 v[212:213], s[26:27], 0, v[132:133]
	s_mov_b32 m0, s28
	s_nop 0
	global_load_lds_dwordx4 v[212:213], off
	v_lshl_add_u64 v[212:213], s[26:27], 0, v[128:129]
	s_add_i32 m0, s28, 0x2000
	s_nop 0
	global_load_lds_dwordx4 v[212:213], off
	v_lshl_add_u64 v[212:213], v[216:217], 0, s[10:11]
	s_mov_b32 m0, s42
	s_nop 0
	global_load_lds_dwordx4 v[212:213], off
	v_lshl_add_u64 v[212:213], v[218:219], 0, s[10:11]
	s_mov_b32 m0, s43
	s_nop 0
	global_load_lds_dwordx4 v[212:213], off
	s_waitcnt vmcnt(8)
	s_waitcnt lgkmcnt(0)
	s_barrier
	s_setprio 1
	s_waitcnt lgkmcnt(0)
	v_mfma_f32_16x16x32_bf16 v[60:63], v[144:147], v[180:183], v[60:63]
	v_mfma_f32_16x16x32_bf16 v[44:47], v[144:147], v[188:191], v[44:47]
	v_mfma_f32_16x16x32_bf16 v[28:31], v[144:147], v[196:199], v[28:31]
	v_mfma_f32_16x16x32_bf16 v[12:15], v[144:147], v[204:207], v[12:15]
	v_mfma_f32_16x16x32_bf16 v[8:11], v[156:159], v[204:207], v[8:11]
	v_mfma_f32_16x16x32_bf16 v[24:27], v[156:159], v[196:199], v[24:27]
	v_mfma_f32_16x16x32_bf16 v[40:43], v[156:159], v[188:191], v[40:43]
	v_mfma_f32_16x16x32_bf16 v[56:59], v[156:159], v[180:183], v[56:59]
	v_mfma_f32_16x16x32_bf16 v[60:63], v[152:155], v[184:187], v[60:63]
	v_mfma_f32_16x16x32_bf16 v[44:47], v[152:155], v[192:195], v[44:47]
	v_mfma_f32_16x16x32_bf16 v[28:31], v[152:155], v[200:203], v[28:31]
	v_mfma_f32_16x16x32_bf16 v[12:15], v[152:155], v[208:211], v[12:15]
	v_mfma_f32_16x16x32_bf16 v[8:11], v[160:163], v[208:211], v[8:11]
	v_mfma_f32_16x16x32_bf16 v[24:27], v[160:163], v[200:203], v[24:27]
	v_mfma_f32_16x16x32_bf16 v[40:43], v[160:163], v[192:195], v[40:43]
	v_mfma_f32_16x16x32_bf16 v[56:59], v[160:163], v[184:187], v[56:59]
	s_setprio 0
	s_setprio 1
	v_mfma_f32_16x16x32_bf16 v[52:55], v[164:167], v[180:183], v[52:55]
	v_mfma_f32_16x16x32_bf16 v[36:39], v[164:167], v[188:191], v[36:39]
	v_mfma_f32_16x16x32_bf16 v[20:23], v[164:167], v[196:199], v[20:23]
	v_mfma_f32_16x16x32_bf16 v[4:7], v[164:167], v[204:207], v[4:7]
	v_mfma_f32_16x16x32_bf16 v[0:3], v[172:175], v[204:207], v[0:3]
	v_mfma_f32_16x16x32_bf16 v[16:19], v[172:175], v[196:199], v[16:19]
	v_mfma_f32_16x16x32_bf16 v[32:35], v[172:175], v[188:191], v[32:35]
	v_mfma_f32_16x16x32_bf16 v[48:51], v[172:175], v[180:183], v[48:51]
	v_mfma_f32_16x16x32_bf16 v[52:55], v[168:171], v[184:187], v[52:55]
	v_mfma_f32_16x16x32_bf16 v[36:39], v[168:171], v[192:195], v[36:39]
	v_mfma_f32_16x16x32_bf16 v[20:23], v[168:171], v[200:203], v[20:23]
	v_mfma_f32_16x16x32_bf16 v[4:7], v[168:171], v[208:211], v[4:7]
	v_mfma_f32_16x16x32_bf16 v[0:3], v[176:179], v[208:211], v[0:3]
	v_mfma_f32_16x16x32_bf16 v[16:19], v[176:179], v[200:203], v[16:19]
	v_mfma_f32_16x16x32_bf16 v[32:35], v[176:179], v[192:195], v[32:35]
	v_mfma_f32_16x16x32_bf16 v[48:51], v[176:179], v[184:187], v[48:51]
	s_setprio 0
	s_barrier
	s_add_i32 s55, s55, 2
	s_add_u32 s53, s53, 0x100
	s_addc_u32 s54, s54, 0
	s_add_u32 s24, s24, 0x100
	s_addc_u32 s25, s25, 0
	s_cmp_gt_u32 s55, 29
	s_cbranch_scc0 .LBB0_418
	s_and_b64 vcc, exec, s[12:13]
	s_cbranch_vccz .LBB0_421
	s_barrier

; #define PG8_STAGE(bufoff, gbase, voff) do { _Pragma("unroll") for (int _i = 0; _i < 2; ++_i) \
;         __builtin_amdgcn_global_load_lds((const unsigned*)((const char*)(gbase) + (voff)[_i]), (PG8_LAS unsigned*)(lds + (bufoff) + ldsw + _i * 8192), 16, 0, 0); } while (0)
; #define PG8_LDA(dst, b, h) do { _Pragma("unroll") for (int m = 0; m < 4; ++m) _Pragma("unroll") for (int k = 0; k < 2; ++k) dst[m][k] = *(const PG8_LAS bf16x8*)(lds + PG8_SA(b, h) + aoff + m * 2048 + k * 1024); } while (0)
; #define PG8_LDB(dst, b, h) do { _Pragma("unroll") for (int n = 0; n < 2; ++n) _Pragma("unroll") for (int k = 0; k < 2; ++k) dst[n][k] = *(const PG8_LAS bf16x8*)(lds + PG8_SB(b, h) + boff + n * 2048 + k * 1024); } while (0)
; #define PG8_MMA(ai, bj, At, Bt) do { __builtin_amdgcn_s_setprio(1); _Pragma("unroll") for (int m = 0; m < 4; ++m) _Pragma("unroll") for (int n = 0; n < 2; ++n) _Pragma("unroll") for (int k = 0; k < 2; ++k) \
;         acc[ai][bj][m][n] = __builtin_amdgcn_mfma_f32_16x16x32_bf16(Bt[n][k], At[m][k], acc[ai][bj][m][n], 0, 0, 0); __builtin_amdgcn_s_setprio(0); } while (0)
; #define PG8_BAR __builtin_amdgcn_s_barrier()
; template <class Epi, class Sched, bool ALIGN_EPI = false, bool SP2 = false>
; __device__ __forceinline__ void gemm_phase(PG8_LAS unsigned char* lds, const Gemm g, const Sched& S, const Epi& E, const int wid) {
;     ...
;             PG8_LDB(B0, 0, 0); PG8_LDB(B1, 0, 1); PG8_SCHED; PG8_LDA(At, 0, 0); PG8_STAGE(PG8_SA(1, 1), a1 + hsA, voffA);
;             PG8_WAIT_V(8); PG8_WAIT_L(0); PG8_BAR; PG8_MMA(0, 0, At, B0); PG8_MMA(0, 1, At, B1); PG8_BAR; PG8_SCHED;
;             PG8_LDA(At, 0, 1); PG8_STAGE(PG8_SB(0, 0), b2, voffB); PG8_STAGE(PG8_SB(0, 1), b2 + hsB, voffB); PG8_STAGE(PG8_SA(0, 0), a2, voffA);
;             PG8_WAIT_V(8); PG8_WAIT_L(0); PG8_BAR; PG8_MMA(1, 0, At, B0); PG8_MMA(1, 1, At, B1); PG8_BAR; PG8_SCHED;
;             PG8_LDB(B0, 1, 0); PG8_LDB(B1, 1, 1); PG8_SCHED; PG8_LDA(At, 1, 0); PG8_STAGE(PG8_SA(0, 1), a2 + hsA, voffA);
;             PG8_WAIT_V(8); PG8_WAIT_L(0); PG8_BAR; PG8_MMA(0, 0, At, B0); PG8_MMA(0, 1, At, B1); PG8_BAR; PG8_SCHED;
;             PG8_LDA(At, 1, 1); PG8_STAGE(PG8_SB(1, 0), b3, voffB); PG8_STAGE(PG8_SB(1, 1), b3 + hsB, voffB); PG8_STAGE(PG8_SA(1, 0), a3, voffA);
;             PG8_WAIT_V(8); PG8_WAIT_L(0); PG8_BAR; PG8_MMA(1, 0, At, B0); PG8_MMA(1, 1, At, B1); PG8_BAR; PG8_SCHED;
.LBB0_497:
	ds_read_b128 v[64:67], v197
	ds_read_b128 v[72:75], v197 offset:1024
	ds_read_b128 v[80:83], v197 offset:2048
	ds_read_b128 v[84:87], v197 offset:3072
	ds_read_b128 v[88:91], v198
	ds_read_b128 v[92:95], v198 offset:1024
	ds_read_b128 v[100:103], v198 offset:2048
	ds_read_b128 v[104:107], v198 offset:3072
	s_add_u32 s4, s30, 0x100
	s_addc_u32 s5, s31, 0
	s_cmpk_eq_i32 s61, 0x54
	s_cselect_b32 s37, s27, s5
	s_cselect_b32 s36, s26, s4
	s_cselect_b32 s35, s29, s60
	s_cselect_b32 s34, s28, s59
	v_lshl_add_u64 v[210:211], s[30:31], 0, v[182:183]
	s_add_i32 m0, s41, 0xc000
	ds_read_b128 v[160:163], v199
	ds_read_b128 v[164:167], v199 offset:1024
	ds_read_b128 v[168:171], v199 offset:2048
	ds_read_b128 v[172:175], v199 offset:3072
	ds_read_b128 v[188:191], v199 offset:4096
	ds_read_b128 v[192:195], v199 offset:5120
	ds_read_b128 v[202:205], v199 offset:6144
	ds_read_b128 v[206:209], v199 offset:7168
	global_load_lds_dwordx4 v[210:211], off
	v_lshl_add_u64 v[210:211], s[30:31], 0, v[180:181]
	s_add_i32 m0, s41, 0xe000
	s_nop 0
	global_load_lds_dwordx4 v[210:211], off
	s_waitcnt vmcnt(8)
	s_waitcnt lgkmcnt(0)
	s_barrier
	s_setprio 1
	s_waitcnt lgkmcnt(0)
	v_mfma_f32_16x16x32_bf16 v[156:159], v[64:67], v[160:163], v[156:159]
	v_mfma_f32_16x16x32_bf16 v[140:143], v[64:67], v[168:171], v[140:143]
	v_mfma_f32_16x16x32_bf16 v[124:127], v[64:67], v[188:191], v[124:127]
	v_mfma_f32_16x16x32_bf16 v[108:111], v[64:67], v[202:205], v[108:111]
	v_mfma_f32_16x16x32_bf16 v[96:99], v[80:83], v[202:205], v[96:99]
	v_mfma_f32_16x16x32_bf16 v[120:123], v[80:83], v[188:191], v[120:123]
	v_mfma_f32_16x16x32_bf16 v[136:139], v[80:83], v[168:171], v[136:139]
	v_mfma_f32_16x16x32_bf16 v[152:155], v[80:83], v[160:163], v[152:155]
	v_mfma_f32_16x16x32_bf16 v[156:159], v[72:75], v[164:167], v[156:159]
	v_mfma_f32_16x16x32_bf16 v[140:143], v[72:75], v[172:175], v[140:143]
	v_mfma_f32_16x16x32_bf16 v[124:127], v[72:75], v[192:195], v[124:127]
	v_mfma_f32_16x16x32_bf16 v[108:111], v[72:75], v[206:209], v[108:111]
	v_mfma_f32_16x16x32_bf16 v[96:99], v[84:87], v[206:209], v[96:99]
	v_mfma_f32_16x16x32_bf16 v[120:123], v[84:87], v[192:195], v[120:123]
	v_mfma_f32_16x16x32_bf16 v[136:139], v[84:87], v[172:175], v[136:139]
	v_mfma_f32_16x16x32_bf16 v[152:155], v[84:87], v[164:167], v[152:155]
	s_setprio 0
	s_setprio 1
	v_mfma_f32_16x16x32_bf16 v[148:151], v[88:91], v[160:163], v[148:151]
	v_mfma_f32_16x16x32_bf16 v[132:135], v[88:91], v[168:171], v[132:135]
	v_mfma_f32_16x16x32_bf16 v[116:119], v[88:91], v[188:191], v[116:119]
	v_mfma_f32_16x16x32_bf16 v[76:79], v[88:91], v[202:205], v[76:79]
	v_mfma_f32_16x16x32_bf16 v[68:71], v[100:103], v[202:205], v[68:71]
	v_mfma_f32_16x16x32_bf16 v[112:115], v[100:103], v[188:191], v[112:115]
	v_mfma_f32_16x16x32_bf16 v[128:131], v[100:103], v[168:171], v[128:131]
	v_mfma_f32_16x16x32_bf16 v[144:147], v[100:103], v[160:163], v[144:147]
	v_mfma_f32_16x16x32_bf16 v[148:151], v[92:95], v[164:167], v[148:151]
	v_mfma_f32_16x16x32_bf16 v[132:135], v[92:95], v[172:175], v[132:135]
	v_mfma_f32_16x16x32_bf16 v[116:119], v[92:95], v[192:195], v[116:119]
	v_mfma_f32_16x16x32_bf16 v[76:79], v[92:95], v[206:209], v[76:79]
	v_mfma_f32_16x16x32_bf16 v[68:71], v[104:107], v[206:209], v[68:71]
	v_mfma_f32_16x16x32_bf16 v[112:115], v[104:107], v[192:195], v[112:115]
	v_mfma_f32_16x16x32_bf16 v[128:131], v[104:107], v[172:175], v[128:131]
	v_mfma_f32_16x16x32_bf16 v[144:147], v[104:107], v[164:167], v[144:147]
	s_setprio 0
	s_barrier
	s_add_i32 s30, s53, s40
	v_lshl_add_u64 v[210:211], s[34:35], 0, v[176:177]
	s_mov_b32 m0, s30
	ds_read_b128 v[160:163], v199 offset:16384
	ds_read_b128 v[164:167], v199 offset:17408
	ds_read_b128 v[168:171], v199 offset:18432
	ds_read_b128 v[172:175], v199 offset:19456
	ds_read_b128 v[188:191], v199 offset:20480
	ds_read_b128 v[192:195], v199 offset:21504
	ds_read_b128 v[202:205], v199 offset:22528
	ds_read_b128 v[206:209], v199 offset:23552
	global_load_lds_dwordx4 v[210:211], off
	s_add_i32 m0, s30, 0x2000
	s_add_u32 s30, s34, 0x160000
	v_lshl_add_u64 v[212:213], s[34:35], 0, v[178:179]
	s_addc_u32 s31, s35, 0
	s_add_i32 s62, s54, s40
	global_load_lds_dwordx4 v[212:213], off
	v_lshl_add_u64 v[214:215], s[30:31], 0, v[176:177]
	s_mov_b32 m0, s62
	v_lshl_add_u64 v[216:217], s[36:37], 0, v[178:179]
	global_load_lds_dwordx4 v[214:215], off
	v_lshl_add_u64 v[214:215], s[30:31], 0, v[178:179]
	s_add_i32 m0, s62, 0x2000
	s_nop 0
	global_load_lds_dwordx4 v[214:215], off
	v_lshl_add_u64 v[214:215], s[36:37], 0, v[176:177]
	s_mov_b32 m0, s41
	s_nop 0
	global_load_lds_dwordx4 v[214:215], off
	s_mov_b32 m0, s42
	s_nop 0
	global_load_lds_dwordx4 v[216:217], off
	s_waitcnt vmcnt(8)
	s_waitcnt lgkmcnt(0)
	s_barrier
; #define PG8_STAGE(bufoff, gbase, voff) do { _Pragma("unroll") for (int _i = 0; _i < 2; ++_i) \
;         __builtin_amdgcn_global_load_lds((const unsigned*)((const char*)(gbase) + (voff)[_i]), (PG8_LAS unsigned*)(lds + (bufoff) + ldsw + _i * 8192), 16, 0, 0); } while (0)
; #define PG8_LDA(dst, b, h) do { _Pragma("unroll") for (int m = 0; m < 4; ++m) _Pragma("unroll") for (int k = 0; k < 2; ++k) dst[m][k] = *(const PG8_LAS bf16x8*)(lds + PG8_SA(b, h) + aoff + m * 2048 + k * 1024); } while (0)
; #define PG8_LDB(dst, b, h) do { _Pragma("unroll") for (int n = 0; n < 2; ++n) _Pragma("unroll") for (int k = 0; k < 2; ++k) dst[n][k] = *(const PG8_LAS bf16x8*)(lds + PG8_SB(b, h) + boff + n * 2048 + k * 1024); } while (0)
; #define PG8_MMA(ai, bj, At, Bt) do { __builtin_amdgcn_s_setprio(1); _Pragma("unroll") for (int m = 0; m < 4; ++m) _Pragma("unroll") for (int n = 0; n < 2; ++n) _Pragma("unroll") for (int k = 0; k < 2; ++k) \
;         acc[ai][bj][m][n] = __builtin_amdgcn_mfma_f32_16x16x32_bf16(Bt[n][k], At[m][k], acc[ai][bj][m][n], 0, 0, 0); __builtin_amdgcn_s_setprio(0); } while (0)
; #define PG8_BAR __builtin_amdgcn_s_barrier()
; template <class Epi, class Sched, bool ALIGN_EPI = false, bool SP2 = false>
; __device__ __forceinline__ void gemm_phase(PG8_LAS unsigned char* lds, const Gemm g, const Sched& S, const Epi& E, const int wid) {
;     ...
;             PG8_LDB(B0, 0, 0); PG8_LDB(B1, 0, 1); PG8_SCHED; PG8_LDA(At, 0, 0); PG8_STAGE(PG8_SA(1, 1), a1 + hsA, voffA);
;             PG8_WAIT_V(8); PG8_WAIT_L(0); PG8_BAR; PG8_MMA(0, 0, At, B0); PG8_MMA(0, 1, At, B1); PG8_BAR; PG8_SCHED;
;             PG8_LDA(At, 0, 1); PG8_STAGE(PG8_SB(0, 0), b2, voffB); PG8_STAGE(PG8_SB(0, 1), b2 + hsB, voffB); PG8_STAGE(PG8_SA(0, 0), a2, voffA);
;             PG8_WAIT_V(8); PG8_WAIT_L(0); PG8_BAR; PG8_MMA(1, 0, At, B0); PG8_MMA(1, 1, At, B1); PG8_BAR; PG8_SCHED;
;             PG8_LDB(B0, 1, 0); PG8_LDB(B1, 1, 1); PG8_SCHED; PG8_LDA(At, 1, 0); PG8_STAGE(PG8_SA(0, 1), a2 + hsA, voffA);
;             PG8_WAIT_V(8); PG8_WAIT_L(0); PG8_BAR; PG8_MMA(0, 0, At, B0); PG8_MMA(0, 1, At, B1); PG8_BAR; PG8_SCHED;
;             PG8_LDA(At, 1, 1); PG8_STAGE(PG8_SB(1, 0), b3, voffB); PG8_STAGE(PG8_SB(1, 1), b3 + hsB, voffB); PG8_STAGE(PG8_SA(1, 0), a3, voffA);
;             PG8_WAIT_V(8); PG8_WAIT_L(0); PG8_BAR; PG8_MMA(1, 0, At, B0); PG8_MMA(1, 1, At, B1); PG8_BAR; PG8_SCHED;
	s_setprio 1
	s_waitcnt lgkmcnt(0)
	v_mfma_f32_16x16x32_bf16 v[60:63], v[64:67], v[160:163], v[60:63]
	v_mfma_f32_16x16x32_bf16 v[44:47], v[64:67], v[168:171], v[44:47]
	v_mfma_f32_16x16x32_bf16 v[28:31], v[64:67], v[188:191], v[28:31]
	v_mfma_f32_16x16x32_bf16 v[12:15], v[64:67], v[202:205], v[12:15]
	v_mfma_f32_16x16x32_bf16 v[8:11], v[80:83], v[202:205], v[8:11]
	v_mfma_f32_16x16x32_bf16 v[24:27], v[80:83], v[188:191], v[24:27]
	v_mfma_f32_16x16x32_bf16 v[40:43], v[80:83], v[168:171], v[40:43]
	v_mfma_f32_16x16x32_bf16 v[56:59], v[80:83], v[160:163], v[56:59]
	v_mfma_f32_16x16x32_bf16 v[60:63], v[72:75], v[164:167], v[60:63]
	v_mfma_f32_16x16x32_bf16 v[44:47], v[72:75], v[172:175], v[44:47]
	v_mfma_f32_16x16x32_bf16 v[28:31], v[72:75], v[192:195], v[28:31]
	v_mfma_f32_16x16x32_bf16 v[12:15], v[72:75], v[206:209], v[12:15]
	v_mfma_f32_16x16x32_bf16 v[8:11], v[84:87], v[206:209], v[8:11]
	v_mfma_f32_16x16x32_bf16 v[24:27], v[84:87], v[192:195], v[24:27]
	v_mfma_f32_16x16x32_bf16 v[40:43], v[84:87], v[172:175], v[40:43]
	v_mfma_f32_16x16x32_bf16 v[56:59], v[84:87], v[164:167], v[56:59]
	s_setprio 0
	s_setprio 1
	v_mfma_f32_16x16x32_bf16 v[52:55], v[88:91], v[160:163], v[52:55]
	v_mfma_f32_16x16x32_bf16 v[36:39], v[88:91], v[168:171], v[36:39]
	v_mfma_f32_16x16x32_bf16 v[20:23], v[88:91], v[188:191], v[20:23]
	v_mfma_f32_16x16x32_bf16 v[4:7], v[88:91], v[202:205], v[4:7]
	v_mfma_f32_16x16x32_bf16 v[0:3], v[100:103], v[202:205], v[0:3]
	v_mfma_f32_16x16x32_bf16 v[16:19], v[100:103], v[188:191], v[16:19]
	v_mfma_f32_16x16x32_bf16 v[32:35], v[100:103], v[168:171], v[32:35]
	v_mfma_f32_16x16x32_bf16 v[48:51], v[100:103], v[160:163], v[48:51]
	v_mfma_f32_16x16x32_bf16 v[52:55], v[92:95], v[164:167], v[52:55]
	v_mfma_f32_16x16x32_bf16 v[36:39], v[92:95], v[172:175], v[36:39]
	v_mfma_f32_16x16x32_bf16 v[20:23], v[92:95], v[192:195], v[20:23]
	v_mfma_f32_16x16x32_bf16 v[4:7], v[92:95], v[206:209], v[4:7]
	v_mfma_f32_16x16x32_bf16 v[0:3], v[104:107], v[206:209], v[0:3]
	v_mfma_f32_16x16x32_bf16 v[16:19], v[104:107], v[192:195], v[16:19]
	v_mfma_f32_16x16x32_bf16 v[32:35], v[104:107], v[172:175], v[32:35]
	v_mfma_f32_16x16x32_bf16 v[48:51], v[104:107], v[164:167], v[48:51]
	s_setprio 0
	s_barrier
	s_add_i32 s62, 0, 0x18000
	s_add_i32 s63, 0, 0x1c000
	v_add_u32_e32 v84, s62, v196
	v_add_u32_e32 v104, s63, v196
	ds_read_b128 v[64:67], v84
	ds_read_b128 v[72:75], v84 offset:1024
	ds_read_b128 v[80:83], v84 offset:2048
	ds_read_b128 v[84:87], v84 offset:3072
	ds_read_b128 v[88:91], v104
	ds_read_b128 v[92:95], v104 offset:1024
	ds_read_b128 v[100:103], v104 offset:2048
	ds_read_b128 v[104:107], v104 offset:3072
	s_add_u32 s30, s36, 0x160000
	s_addc_u32 s31, s37, 0
	s_mov_b32 m0, s43
	v_lshl_add_u64 v[218:219], s[30:31], 0, v[176:177]
	ds_read_b128 v[160:163], v199 offset:32768
	ds_read_b128 v[164:167], v199 offset:33792
	ds_read_b128 v[168:171], v199 offset:34816
	ds_read_b128 v[172:175], v199 offset:35840
	ds_read_b128 v[188:191], v199 offset:36864
	ds_read_b128 v[192:195], v199 offset:37888
	ds_read_b128 v[202:205], v199 offset:38912
	ds_read_b128 v[206:209], v199 offset:39936
	global_load_lds_dwordx4 v[218:219], off
	v_lshl_add_u64 v[218:219], s[30:31], 0, v[178:179]
	s_mov_b32 m0, s44
	s_nop 0
	global_load_lds_dwordx4 v[218:219], off
	s_waitcnt vmcnt(8)
	s_waitcnt lgkmcnt(0)
	s_barrier
	s_setprio 1
	s_waitcnt lgkmcnt(0)
	v_mfma_f32_16x16x32_bf16 v[156:159], v[64:67], v[160:163], v[156:159]
	v_mfma_f32_16x16x32_bf16 v[140:143], v[64:67], v[168:171], v[140:143]
	v_mfma_f32_16x16x32_bf16 v[124:127], v[64:67], v[188:191], v[124:127]
	v_mfma_f32_16x16x32_bf16 v[108:111], v[64:67], v[202:205], v[108:111]
	v_mfma_f32_16x16x32_bf16 v[96:99], v[80:83], v[202:205], v[96:99]
	v_mfma_f32_16x16x32_bf16 v[120:123], v[80:83], v[188:191], v[120:123]
	v_mfma_f32_16x16x32_bf16 v[136:139], v[80:83], v[168:171], v[136:139]
	v_mfma_f32_16x16x32_bf16 v[152:155], v[80:83], v[160:163], v[152:155]
	v_mfma_f32_16x16x32_bf16 v[156:159], v[72:75], v[164:167], v[156:159]
	v_mfma_f32_16x16x32_bf16 v[140:143], v[72:75], v[172:175], v[140:143]
	v_mfma_f32_16x16x32_bf16 v[124:127], v[72:75], v[192:195], v[124:127]
	v_mfma_f32_16x16x32_bf16 v[108:111], v[72:75], v[206:209], v[108:111]
	v_mfma_f32_16x16x32_bf16 v[96:99], v[84:87], v[206:209], v[96:99]
	v_mfma_f32_16x16x32_bf16 v[120:123], v[84:87], v[192:195], v[120:123]
	v_mfma_f32_16x16x32_bf16 v[136:139], v[84:87], v[172:175], v[136:139]
	v_mfma_f32_16x16x32_bf16 v[152:155], v[84:87], v[164:167], v[152:155]
	s_setprio 0
	s_setprio 1
	v_mfma_f32_16x16x32_bf16 v[148:151], v[88:91], v[160:163], v[148:151]
	v_mfma_f32_16x16x32_bf16 v[132:135], v[88:91], v[168:171], v[132:135]
	v_mfma_f32_16x16x32_bf16 v[116:119], v[88:91], v[188:191], v[116:119]
	v_mfma_f32_16x16x32_bf16 v[76:79], v[88:91], v[202:205], v[76:79]
	v_mfma_f32_16x16x32_bf16 v[68:71], v[100:103], v[202:205], v[68:71]
	v_mfma_f32_16x16x32_bf16 v[112:115], v[100:103], v[188:191], v[112:115]
	v_mfma_f32_16x16x32_bf16 v[128:131], v[100:103], v[168:171], v[128:131]
	v_mfma_f32_16x16x32_bf16 v[144:147], v[100:103], v[160:163], v[144:147]
	v_mfma_f32_16x16x32_bf16 v[148:151], v[92:95], v[164:167], v[148:151]
	v_mfma_f32_16x16x32_bf16 v[132:135], v[92:95], v[172:175], v[132:135]
	v_mfma_f32_16x16x32_bf16 v[116:119], v[92:95], v[192:195], v[116:119]
	v_mfma_f32_16x16x32_bf16 v[76:79], v[92:95], v[206:209], v[76:79]
	v_mfma_f32_16x16x32_bf16 v[68:71], v[104:107], v[206:209], v[68:71]
	v_mfma_f32_16x16x32_bf16 v[112:115], v[104:107], v[192:195], v[112:115]
	v_mfma_f32_16x16x32_bf16 v[128:131], v[104:107], v[172:175], v[128:131]
	v_mfma_f32_16x16x32_bf16 v[144:147], v[104:107], v[164:167], v[144:147]
	s_setprio 0
	s_barrier
; #define PG8_STAGE(bufoff, gbase, voff) do { _Pragma("unroll") for (int _i = 0; _i < 2; ++_i) \
;         __builtin_amdgcn_global_load_lds((const unsigned*)((const char*)(gbase) + (voff)[_i]), (PG8_LAS unsigned*)(lds + (bufoff) + ldsw + _i * 8192), 16, 0, 0); } while (0)
; #define PG8_LDA(dst, b, h) do { _Pragma("unroll") for (int m = 0; m < 4; ++m) _Pragma("unroll") for (int k = 0; k < 2; ++k) dst[m][k] = *(const PG8_LAS bf16x8*)(lds + PG8_SA(b, h) + aoff + m * 2048 + k * 1024); } while (0)
; #define PG8_LDB(dst, b, h) do { _Pragma("unroll") for (int n = 0; n < 2; ++n) _Pragma("unroll") for (int k = 0; k < 2; ++k) dst[n][k] = *(const PG8_LAS bf16x8*)(lds + PG8_SB(b, h) + boff + n * 2048 + k * 1024); } while (0)
; #define PG8_MMA(ai, bj, At, Bt) do { __builtin_amdgcn_s_setprio(1); _Pragma("unroll") for (int m = 0; m < 4; ++m) _Pragma("unroll") for (int n = 0; n < 2; ++n) _Pragma("unroll") for (int k = 0; k < 2; ++k) \
;         acc[ai][bj][m][n] = __builtin_amdgcn_mfma_f32_16x16x32_bf16(Bt[n][k], At[m][k], acc[ai][bj][m][n], 0, 0, 0); __builtin_amdgcn_s_setprio(0); } while (0)
; #define PG8_BAR __builtin_amdgcn_s_barrier()
; template <class Epi, class Sched, bool ALIGN_EPI = false, bool SP2 = false>
; __device__ __forceinline__ void gemm_phase(PG8_LAS unsigned char* lds, const Gemm g, const Sched& S, const Epi& E, const int wid) {
;     ...
;             PG8_LDB(B0, 0, 0); PG8_LDB(B1, 0, 1); PG8_SCHED; PG8_LDA(At, 0, 0); PG8_STAGE(PG8_SA(1, 1), a1 + hsA, voffA);
;             PG8_WAIT_V(8); PG8_WAIT_L(0); PG8_BAR; PG8_MMA(0, 0, At, B0); PG8_MMA(0, 1, At, B1); PG8_BAR; PG8_SCHED;
;             PG8_LDA(At, 0, 1); PG8_STAGE(PG8_SB(0, 0), b2, voffB); PG8_STAGE(PG8_SB(0, 1), b2 + hsB, voffB); PG8_STAGE(PG8_SA(0, 0), a2, voffA);
;             PG8_WAIT_V(8); PG8_WAIT_L(0); PG8_BAR; PG8_MMA(1, 0, At, B0); PG8_MMA(1, 1, At, B1); PG8_BAR; PG8_SCHED;
;             PG8_LDB(B0, 1, 0); PG8_LDB(B1, 1, 1); PG8_SCHED; PG8_LDA(At, 1, 0); PG8_STAGE(PG8_SA(0, 1), a2 + hsA, voffA);
;             PG8_WAIT_V(8); PG8_WAIT_L(0); PG8_BAR; PG8_MMA(0, 0, At, B0); PG8_MMA(0, 1, At, B1); PG8_BAR; PG8_SCHED;
;             PG8_LDA(At, 1, 1); PG8_STAGE(PG8_SB(1, 0), b3, voffB); PG8_STAGE(PG8_SB(1, 1), b3 + hsB, voffB); PG8_STAGE(PG8_SA(1, 0), a3, voffA);
;             PG8_WAIT_V(8); PG8_WAIT_L(0); PG8_BAR; PG8_MMA(1, 0, At, B0); PG8_MMA(1, 1, At, B1); PG8_BAR; PG8_SCHED;
	s_add_i32 s30, s62, s40
	v_lshl_add_u64 v[210:211], v[210:211], 0, s[22:23]
	s_mov_b32 m0, s30
	ds_read_b128 v[160:163], v199 offset:49152
	ds_read_b128 v[164:167], v199 offset:50176
	ds_read_b128 v[168:171], v199 offset:51200
	ds_read_b128 v[172:175], v199 offset:52224
	ds_read_b128 v[188:191], v199 offset:53248
	ds_read_b128 v[192:195], v199 offset:54272
	ds_read_b128 v[202:205], v199 offset:55296
	ds_read_b128 v[206:209], v199 offset:56320
	global_load_lds_dwordx4 v[210:211], off
	s_add_i32 m0, s30, 0x2000
	s_add_u32 s30, s34, 0x160080
	v_lshl_add_u64 v[210:211], v[212:213], 0, s[22:23]
	s_addc_u32 s31, s35, 0
	s_add_i32 s34, s63, s40
	global_load_lds_dwordx4 v[210:211], off
	v_lshl_add_u64 v[210:211], s[30:31], 0, v[176:177]
	s_mov_b32 m0, s34
	s_nop 0
	global_load_lds_dwordx4 v[210:211], off
	v_lshl_add_u64 v[210:211], s[30:31], 0, v[178:179]
	s_add_i32 m0, s34, 0x2000
	s_nop 0
	global_load_lds_dwordx4 v[210:211], off
	v_lshl_add_u64 v[210:211], v[214:215], 0, s[22:23]
	s_mov_b32 m0, s48
	s_nop 0
	global_load_lds_dwordx4 v[210:211], off
	v_lshl_add_u64 v[210:211], v[216:217], 0, s[22:23]
	s_mov_b32 m0, s49
	s_nop 0
	global_load_lds_dwordx4 v[210:211], off
	s_waitcnt vmcnt(8)
	s_waitcnt lgkmcnt(0)
	s_barrier
	s_setprio 1
	s_waitcnt lgkmcnt(0)
	v_mfma_f32_16x16x32_bf16 v[60:63], v[64:67], v[160:163], v[60:63]
	v_mfma_f32_16x16x32_bf16 v[44:47], v[64:67], v[168:171], v[44:47]
	v_mfma_f32_16x16x32_bf16 v[28:31], v[64:67], v[188:191], v[28:31]
	v_mfma_f32_16x16x32_bf16 v[12:15], v[64:67], v[202:205], v[12:15]
	v_mfma_f32_16x16x32_bf16 v[8:11], v[80:83], v[202:205], v[8:11]
	v_mfma_f32_16x16x32_bf16 v[24:27], v[80:83], v[188:191], v[24:27]
	v_mfma_f32_16x16x32_bf16 v[40:43], v[80:83], v[168:171], v[40:43]
	v_mfma_f32_16x16x32_bf16 v[56:59], v[80:83], v[160:163], v[56:59]
	v_mfma_f32_16x16x32_bf16 v[60:63], v[72:75], v[164:167], v[60:63]
	v_mfma_f32_16x16x32_bf16 v[44:47], v[72:75], v[172:175], v[44:47]
	v_mfma_f32_16x16x32_bf16 v[28:31], v[72:75], v[192:195], v[28:31]
	v_mfma_f32_16x16x32_bf16 v[12:15], v[72:75], v[206:209], v[12:15]
	v_mfma_f32_16x16x32_bf16 v[8:11], v[84:87], v[206:209], v[8:11]
	v_mfma_f32_16x16x32_bf16 v[24:27], v[84:87], v[192:195], v[24:27]
	v_mfma_f32_16x16x32_bf16 v[40:43], v[84:87], v[172:175], v[40:43]
	v_mfma_f32_16x16x32_bf16 v[56:59], v[84:87], v[164:167], v[56:59]
	s_setprio 0
	s_setprio 1
	v_mfma_f32_16x16x32_bf16 v[52:55], v[88:91], v[160:163], v[52:55]
	v_mfma_f32_16x16x32_bf16 v[36:39], v[88:91], v[168:171], v[36:39]
	v_mfma_f32_16x16x32_bf16 v[20:23], v[88:91], v[188:191], v[20:23]
	v_mfma_f32_16x16x32_bf16 v[4:7], v[88:91], v[202:205], v[4:7]
	v_mfma_f32_16x16x32_bf16 v[0:3], v[100:103], v[202:205], v[0:3]
	v_mfma_f32_16x16x32_bf16 v[16:19], v[100:103], v[188:191], v[16:19]
	v_mfma_f32_16x16x32_bf16 v[32:35], v[100:103], v[168:171], v[32:35]
	v_mfma_f32_16x16x32_bf16 v[48:51], v[100:103], v[160:163], v[48:51]
	v_mfma_f32_16x16x32_bf16 v[52:55], v[92:95], v[164:167], v[52:55]
	v_mfma_f32_16x16x32_bf16 v[36:39], v[92:95], v[172:175], v[36:39]
	v_mfma_f32_16x16x32_bf16 v[20:23], v[92:95], v[192:195], v[20:23]
	v_mfma_f32_16x16x32_bf16 v[4:7], v[92:95], v[206:209], v[4:7]
	v_mfma_f32_16x16x32_bf16 v[0:3], v[104:107], v[206:209], v[0:3]
	v_mfma_f32_16x16x32_bf16 v[16:19], v[104:107], v[192:195], v[16:19]
	v_mfma_f32_16x16x32_bf16 v[32:35], v[104:107], v[172:175], v[32:35]
	v_mfma_f32_16x16x32_bf16 v[48:51], v[104:107], v[164:167], v[48:51]
	s_setprio 0
	s_barrier
	s_add_i32 s61, s61, 2
	s_add_u32 s59, s59, 0x100
	s_addc_u32 s60, s60, 0
	s_cmpk_gt_u32 s61, 0x55
	s_mov_b64 s[30:31], s[4:5]
	s_cbranch_scc0 .LBB0_497
	s_and_b64 vcc, exec, s[24:25]
	s_cbranch_vccz .LBB0_500
	s_barrier

; #define PG8_STAGE(bufoff, gbase, voff) do { _Pragma("unroll") for (int _i = 0; _i < 2; ++_i) \
;         __builtin_amdgcn_global_load_lds((const unsigned*)((const char*)(gbase) + (voff)[_i]), (PG8_LAS unsigned*)(lds + (bufoff) + ldsw + _i * 8192), 16, 0, 0); } while (0)
; #define PG8_LDA(dst, b, h) do { _Pragma("unroll") for (int m = 0; m < 4; ++m) _Pragma("unroll") for (int k = 0; k < 2; ++k) dst[m][k] = *(const PG8_LAS bf16x8*)(lds + PG8_SA(b, h) + aoff + m * 2048 + k * 1024); } while (0)
; #define PG8_LDB(dst, b, h) do { _Pragma("unroll") for (int n = 0; n < 2; ++n) _Pragma("unroll") for (int k = 0; k < 2; ++k) dst[n][k] = *(const PG8_LAS bf16x8*)(lds + PG8_SB(b, h) + boff + n * 2048 + k * 1024); } while (0)
; #define PG8_MMA(ai, bj, At, Bt) do { __builtin_amdgcn_s_setprio(1); _Pragma("unroll") for (int m = 0; m < 4; ++m) _Pragma("unroll") for (int n = 0; n < 2; ++n) _Pragma("unroll") for (int k = 0; k < 2; ++k) \
;         acc[ai][bj][m][n] = __builtin_amdgcn_mfma_f32_16x16x32_bf16(Bt[n][k], At[m][k], acc[ai][bj][m][n], 0, 0, 0); __builtin_amdgcn_s_setprio(0); } while (0)
; #define PG8_BAR __builtin_amdgcn_s_barrier()
; template <class Epi, class Sched, bool ALIGN_EPI = false, bool SP2 = false>
; __device__ __forceinline__ void gemm_phase(PG8_LAS unsigned char* lds, const Gemm g, const Sched& S, const Epi& E, const int wid) {
;     ...
;             PG8_LDB(B0, 0, 0); PG8_LDB(B1, 0, 1); PG8_SCHED; PG8_LDA(At, 0, 0); PG8_STAGE(PG8_SA(1, 1), a1 + hsA, voffA);
;             PG8_WAIT_V(8); PG8_WAIT_L(0); PG8_BAR; PG8_MMA(0, 0, At, B0); PG8_MMA(0, 1, At, B1); PG8_BAR; PG8_SCHED;
;             PG8_LDA(At, 0, 1); PG8_STAGE(PG8_SB(0, 0), b2, voffB); PG8_STAGE(PG8_SB(0, 1), b2 + hsB, voffB); PG8_STAGE(PG8_SA(0, 0), a2, voffA);
;             PG8_WAIT_V(8); PG8_WAIT_L(0); PG8_BAR; PG8_MMA(1, 0, At, B0); PG8_MMA(1, 1, At, B1); PG8_BAR; PG8_SCHED;
;             PG8_LDB(B0, 1, 0); PG8_LDB(B1, 1, 1); PG8_SCHED; PG8_LDA(At, 1, 0); PG8_STAGE(PG8_SA(0, 1), a2 + hsA, voffA);
;             PG8_WAIT_V(8); PG8_WAIT_L(0); PG8_BAR; PG8_MMA(0, 0, At, B0); PG8_MMA(0, 1, At, B1); PG8_BAR; PG8_SCHED;
;             PG8_LDA(At, 1, 1); PG8_STAGE(PG8_SB(1, 0), b3, voffB); PG8_STAGE(PG8_SB(1, 1), b3 + hsB, voffB); PG8_STAGE(PG8_SA(1, 0), a3, voffA);
;             PG8_WAIT_V(8); PG8_WAIT_L(0); PG8_BAR; PG8_MMA(1, 0, At, B0); PG8_MMA(1, 1, At, B1); PG8_BAR; PG8_SCHED;
.LBB0_588:
	ds_read_b128 v[128:131], v237
	ds_read_b128 v[132:135], v237 offset:1024
	ds_read_b128 v[136:139], v237 offset:2048
	ds_read_b128 v[140:143], v237 offset:3072
	ds_read_b128 v[144:147], v238
	ds_read_b128 v[148:151], v238 offset:1024
	ds_read_b128 v[152:155], v238 offset:2048
	ds_read_b128 v[156:159], v238 offset:3072
	s_add_u32 s8, s6, 0xfff80080
	s_addc_u32 s9, s7, -1
	s_cmp_eq_u32 s87, 28
	s_cselect_b32 s53, s5, s9
	s_cselect_b32 s52, s47, s8
	s_cselect_b32 s9, s45, s86
	s_cselect_b32 s8, s54, s55
	v_lshl_add_u64 v[210:211], s[6:7], 0, v[180:181]
	s_add_i32 m0, s59, 0xc000
	ds_read_b128 v[160:163], v239
	ds_read_b128 v[164:167], v239 offset:1024
	ds_read_b128 v[186:189], v239 offset:2048
	ds_read_b128 v[190:193], v239 offset:3072
	ds_read_b128 v[194:197], v239 offset:4096
	ds_read_b128 v[198:201], v239 offset:5120
	ds_read_b128 v[202:205], v239 offset:6144
	ds_read_b128 v[206:209], v239 offset:7168
	global_load_lds_dwordx4 v[210:211], off
	v_lshl_add_u64 v[210:211], s[6:7], 0, v[178:179]
	s_add_i32 m0, s59, 0xe000
	s_nop 0
	global_load_lds_dwordx4 v[210:211], off
	s_waitcnt vmcnt(8)
	s_waitcnt lgkmcnt(0)
	s_barrier
	s_setprio 1
	s_waitcnt lgkmcnt(0)
	v_mfma_f32_16x16x32_bf16 v[124:127], v[128:131], v[160:163], v[124:127]
	v_mfma_f32_16x16x32_bf16 v[108:111], v[128:131], v[186:189], v[108:111]
	v_mfma_f32_16x16x32_bf16 v[92:95], v[128:131], v[194:197], v[92:95]
	v_mfma_f32_16x16x32_bf16 v[76:79], v[128:131], v[202:205], v[76:79]
	v_mfma_f32_16x16x32_bf16 v[72:75], v[136:139], v[202:205], v[72:75]
	v_mfma_f32_16x16x32_bf16 v[88:91], v[136:139], v[194:197], v[88:91]
	v_mfma_f32_16x16x32_bf16 v[104:107], v[136:139], v[186:189], v[104:107]
	v_mfma_f32_16x16x32_bf16 v[120:123], v[136:139], v[160:163], v[120:123]
	v_mfma_f32_16x16x32_bf16 v[124:127], v[132:135], v[164:167], v[124:127]
	v_mfma_f32_16x16x32_bf16 v[108:111], v[132:135], v[190:193], v[108:111]
	v_mfma_f32_16x16x32_bf16 v[92:95], v[132:135], v[198:201], v[92:95]
	v_mfma_f32_16x16x32_bf16 v[76:79], v[132:135], v[206:209], v[76:79]
	v_mfma_f32_16x16x32_bf16 v[72:75], v[140:143], v[206:209], v[72:75]
	v_mfma_f32_16x16x32_bf16 v[88:91], v[140:143], v[198:201], v[88:91]
	v_mfma_f32_16x16x32_bf16 v[104:107], v[140:143], v[190:193], v[104:107]
	v_mfma_f32_16x16x32_bf16 v[120:123], v[140:143], v[164:167], v[120:123]
	s_setprio 0
	s_setprio 1
	v_mfma_f32_16x16x32_bf16 v[116:119], v[144:147], v[160:163], v[116:119]
	v_mfma_f32_16x16x32_bf16 v[100:103], v[144:147], v[186:189], v[100:103]
	v_mfma_f32_16x16x32_bf16 v[84:87], v[144:147], v[194:197], v[84:87]
	v_mfma_f32_16x16x32_bf16 v[68:71], v[144:147], v[202:205], v[68:71]
	v_mfma_f32_16x16x32_bf16 v[64:67], v[152:155], v[202:205], v[64:67]
	v_mfma_f32_16x16x32_bf16 v[80:83], v[152:155], v[194:197], v[80:83]
	v_mfma_f32_16x16x32_bf16 v[96:99], v[152:155], v[186:189], v[96:99]
	v_mfma_f32_16x16x32_bf16 v[112:115], v[152:155], v[160:163], v[112:115]
	v_mfma_f32_16x16x32_bf16 v[116:119], v[148:151], v[164:167], v[116:119]
	v_mfma_f32_16x16x32_bf16 v[100:103], v[148:151], v[190:193], v[100:103]
	v_mfma_f32_16x16x32_bf16 v[84:87], v[148:151], v[198:201], v[84:87]
	v_mfma_f32_16x16x32_bf16 v[68:71], v[148:151], v[206:209], v[68:71]
	v_mfma_f32_16x16x32_bf16 v[64:67], v[156:159], v[206:209], v[64:67]
	v_mfma_f32_16x16x32_bf16 v[80:83], v[156:159], v[198:201], v[80:83]
	v_mfma_f32_16x16x32_bf16 v[96:99], v[156:159], v[190:193], v[96:99]
	v_mfma_f32_16x16x32_bf16 v[112:115], v[156:159], v[164:167], v[112:115]
	s_setprio 0
	s_barrier
	s_add_i32 s88, s81, s58
	v_lshl_add_u64 v[210:211], s[8:9], 0, v[170:171]
	s_mov_b32 m0, s88
	ds_read_b128 v[160:163], v239 offset:16384
	ds_read_b128 v[164:167], v239 offset:17408
	ds_read_b128 v[186:189], v239 offset:18432
	ds_read_b128 v[190:193], v239 offset:19456
	ds_read_b128 v[194:197], v239 offset:20480
	ds_read_b128 v[198:201], v239 offset:21504
	ds_read_b128 v[202:205], v239 offset:22528
	ds_read_b128 v[206:209], v239 offset:23552
	global_load_lds_dwordx4 v[210:211], off
	s_add_i32 m0, s88, 0x2000
	s_add_u32 s88, s8, 0x80000
	v_lshl_add_u64 v[212:213], s[8:9], 0, v[174:175]
	s_addc_u32 s89, s9, 0
	s_add_i32 s90, s82, s58
	global_load_lds_dwordx4 v[212:213], off
	v_lshl_add_u64 v[214:215], s[88:89], 0, v[170:171]
	s_mov_b32 m0, s90
	v_lshl_add_u64 v[216:217], s[52:53], 0, v[172:173]
	global_load_lds_dwordx4 v[214:215], off
	v_lshl_add_u64 v[214:215], s[88:89], 0, v[174:175]
	s_add_i32 m0, s90, 0x2000
	s_nop 0
	global_load_lds_dwordx4 v[214:215], off
	v_lshl_add_u64 v[214:215], s[52:53], 0, v[168:169]
	s_mov_b32 m0, s59
	s_nop 0
	global_load_lds_dwordx4 v[214:215], off
	s_mov_b32 m0, s60
	s_nop 0
	global_load_lds_dwordx4 v[216:217], off
	s_waitcnt vmcnt(8)
	s_waitcnt lgkmcnt(0)
	s_barrier
; #define PG8_STAGE(bufoff, gbase, voff) do { _Pragma("unroll") for (int _i = 0; _i < 2; ++_i) \
;         __builtin_amdgcn_global_load_lds((const unsigned*)((const char*)(gbase) + (voff)[_i]), (PG8_LAS unsigned*)(lds + (bufoff) + ldsw + _i * 8192), 16, 0, 0); } while (0)
; #define PG8_LDA(dst, b, h) do { _Pragma("unroll") for (int m = 0; m < 4; ++m) _Pragma("unroll") for (int k = 0; k < 2; ++k) dst[m][k] = *(const PG8_LAS bf16x8*)(lds + PG8_SA(b, h) + aoff + m * 2048 + k * 1024); } while (0)
; #define PG8_LDB(dst, b, h) do { _Pragma("unroll") for (int n = 0; n < 2; ++n) _Pragma("unroll") for (int k = 0; k < 2; ++k) dst[n][k] = *(const PG8_LAS bf16x8*)(lds + PG8_SB(b, h) + boff + n * 2048 + k * 1024); } while (0)
; #define PG8_MMA(ai, bj, At, Bt) do { __builtin_amdgcn_s_setprio(1); _Pragma("unroll") for (int m = 0; m < 4; ++m) _Pragma("unroll") for (int n = 0; n < 2; ++n) _Pragma("unroll") for (int k = 0; k < 2; ++k) \
;         acc[ai][bj][m][n] = __builtin_amdgcn_mfma_f32_16x16x32_bf16(Bt[n][k], At[m][k], acc[ai][bj][m][n], 0, 0, 0); __builtin_amdgcn_s_setprio(0); } while (0)
; #define PG8_BAR __builtin_amdgcn_s_barrier()
; template <class Epi, class Sched, bool ALIGN_EPI = false, bool SP2 = false>
; __device__ __forceinline__ void gemm_phase(PG8_LAS unsigned char* lds, const Gemm g, const Sched& S, const Epi& E, const int wid) {
;     ...
;             PG8_LDB(B0, 0, 0); PG8_LDB(B1, 0, 1); PG8_SCHED; PG8_LDA(At, 0, 0); PG8_STAGE(PG8_SA(1, 1), a1 + hsA, voffA);
;             PG8_WAIT_V(8); PG8_WAIT_L(0); PG8_BAR; PG8_MMA(0, 0, At, B0); PG8_MMA(0, 1, At, B1); PG8_BAR; PG8_SCHED;
;             PG8_LDA(At, 0, 1); PG8_STAGE(PG8_SB(0, 0), b2, voffB); PG8_STAGE(PG8_SB(0, 1), b2 + hsB, voffB); PG8_STAGE(PG8_SA(0, 0), a2, voffA);
;             PG8_WAIT_V(8); PG8_WAIT_L(0); PG8_BAR; PG8_MMA(1, 0, At, B0); PG8_MMA(1, 1, At, B1); PG8_BAR; PG8_SCHED;
;             PG8_LDB(B0, 1, 0); PG8_LDB(B1, 1, 1); PG8_SCHED; PG8_LDA(At, 1, 0); PG8_STAGE(PG8_SA(0, 1), a2 + hsA, voffA);
;             PG8_WAIT_V(8); PG8_WAIT_L(0); PG8_BAR; PG8_MMA(0, 0, At, B0); PG8_MMA(0, 1, At, B1); PG8_BAR; PG8_SCHED;
;             PG8_LDA(At, 1, 1); PG8_STAGE(PG8_SB(1, 0), b3, voffB); PG8_STAGE(PG8_SB(1, 1), b3 + hsB, voffB); PG8_STAGE(PG8_SA(1, 0), a3, voffA);
;             PG8_WAIT_V(8); PG8_WAIT_L(0); PG8_BAR; PG8_MMA(1, 0, At, B0); PG8_MMA(1, 1, At, B1); PG8_BAR; PG8_SCHED;
	s_setprio 1
	s_waitcnt lgkmcnt(0)
	v_mfma_f32_16x16x32_bf16 v[60:63], v[128:131], v[160:163], v[60:63]
	v_mfma_f32_16x16x32_bf16 v[44:47], v[128:131], v[186:189], v[44:47]
	v_mfma_f32_16x16x32_bf16 v[28:31], v[128:131], v[194:197], v[28:31]
	v_mfma_f32_16x16x32_bf16 v[12:15], v[128:131], v[202:205], v[12:15]
	v_mfma_f32_16x16x32_bf16 v[8:11], v[136:139], v[202:205], v[8:11]
	v_mfma_f32_16x16x32_bf16 v[24:27], v[136:139], v[194:197], v[24:27]
	v_mfma_f32_16x16x32_bf16 v[40:43], v[136:139], v[186:189], v[40:43]
	v_mfma_f32_16x16x32_bf16 v[56:59], v[136:139], v[160:163], v[56:59]
	v_mfma_f32_16x16x32_bf16 v[60:63], v[132:135], v[164:167], v[60:63]
	v_mfma_f32_16x16x32_bf16 v[44:47], v[132:135], v[190:193], v[44:47]
	v_mfma_f32_16x16x32_bf16 v[28:31], v[132:135], v[198:201], v[28:31]
	v_mfma_f32_16x16x32_bf16 v[12:15], v[132:135], v[206:209], v[12:15]
	v_mfma_f32_16x16x32_bf16 v[8:11], v[140:143], v[206:209], v[8:11]
	v_mfma_f32_16x16x32_bf16 v[24:27], v[140:143], v[198:201], v[24:27]
	v_mfma_f32_16x16x32_bf16 v[40:43], v[140:143], v[190:193], v[40:43]
	v_mfma_f32_16x16x32_bf16 v[56:59], v[140:143], v[164:167], v[56:59]
	s_setprio 0
	s_setprio 1
	v_mfma_f32_16x16x32_bf16 v[52:55], v[144:147], v[160:163], v[52:55]
	v_mfma_f32_16x16x32_bf16 v[36:39], v[144:147], v[186:189], v[36:39]
	v_mfma_f32_16x16x32_bf16 v[20:23], v[144:147], v[194:197], v[20:23]
	v_mfma_f32_16x16x32_bf16 v[4:7], v[144:147], v[202:205], v[4:7]
	v_mfma_f32_16x16x32_bf16 v[0:3], v[152:155], v[202:205], v[0:3]
	v_mfma_f32_16x16x32_bf16 v[16:19], v[152:155], v[194:197], v[16:19]
	v_mfma_f32_16x16x32_bf16 v[32:35], v[152:155], v[186:189], v[32:35]
	v_mfma_f32_16x16x32_bf16 v[48:51], v[152:155], v[160:163], v[48:51]
	v_mfma_f32_16x16x32_bf16 v[52:55], v[148:151], v[164:167], v[52:55]
	v_mfma_f32_16x16x32_bf16 v[36:39], v[148:151], v[190:193], v[36:39]
	v_mfma_f32_16x16x32_bf16 v[20:23], v[148:151], v[198:201], v[20:23]
	v_mfma_f32_16x16x32_bf16 v[4:7], v[148:151], v[206:209], v[4:7]
	v_mfma_f32_16x16x32_bf16 v[0:3], v[156:159], v[206:209], v[0:3]
	v_mfma_f32_16x16x32_bf16 v[16:19], v[156:159], v[198:201], v[16:19]
	v_mfma_f32_16x16x32_bf16 v[32:35], v[156:159], v[190:193], v[32:35]
	v_mfma_f32_16x16x32_bf16 v[48:51], v[156:159], v[164:167], v[48:51]
	s_setprio 0
	s_barrier
	s_add_i32 s88, 0, 0x18000
	s_add_i32 s89, 0, 0x1c000
	v_add_u32_e32 v140, s88, v236
	v_add_u32_e32 v156, s89, v236
	ds_read_b128 v[128:131], v140
	ds_read_b128 v[132:135], v140 offset:1024
	ds_read_b128 v[136:139], v140 offset:2048
	ds_read_b128 v[140:143], v140 offset:3072
	ds_read_b128 v[144:147], v156
	ds_read_b128 v[148:151], v156 offset:1024
	ds_read_b128 v[152:155], v156 offset:2048
	ds_read_b128 v[156:159], v156 offset:3072
	s_add_u32 s52, s52, 0x80000
	s_addc_u32 s53, s53, 0
	s_mov_b32 m0, s61
	v_lshl_add_u64 v[218:219], s[52:53], 0, v[168:169]
	ds_read_b128 v[160:163], v239 offset:32768
	ds_read_b128 v[164:167], v239 offset:33792
	ds_read_b128 v[186:189], v239 offset:34816
	ds_read_b128 v[190:193], v239 offset:35840
	ds_read_b128 v[194:197], v239 offset:36864
	ds_read_b128 v[198:201], v239 offset:37888
	ds_read_b128 v[202:205], v239 offset:38912
	ds_read_b128 v[206:209], v239 offset:39936
	global_load_lds_dwordx4 v[218:219], off
	v_lshl_add_u64 v[218:219], s[52:53], 0, v[172:173]
	s_mov_b32 m0, s62
	s_nop 0
	global_load_lds_dwordx4 v[218:219], off
	s_waitcnt vmcnt(8)
	s_waitcnt lgkmcnt(0)
	s_barrier
	s_setprio 1
	s_waitcnt lgkmcnt(0)
	v_mfma_f32_16x16x32_bf16 v[124:127], v[128:131], v[160:163], v[124:127]
	v_mfma_f32_16x16x32_bf16 v[108:111], v[128:131], v[186:189], v[108:111]
	v_mfma_f32_16x16x32_bf16 v[92:95], v[128:131], v[194:197], v[92:95]
	v_mfma_f32_16x16x32_bf16 v[76:79], v[128:131], v[202:205], v[76:79]
	v_mfma_f32_16x16x32_bf16 v[72:75], v[136:139], v[202:205], v[72:75]
	v_mfma_f32_16x16x32_bf16 v[88:91], v[136:139], v[194:197], v[88:91]
	v_mfma_f32_16x16x32_bf16 v[104:107], v[136:139], v[186:189], v[104:107]
	v_mfma_f32_16x16x32_bf16 v[120:123], v[136:139], v[160:163], v[120:123]
	v_mfma_f32_16x16x32_bf16 v[124:127], v[132:135], v[164:167], v[124:127]
	v_mfma_f32_16x16x32_bf16 v[108:111], v[132:135], v[190:193], v[108:111]
	v_mfma_f32_16x16x32_bf16 v[92:95], v[132:135], v[198:201], v[92:95]
	v_mfma_f32_16x16x32_bf16 v[76:79], v[132:135], v[206:209], v[76:79]
	v_mfma_f32_16x16x32_bf16 v[72:75], v[140:143], v[206:209], v[72:75]
	v_mfma_f32_16x16x32_bf16 v[88:91], v[140:143], v[198:201], v[88:91]
	v_mfma_f32_16x16x32_bf16 v[104:107], v[140:143], v[190:193], v[104:107]
	v_mfma_f32_16x16x32_bf16 v[120:123], v[140:143], v[164:167], v[120:123]
	s_setprio 0
	s_setprio 1
	v_mfma_f32_16x16x32_bf16 v[116:119], v[144:147], v[160:163], v[116:119]
	v_mfma_f32_16x16x32_bf16 v[100:103], v[144:147], v[186:189], v[100:103]
	v_mfma_f32_16x16x32_bf16 v[84:87], v[144:147], v[194:197], v[84:87]
	v_mfma_f32_16x16x32_bf16 v[68:71], v[144:147], v[202:205], v[68:71]
	v_mfma_f32_16x16x32_bf16 v[64:67], v[152:155], v[202:205], v[64:67]
	v_mfma_f32_16x16x32_bf16 v[80:83], v[152:155], v[194:197], v[80:83]
	v_mfma_f32_16x16x32_bf16 v[96:99], v[152:155], v[186:189], v[96:99]
	v_mfma_f32_16x16x32_bf16 v[112:115], v[152:155], v[160:163], v[112:115]
	v_mfma_f32_16x16x32_bf16 v[116:119], v[148:151], v[164:167], v[116:119]
	v_mfma_f32_16x16x32_bf16 v[100:103], v[148:151], v[190:193], v[100:103]
	v_mfma_f32_16x16x32_bf16 v[84:87], v[148:151], v[198:201], v[84:87]
	v_mfma_f32_16x16x32_bf16 v[68:71], v[148:151], v[206:209], v[68:71]
	v_mfma_f32_16x16x32_bf16 v[64:67], v[156:159], v[206:209], v[64:67]
	v_mfma_f32_16x16x32_bf16 v[80:83], v[156:159], v[198:201], v[80:83]
	v_mfma_f32_16x16x32_bf16 v[96:99], v[156:159], v[190:193], v[96:99]
	v_mfma_f32_16x16x32_bf16 v[112:115], v[156:159], v[164:167], v[112:115]
	s_setprio 0
	s_barrier
; #define PG8_STAGE(bufoff, gbase, voff) do { _Pragma("unroll") for (int _i = 0; _i < 2; ++_i) \
;         __builtin_amdgcn_global_load_lds((const unsigned*)((const char*)(gbase) + (voff)[_i]), (PG8_LAS unsigned*)(lds + (bufoff) + ldsw + _i * 8192), 16, 0, 0); } while (0)
; #define PG8_LDA(dst, b, h) do { _Pragma("unroll") for (int m = 0; m < 4; ++m) _Pragma("unroll") for (int k = 0; k < 2; ++k) dst[m][k] = *(const PG8_LAS bf16x8*)(lds + PG8_SA(b, h) + aoff + m * 2048 + k * 1024); } while (0)
; #define PG8_LDB(dst, b, h) do { _Pragma("unroll") for (int n = 0; n < 2; ++n) _Pragma("unroll") for (int k = 0; k < 2; ++k) dst[n][k] = *(const PG8_LAS bf16x8*)(lds + PG8_SB(b, h) + boff + n * 2048 + k * 1024); } while (0)
; #define PG8_MMA(ai, bj, At, Bt) do { __builtin_amdgcn_s_setprio(1); _Pragma("unroll") for (int m = 0; m < 4; ++m) _Pragma("unroll") for (int n = 0; n < 2; ++n) _Pragma("unroll") for (int k = 0; k < 2; ++k) \
;         acc[ai][bj][m][n] = __builtin_amdgcn_mfma_f32_16x16x32_bf16(Bt[n][k], At[m][k], acc[ai][bj][m][n], 0, 0, 0); __builtin_amdgcn_s_setprio(0); } while (0)
; #define PG8_BAR __builtin_amdgcn_s_barrier()
; template <class Epi, class Sched, bool ALIGN_EPI = false, bool SP2 = false>
; __device__ __forceinline__ void gemm_phase(PG8_LAS unsigned char* lds, const Gemm g, const Sched& S, const Epi& E, const int wid) {
;     ...
;             PG8_LDB(B0, 0, 0); PG8_LDB(B1, 0, 1); PG8_SCHED; PG8_LDA(At, 0, 0); PG8_STAGE(PG8_SA(1, 1), a1 + hsA, voffA);
;             PG8_WAIT_V(8); PG8_WAIT_L(0); PG8_BAR; PG8_MMA(0, 0, At, B0); PG8_MMA(0, 1, At, B1); PG8_BAR; PG8_SCHED;
;             PG8_LDA(At, 0, 1); PG8_STAGE(PG8_SB(0, 0), b2, voffB); PG8_STAGE(PG8_SB(0, 1), b2 + hsB, voffB); PG8_STAGE(PG8_SA(0, 0), a2, voffA);
;             PG8_WAIT_V(8); PG8_WAIT_L(0); PG8_BAR; PG8_MMA(1, 0, At, B0); PG8_MMA(1, 1, At, B1); PG8_BAR; PG8_SCHED;
;             PG8_LDB(B0, 1, 0); PG8_LDB(B1, 1, 1); PG8_SCHED; PG8_LDA(At, 1, 0); PG8_STAGE(PG8_SA(0, 1), a2 + hsA, voffA);
;             PG8_WAIT_V(8); PG8_WAIT_L(0); PG8_BAR; PG8_MMA(0, 0, At, B0); PG8_MMA(0, 1, At, B1); PG8_BAR; PG8_SCHED;
;             PG8_LDA(At, 1, 1); PG8_STAGE(PG8_SB(1, 0), b3, voffB); PG8_STAGE(PG8_SB(1, 1), b3 + hsB, voffB); PG8_STAGE(PG8_SA(1, 0), a3, voffA);
;             PG8_WAIT_V(8); PG8_WAIT_L(0); PG8_BAR; PG8_MMA(1, 0, At, B0); PG8_MMA(1, 1, At, B1); PG8_BAR; PG8_SCHED;
	s_add_i32 s52, s88, s58
	v_lshl_add_u64 v[210:211], v[210:211], 0, s[26:27]
	s_mov_b32 m0, s52
	ds_read_b128 v[160:163], v239 offset:49152
	ds_read_b128 v[164:167], v239 offset:50176
	ds_read_b128 v[186:189], v239 offset:51200
	ds_read_b128 v[190:193], v239 offset:52224
	ds_read_b128 v[194:197], v239 offset:53248
	ds_read_b128 v[198:201], v239 offset:54272
	ds_read_b128 v[202:205], v239 offset:55296
	ds_read_b128 v[206:209], v239 offset:56320
	global_load_lds_dwordx4 v[210:211], off
	s_add_i32 m0, s52, 0x2000
	s_add_u32 s8, s8, 0x80080
	v_lshl_add_u64 v[210:211], v[212:213], 0, s[26:27]
	s_addc_u32 s9, s9, 0
	s_add_i32 s52, s89, s58
	global_load_lds_dwordx4 v[210:211], off
	v_lshl_add_u64 v[210:211], s[8:9], 0, v[170:171]
	s_mov_b32 m0, s52
	s_nop 0
	global_load_lds_dwordx4 v[210:211], off
	v_lshl_add_u64 v[210:211], s[8:9], 0, v[174:175]
	s_add_i32 m0, s52, 0x2000
	s_nop 0
	global_load_lds_dwordx4 v[210:211], off
	v_lshl_add_u64 v[210:211], v[214:215], 0, s[26:27]
	s_mov_b32 m0, s73
	s_nop 0
	global_load_lds_dwordx4 v[210:211], off
	v_lshl_add_u64 v[210:211], v[216:217], 0, s[26:27]
	s_mov_b32 m0, s74
	s_nop 0
	global_load_lds_dwordx4 v[210:211], off
	s_waitcnt vmcnt(8)
	s_waitcnt lgkmcnt(0)
	s_barrier
	s_setprio 1
	s_waitcnt lgkmcnt(0)
	v_mfma_f32_16x16x32_bf16 v[60:63], v[128:131], v[160:163], v[60:63]
	v_mfma_f32_16x16x32_bf16 v[44:47], v[128:131], v[186:189], v[44:47]
	v_mfma_f32_16x16x32_bf16 v[28:31], v[128:131], v[194:197], v[28:31]
	v_mfma_f32_16x16x32_bf16 v[12:15], v[128:131], v[202:205], v[12:15]
	v_mfma_f32_16x16x32_bf16 v[8:11], v[136:139], v[202:205], v[8:11]
	v_mfma_f32_16x16x32_bf16 v[24:27], v[136:139], v[194:197], v[24:27]
	v_mfma_f32_16x16x32_bf16 v[40:43], v[136:139], v[186:189], v[40:43]
	v_mfma_f32_16x16x32_bf16 v[56:59], v[136:139], v[160:163], v[56:59]
	v_mfma_f32_16x16x32_bf16 v[60:63], v[132:135], v[164:167], v[60:63]
	v_mfma_f32_16x16x32_bf16 v[44:47], v[132:135], v[190:193], v[44:47]
	v_mfma_f32_16x16x32_bf16 v[28:31], v[132:135], v[198:201], v[28:31]
	v_mfma_f32_16x16x32_bf16 v[12:15], v[132:135], v[206:209], v[12:15]
	v_mfma_f32_16x16x32_bf16 v[8:11], v[140:143], v[206:209], v[8:11]
	v_mfma_f32_16x16x32_bf16 v[24:27], v[140:143], v[198:201], v[24:27]
	v_mfma_f32_16x16x32_bf16 v[40:43], v[140:143], v[190:193], v[40:43]
	v_mfma_f32_16x16x32_bf16 v[56:59], v[140:143], v[164:167], v[56:59]
	s_setprio 0
	s_setprio 1
	v_mfma_f32_16x16x32_bf16 v[52:55], v[144:147], v[160:163], v[52:55]
	v_mfma_f32_16x16x32_bf16 v[36:39], v[144:147], v[186:189], v[36:39]
	v_mfma_f32_16x16x32_bf16 v[20:23], v[144:147], v[194:197], v[20:23]
	v_mfma_f32_16x16x32_bf16 v[4:7], v[144:147], v[202:205], v[4:7]
	v_mfma_f32_16x16x32_bf16 v[0:3], v[152:155], v[202:205], v[0:3]
	v_mfma_f32_16x16x32_bf16 v[16:19], v[152:155], v[194:197], v[16:19]
	v_mfma_f32_16x16x32_bf16 v[32:35], v[152:155], v[186:189], v[32:35]
	v_mfma_f32_16x16x32_bf16 v[48:51], v[152:155], v[160:163], v[48:51]
	v_mfma_f32_16x16x32_bf16 v[52:55], v[148:151], v[164:167], v[52:55]
	v_mfma_f32_16x16x32_bf16 v[36:39], v[148:151], v[190:193], v[36:39]
	v_mfma_f32_16x16x32_bf16 v[20:23], v[148:151], v[198:201], v[20:23]
	v_mfma_f32_16x16x32_bf16 v[4:7], v[148:151], v[206:209], v[4:7]
	v_mfma_f32_16x16x32_bf16 v[0:3], v[156:159], v[206:209], v[0:3]
	v_mfma_f32_16x16x32_bf16 v[16:19], v[156:159], v[198:201], v[16:19]
	v_mfma_f32_16x16x32_bf16 v[32:35], v[156:159], v[190:193], v[32:35]
	v_mfma_f32_16x16x32_bf16 v[48:51], v[156:159], v[164:167], v[48:51]
	s_setprio 0
	s_barrier
	s_add_i32 s87, s87, 2
	s_add_u32 s55, s55, 0x100
	s_addc_u32 s86, s86, 0
	s_add_u32 s6, s6, 0x100
	s_addc_u32 s7, s7, 0
	s_cmp_gt_u32 s87, 29
	s_cbranch_scc0 .LBB0_588
	s_and_b64 vcc, exec, s[28:29]
	s_cbranch_vccz .LBB0_591
	s_barrier

; #define PG8_STAGE(bufoff, gbase, voff) do { _Pragma("unroll") for (int _i = 0; _i < 2; ++_i) \
;         __builtin_amdgcn_global_load_lds((const unsigned*)((const char*)(gbase) + (voff)[_i]), (PG8_LAS unsigned*)(lds + (bufoff) + ldsw + _i * 8192), 16, 0, 0); } while (0)
; #define PG8_LDA(dst, b, h) do { _Pragma("unroll") for (int m = 0; m < 4; ++m) _Pragma("unroll") for (int k = 0; k < 2; ++k) dst[m][k] = *(const PG8_LAS bf16x8*)(lds + PG8_SA(b, h) + aoff + m * 2048 + k * 1024); } while (0)
; #define PG8_LDB(dst, b, h) do { _Pragma("unroll") for (int n = 0; n < 2; ++n) _Pragma("unroll") for (int k = 0; k < 2; ++k) dst[n][k] = *(const PG8_LAS bf16x8*)(lds + PG8_SB(b, h) + boff + n * 2048 + k * 1024); } while (0)
; #define PG8_MMA(ai, bj, At, Bt) do { __builtin_amdgcn_s_setprio(1); _Pragma("unroll") for (int m = 0; m < 4; ++m) _Pragma("unroll") for (int n = 0; n < 2; ++n) _Pragma("unroll") for (int k = 0; k < 2; ++k) \
;         acc[ai][bj][m][n] = __builtin_amdgcn_mfma_f32_16x16x32_bf16(Bt[n][k], At[m][k], acc[ai][bj][m][n], 0, 0, 0); __builtin_amdgcn_s_setprio(0); } while (0)
; #define PG8_BAR __builtin_amdgcn_s_barrier()
; template <class Epi, class Sched, bool ALIGN_EPI = false, bool SP2 = false>
; __device__ __forceinline__ void gemm_phase(PG8_LAS unsigned char* lds, const Gemm g, const Sched& S, const Epi& E, const int wid) {
;     ...
;             PG8_LDB(B0, 0, 0); PG8_LDB(B1, 0, 1); PG8_SCHED; PG8_LDA(At, 0, 0); PG8_STAGE(PG8_SA(1, 1), a1 + hsA, voffA);
;             PG8_WAIT_V(8); PG8_WAIT_L(0); PG8_BAR; PG8_MMA(0, 0, At, B0); PG8_MMA(0, 1, At, B1); PG8_BAR; PG8_SCHED;
;             PG8_LDA(At, 0, 1); PG8_STAGE(PG8_SB(0, 0), b2, voffB); PG8_STAGE(PG8_SB(0, 1), b2 + hsB, voffB); PG8_STAGE(PG8_SA(0, 0), a2, voffA);
;             PG8_WAIT_V(8); PG8_WAIT_L(0); PG8_BAR; PG8_MMA(1, 0, At, B0); PG8_MMA(1, 1, At, B1); PG8_BAR; PG8_SCHED;
;             PG8_LDB(B0, 1, 0); PG8_LDB(B1, 1, 1); PG8_SCHED; PG8_LDA(At, 1, 0); PG8_STAGE(PG8_SA(0, 1), a2 + hsA, voffA);
;             PG8_WAIT_V(8); PG8_WAIT_L(0); PG8_BAR; PG8_MMA(0, 0, At, B0); PG8_MMA(0, 1, At, B1); PG8_BAR; PG8_SCHED;
;             PG8_LDA(At, 1, 1); PG8_STAGE(PG8_SB(1, 0), b3, voffB); PG8_STAGE(PG8_SB(1, 1), b3 + hsB, voffB); PG8_STAGE(PG8_SA(1, 0), a3, voffA);
;             PG8_WAIT_V(8); PG8_WAIT_L(0); PG8_BAR; PG8_MMA(1, 0, At, B0); PG8_MMA(1, 1, At, B1); PG8_BAR; PG8_SCHED;
.LBB0_773:
	ds_read_b128 v[150:153], v147
	ds_read_b128 v[154:157], v147 offset:1024
	ds_read_b128 v[158:161], v147 offset:2048
	ds_read_b128 v[162:165], v147 offset:3072
	ds_read_b128 v[166:169], v148
	ds_read_b128 v[170:173], v148 offset:1024
	ds_read_b128 v[174:177], v148 offset:2048
	ds_read_b128 v[178:181], v148 offset:3072
	s_add_u32 s28, s26, 0x100
	s_addc_u32 s29, s27, 0
	s_cmp_eq_u32 s60, 8
	s_cselect_b32 s35, s5, s29
	s_cselect_b32 s34, s4, s28
	s_cselect_b32 s31, s25, s59
	s_cselect_b32 s30, s24, s58
	v_lshl_add_u64 v[214:215], s[26:27], 0, v[138:139]
	s_add_i32 m0, s40, 0xc000
	ds_read_b128 v[182:185], v149
	ds_read_b128 v[186:189], v149 offset:1024
	ds_read_b128 v[190:193], v149 offset:2048
	ds_read_b128 v[194:197], v149 offset:3072
	ds_read_b128 v[198:201], v149 offset:4096
	ds_read_b128 v[202:205], v149 offset:5120
	ds_read_b128 v[206:209], v149 offset:6144
	ds_read_b128 v[210:213], v149 offset:7168
	global_load_lds_dwordx4 v[214:215], off
	v_lshl_add_u64 v[214:215], s[26:27], 0, v[136:137]
	s_add_i32 m0, s40, 0xe000
	s_nop 0
	global_load_lds_dwordx4 v[214:215], off
	s_waitcnt vmcnt(8)
	s_waitcnt lgkmcnt(0)
	s_barrier
	s_setprio 1
	s_waitcnt lgkmcnt(0)
	v_mfma_f32_16x16x32_bf16 v[124:127], v[150:153], v[182:185], v[124:127]
	v_mfma_f32_16x16x32_bf16 v[116:119], v[150:153], v[190:193], v[116:119]
	v_mfma_f32_16x16x32_bf16 v[104:107], v[150:153], v[198:201], v[104:107]
	v_mfma_f32_16x16x32_bf16 v[88:91], v[150:153], v[206:209], v[88:91]
	v_mfma_f32_16x16x32_bf16 v[80:83], v[158:161], v[206:209], v[80:83]
	v_mfma_f32_16x16x32_bf16 v[96:99], v[158:161], v[198:201], v[96:99]
	v_mfma_f32_16x16x32_bf16 v[112:115], v[158:161], v[190:193], v[112:115]
	v_mfma_f32_16x16x32_bf16 v[120:123], v[158:161], v[182:185], v[120:123]
	v_mfma_f32_16x16x32_bf16 v[124:127], v[154:157], v[186:189], v[124:127]
	v_mfma_f32_16x16x32_bf16 v[116:119], v[154:157], v[194:197], v[116:119]
	v_mfma_f32_16x16x32_bf16 v[104:107], v[154:157], v[202:205], v[104:107]
	v_mfma_f32_16x16x32_bf16 v[88:91], v[154:157], v[210:213], v[88:91]
	v_mfma_f32_16x16x32_bf16 v[80:83], v[162:165], v[210:213], v[80:83]
	v_mfma_f32_16x16x32_bf16 v[96:99], v[162:165], v[202:205], v[96:99]
	v_mfma_f32_16x16x32_bf16 v[112:115], v[162:165], v[194:197], v[112:115]
	v_mfma_f32_16x16x32_bf16 v[120:123], v[162:165], v[186:189], v[120:123]
	s_setprio 0
	s_setprio 1
	v_mfma_f32_16x16x32_bf16 v[108:111], v[166:169], v[182:185], v[108:111]
	v_mfma_f32_16x16x32_bf16 v[92:95], v[166:169], v[190:193], v[92:95]
	v_mfma_f32_16x16x32_bf16 v[76:79], v[166:169], v[198:201], v[76:79]
	v_mfma_f32_16x16x32_bf16 v[68:71], v[166:169], v[206:209], v[68:71]
	v_mfma_f32_16x16x32_bf16 v[64:67], v[174:177], v[206:209], v[64:67]
	v_mfma_f32_16x16x32_bf16 v[72:75], v[174:177], v[198:201], v[72:75]
	v_mfma_f32_16x16x32_bf16 v[84:87], v[174:177], v[190:193], v[84:87]
	v_mfma_f32_16x16x32_bf16 v[100:103], v[174:177], v[182:185], v[100:103]
	v_mfma_f32_16x16x32_bf16 v[108:111], v[170:173], v[186:189], v[108:111]
	v_mfma_f32_16x16x32_bf16 v[92:95], v[170:173], v[194:197], v[92:95]
	v_mfma_f32_16x16x32_bf16 v[76:79], v[170:173], v[202:205], v[76:79]
	v_mfma_f32_16x16x32_bf16 v[68:71], v[170:173], v[210:213], v[68:71]
	v_mfma_f32_16x16x32_bf16 v[64:67], v[178:181], v[210:213], v[64:67]
	v_mfma_f32_16x16x32_bf16 v[72:75], v[178:181], v[202:205], v[72:75]
	v_mfma_f32_16x16x32_bf16 v[84:87], v[178:181], v[194:197], v[84:87]
	v_mfma_f32_16x16x32_bf16 v[100:103], v[178:181], v[186:189], v[100:103]
	s_setprio 0
	s_barrier
	s_add_i32 s26, s51, s38
	v_lshl_add_u64 v[214:215], s[30:31], 0, v[132:133]
	s_mov_b32 m0, s26
	ds_read_b128 v[182:185], v149 offset:16384
	ds_read_b128 v[186:189], v149 offset:17408
	ds_read_b128 v[190:193], v149 offset:18432
	ds_read_b128 v[194:197], v149 offset:19456
	ds_read_b128 v[198:201], v149 offset:20480
	ds_read_b128 v[202:205], v149 offset:21504
	ds_read_b128 v[206:209], v149 offset:22528
	ds_read_b128 v[210:213], v149 offset:23552
	global_load_lds_dwordx4 v[214:215], off
	s_add_i32 m0, s26, 0x2000
	s_add_u32 s26, s30, 0x30000
	v_lshl_add_u64 v[216:217], s[30:31], 0, v[128:129]
	s_addc_u32 s27, s31, 0
	s_add_i32 s61, s52, s38
	global_load_lds_dwordx4 v[216:217], off
	v_lshl_add_u64 v[218:219], s[26:27], 0, v[132:133]
	s_mov_b32 m0, s61
	v_lshl_add_u64 v[220:221], s[34:35], 0, v[130:131]
	global_load_lds_dwordx4 v[218:219], off
	v_lshl_add_u64 v[218:219], s[26:27], 0, v[128:129]
	s_add_i32 m0, s61, 0x2000
	s_nop 0
	global_load_lds_dwordx4 v[218:219], off
	v_lshl_add_u64 v[218:219], s[34:35], 0, v[134:135]
	s_mov_b32 m0, s40
	s_nop 0
	global_load_lds_dwordx4 v[218:219], off
	s_mov_b32 m0, s41
	s_nop 0
	global_load_lds_dwordx4 v[220:221], off
	s_waitcnt vmcnt(8)
	s_waitcnt lgkmcnt(0)
	s_barrier
; #define PG8_STAGE(bufoff, gbase, voff) do { _Pragma("unroll") for (int _i = 0; _i < 2; ++_i) \
;         __builtin_amdgcn_global_load_lds((const unsigned*)((const char*)(gbase) + (voff)[_i]), (PG8_LAS unsigned*)(lds + (bufoff) + ldsw + _i * 8192), 16, 0, 0); } while (0)
; #define PG8_LDA(dst, b, h) do { _Pragma("unroll") for (int m = 0; m < 4; ++m) _Pragma("unroll") for (int k = 0; k < 2; ++k) dst[m][k] = *(const PG8_LAS bf16x8*)(lds + PG8_SA(b, h) + aoff + m * 2048 + k * 1024); } while (0)
; #define PG8_LDB(dst, b, h) do { _Pragma("unroll") for (int n = 0; n < 2; ++n) _Pragma("unroll") for (int k = 0; k < 2; ++k) dst[n][k] = *(const PG8_LAS bf16x8*)(lds + PG8_SB(b, h) + boff + n * 2048 + k * 1024); } while (0)
; #define PG8_MMA(ai, bj, At, Bt) do { __builtin_amdgcn_s_setprio(1); _Pragma("unroll") for (int m = 0; m < 4; ++m) _Pragma("unroll") for (int n = 0; n < 2; ++n) _Pragma("unroll") for (int k = 0; k < 2; ++k) \
;         acc[ai][bj][m][n] = __builtin_amdgcn_mfma_f32_16x16x32_bf16(Bt[n][k], At[m][k], acc[ai][bj][m][n], 0, 0, 0); __builtin_amdgcn_s_setprio(0); } while (0)
; #define PG8_BAR __builtin_amdgcn_s_barrier()
; template <class Epi, class Sched, bool ALIGN_EPI = false, bool SP2 = false>
; __device__ __forceinline__ void gemm_phase(PG8_LAS unsigned char* lds, const Gemm g, const Sched& S, const Epi& E, const int wid) {
;     ...
;             PG8_LDB(B0, 0, 0); PG8_LDB(B1, 0, 1); PG8_SCHED; PG8_LDA(At, 0, 0); PG8_STAGE(PG8_SA(1, 1), a1 + hsA, voffA);
;             PG8_WAIT_V(8); PG8_WAIT_L(0); PG8_BAR; PG8_MMA(0, 0, At, B0); PG8_MMA(0, 1, At, B1); PG8_BAR; PG8_SCHED;
;             PG8_LDA(At, 0, 1); PG8_STAGE(PG8_SB(0, 0), b2, voffB); PG8_STAGE(PG8_SB(0, 1), b2 + hsB, voffB); PG8_STAGE(PG8_SA(0, 0), a2, voffA);
;             PG8_WAIT_V(8); PG8_WAIT_L(0); PG8_BAR; PG8_MMA(1, 0, At, B0); PG8_MMA(1, 1, At, B1); PG8_BAR; PG8_SCHED;
;             PG8_LDB(B0, 1, 0); PG8_LDB(B1, 1, 1); PG8_SCHED; PG8_LDA(At, 1, 0); PG8_STAGE(PG8_SA(0, 1), a2 + hsA, voffA);
;             PG8_WAIT_V(8); PG8_WAIT_L(0); PG8_BAR; PG8_MMA(0, 0, At, B0); PG8_MMA(0, 1, At, B1); PG8_BAR; PG8_SCHED;
;             PG8_LDA(At, 1, 1); PG8_STAGE(PG8_SB(1, 0), b3, voffB); PG8_STAGE(PG8_SB(1, 1), b3 + hsB, voffB); PG8_STAGE(PG8_SA(1, 0), a3, voffA);
;             PG8_WAIT_V(8); PG8_WAIT_L(0); PG8_BAR; PG8_MMA(1, 0, At, B0); PG8_MMA(1, 1, At, B1); PG8_BAR; PG8_SCHED;
	s_setprio 1
	s_waitcnt lgkmcnt(0)
	v_mfma_f32_16x16x32_bf16 v[60:63], v[150:153], v[182:185], v[60:63]
	v_mfma_f32_16x16x32_bf16 v[52:55], v[150:153], v[190:193], v[52:55]
	v_mfma_f32_16x16x32_bf16 v[40:43], v[150:153], v[198:201], v[40:43]
	v_mfma_f32_16x16x32_bf16 v[24:27], v[150:153], v[206:209], v[24:27]
	v_mfma_f32_16x16x32_bf16 v[16:19], v[158:161], v[206:209], v[16:19]
	v_mfma_f32_16x16x32_bf16 v[32:35], v[158:161], v[198:201], v[32:35]
	v_mfma_f32_16x16x32_bf16 v[48:51], v[158:161], v[190:193], v[48:51]
	v_mfma_f32_16x16x32_bf16 v[56:59], v[158:161], v[182:185], v[56:59]
	v_mfma_f32_16x16x32_bf16 v[60:63], v[154:157], v[186:189], v[60:63]
	v_mfma_f32_16x16x32_bf16 v[52:55], v[154:157], v[194:197], v[52:55]
	v_mfma_f32_16x16x32_bf16 v[40:43], v[154:157], v[202:205], v[40:43]
	v_mfma_f32_16x16x32_bf16 v[24:27], v[154:157], v[210:213], v[24:27]
	v_mfma_f32_16x16x32_bf16 v[16:19], v[162:165], v[210:213], v[16:19]
	v_mfma_f32_16x16x32_bf16 v[32:35], v[162:165], v[202:205], v[32:35]
	v_mfma_f32_16x16x32_bf16 v[48:51], v[162:165], v[194:197], v[48:51]
	v_mfma_f32_16x16x32_bf16 v[56:59], v[162:165], v[186:189], v[56:59]
	s_setprio 0
	s_setprio 1
	v_mfma_f32_16x16x32_bf16 v[44:47], v[166:169], v[182:185], v[44:47]
	v_mfma_f32_16x16x32_bf16 v[28:31], v[166:169], v[190:193], v[28:31]
	v_mfma_f32_16x16x32_bf16 v[12:15], v[166:169], v[198:201], v[12:15]
	v_mfma_f32_16x16x32_bf16 v[4:7], v[166:169], v[206:209], v[4:7]
	v_mfma_f32_16x16x32_bf16 v[0:3], v[174:177], v[206:209], v[0:3]
	v_mfma_f32_16x16x32_bf16 v[8:11], v[174:177], v[198:201], v[8:11]
	v_mfma_f32_16x16x32_bf16 v[20:23], v[174:177], v[190:193], v[20:23]
	v_mfma_f32_16x16x32_bf16 v[36:39], v[174:177], v[182:185], v[36:39]
	v_mfma_f32_16x16x32_bf16 v[44:47], v[170:173], v[186:189], v[44:47]
	v_mfma_f32_16x16x32_bf16 v[28:31], v[170:173], v[194:197], v[28:31]
	v_mfma_f32_16x16x32_bf16 v[12:15], v[170:173], v[202:205], v[12:15]
	v_mfma_f32_16x16x32_bf16 v[4:7], v[170:173], v[210:213], v[4:7]
	v_mfma_f32_16x16x32_bf16 v[0:3], v[178:181], v[210:213], v[0:3]
	v_mfma_f32_16x16x32_bf16 v[8:11], v[178:181], v[202:205], v[8:11]
	v_mfma_f32_16x16x32_bf16 v[20:23], v[178:181], v[194:197], v[20:23]
	v_mfma_f32_16x16x32_bf16 v[36:39], v[178:181], v[186:189], v[36:39]
	s_setprio 0
	s_barrier
	s_add_i32 s61, 0, 0x18000
	s_add_i32 s62, 0, 0x1c000
	v_add_u32_e32 v162, s61, v145
	v_add_u32_e32 v178, s62, v145
	ds_read_b128 v[150:153], v162
	ds_read_b128 v[154:157], v162 offset:1024
	ds_read_b128 v[158:161], v162 offset:2048
	ds_read_b128 v[162:165], v162 offset:3072
	ds_read_b128 v[166:169], v178
	ds_read_b128 v[170:173], v178 offset:1024
	ds_read_b128 v[174:177], v178 offset:2048
	ds_read_b128 v[178:181], v178 offset:3072
	s_add_u32 s26, s34, 0x600000
	s_addc_u32 s27, s35, 0
	s_mov_b32 m0, s42
	v_lshl_add_u64 v[222:223], s[26:27], 0, v[134:135]
	ds_read_b128 v[182:185], v149 offset:32768
	ds_read_b128 v[186:189], v149 offset:33792
	ds_read_b128 v[190:193], v149 offset:34816
	ds_read_b128 v[194:197], v149 offset:35840
	ds_read_b128 v[198:201], v149 offset:36864
	ds_read_b128 v[202:205], v149 offset:37888
	ds_read_b128 v[206:209], v149 offset:38912
	ds_read_b128 v[210:213], v149 offset:39936
	global_load_lds_dwordx4 v[222:223], off
	v_lshl_add_u64 v[222:223], s[26:27], 0, v[130:131]
	s_mov_b32 m0, s43
	s_nop 0
	global_load_lds_dwordx4 v[222:223], off
	s_waitcnt vmcnt(8)
	s_waitcnt lgkmcnt(0)
	s_barrier
	s_setprio 1
	s_waitcnt lgkmcnt(0)
	v_mfma_f32_16x16x32_bf16 v[124:127], v[150:153], v[182:185], v[124:127]
	v_mfma_f32_16x16x32_bf16 v[116:119], v[150:153], v[190:193], v[116:119]
	v_mfma_f32_16x16x32_bf16 v[104:107], v[150:153], v[198:201], v[104:107]
	v_mfma_f32_16x16x32_bf16 v[88:91], v[150:153], v[206:209], v[88:91]
	v_mfma_f32_16x16x32_bf16 v[80:83], v[158:161], v[206:209], v[80:83]
	v_mfma_f32_16x16x32_bf16 v[96:99], v[158:161], v[198:201], v[96:99]
	v_mfma_f32_16x16x32_bf16 v[112:115], v[158:161], v[190:193], v[112:115]
	v_mfma_f32_16x16x32_bf16 v[120:123], v[158:161], v[182:185], v[120:123]
	v_mfma_f32_16x16x32_bf16 v[124:127], v[154:157], v[186:189], v[124:127]
	v_mfma_f32_16x16x32_bf16 v[116:119], v[154:157], v[194:197], v[116:119]
	v_mfma_f32_16x16x32_bf16 v[104:107], v[154:157], v[202:205], v[104:107]
	v_mfma_f32_16x16x32_bf16 v[88:91], v[154:157], v[210:213], v[88:91]
	v_mfma_f32_16x16x32_bf16 v[80:83], v[162:165], v[210:213], v[80:83]
	v_mfma_f32_16x16x32_bf16 v[96:99], v[162:165], v[202:205], v[96:99]
	v_mfma_f32_16x16x32_bf16 v[112:115], v[162:165], v[194:197], v[112:115]
	v_mfma_f32_16x16x32_bf16 v[120:123], v[162:165], v[186:189], v[120:123]
	s_setprio 0
	s_setprio 1
	v_mfma_f32_16x16x32_bf16 v[108:111], v[166:169], v[182:185], v[108:111]
	v_mfma_f32_16x16x32_bf16 v[92:95], v[166:169], v[190:193], v[92:95]
	v_mfma_f32_16x16x32_bf16 v[76:79], v[166:169], v[198:201], v[76:79]
	v_mfma_f32_16x16x32_bf16 v[68:71], v[166:169], v[206:209], v[68:71]
	v_mfma_f32_16x16x32_bf16 v[64:67], v[174:177], v[206:209], v[64:67]
	v_mfma_f32_16x16x32_bf16 v[72:75], v[174:177], v[198:201], v[72:75]
	v_mfma_f32_16x16x32_bf16 v[84:87], v[174:177], v[190:193], v[84:87]
	v_mfma_f32_16x16x32_bf16 v[100:103], v[174:177], v[182:185], v[100:103]
	v_mfma_f32_16x16x32_bf16 v[108:111], v[170:173], v[186:189], v[108:111]
	v_mfma_f32_16x16x32_bf16 v[92:95], v[170:173], v[194:197], v[92:95]
	v_mfma_f32_16x16x32_bf16 v[76:79], v[170:173], v[202:205], v[76:79]
	v_mfma_f32_16x16x32_bf16 v[68:71], v[170:173], v[210:213], v[68:71]
	v_mfma_f32_16x16x32_bf16 v[64:67], v[178:181], v[210:213], v[64:67]
	v_mfma_f32_16x16x32_bf16 v[72:75], v[178:181], v[202:205], v[72:75]
	v_mfma_f32_16x16x32_bf16 v[84:87], v[178:181], v[194:197], v[84:87]
	v_mfma_f32_16x16x32_bf16 v[100:103], v[178:181], v[186:189], v[100:103]
	s_setprio 0
	s_barrier
; #define PG8_STAGE(bufoff, gbase, voff) do { _Pragma("unroll") for (int _i = 0; _i < 2; ++_i) \
;         __builtin_amdgcn_global_load_lds((const unsigned*)((const char*)(gbase) + (voff)[_i]), (PG8_LAS unsigned*)(lds + (bufoff) + ldsw + _i * 8192), 16, 0, 0); } while (0)
; #define PG8_LDA(dst, b, h) do { _Pragma("unroll") for (int m = 0; m < 4; ++m) _Pragma("unroll") for (int k = 0; k < 2; ++k) dst[m][k] = *(const PG8_LAS bf16x8*)(lds + PG8_SA(b, h) + aoff + m * 2048 + k * 1024); } while (0)
; #define PG8_LDB(dst, b, h) do { _Pragma("unroll") for (int n = 0; n < 2; ++n) _Pragma("unroll") for (int k = 0; k < 2; ++k) dst[n][k] = *(const PG8_LAS bf16x8*)(lds + PG8_SB(b, h) + boff + n * 2048 + k * 1024); } while (0)
; #define PG8_MMA(ai, bj, At, Bt) do { __builtin_amdgcn_s_setprio(1); _Pragma("unroll") for (int m = 0; m < 4; ++m) _Pragma("unroll") for (int n = 0; n < 2; ++n) _Pragma("unroll") for (int k = 0; k < 2; ++k) \
;         acc[ai][bj][m][n] = __builtin_amdgcn_mfma_f32_16x16x32_bf16(Bt[n][k], At[m][k], acc[ai][bj][m][n], 0, 0, 0); __builtin_amdgcn_s_setprio(0); } while (0)
; #define PG8_BAR __builtin_amdgcn_s_barrier()
; template <class Epi, class Sched, bool ALIGN_EPI = false, bool SP2 = false>
; __device__ __forceinline__ void gemm_phase(PG8_LAS unsigned char* lds, const Gemm g, const Sched& S, const Epi& E, const int wid) {
;     ...
;             PG8_LDB(B0, 0, 0); PG8_LDB(B1, 0, 1); PG8_SCHED; PG8_LDA(At, 0, 0); PG8_STAGE(PG8_SA(1, 1), a1 + hsA, voffA);
;             PG8_WAIT_V(8); PG8_WAIT_L(0); PG8_BAR; PG8_MMA(0, 0, At, B0); PG8_MMA(0, 1, At, B1); PG8_BAR; PG8_SCHED;
;             PG8_LDA(At, 0, 1); PG8_STAGE(PG8_SB(0, 0), b2, voffB); PG8_STAGE(PG8_SB(0, 1), b2 + hsB, voffB); PG8_STAGE(PG8_SA(0, 0), a2, voffA);
;             PG8_WAIT_V(8); PG8_WAIT_L(0); PG8_BAR; PG8_MMA(1, 0, At, B0); PG8_MMA(1, 1, At, B1); PG8_BAR; PG8_SCHED;
;             PG8_LDB(B0, 1, 0); PG8_LDB(B1, 1, 1); PG8_SCHED; PG8_LDA(At, 1, 0); PG8_STAGE(PG8_SA(0, 1), a2 + hsA, voffA);
;             PG8_WAIT_V(8); PG8_WAIT_L(0); PG8_BAR; PG8_MMA(0, 0, At, B0); PG8_MMA(0, 1, At, B1); PG8_BAR; PG8_SCHED;
;             PG8_LDA(At, 1, 1); PG8_STAGE(PG8_SB(1, 0), b3, voffB); PG8_STAGE(PG8_SB(1, 1), b3 + hsB, voffB); PG8_STAGE(PG8_SA(1, 0), a3, voffA);
;             PG8_WAIT_V(8); PG8_WAIT_L(0); PG8_BAR; PG8_MMA(1, 0, At, B0); PG8_MMA(1, 1, At, B1); PG8_BAR; PG8_SCHED;
	s_add_i32 s26, s61, s38
	v_lshl_add_u64 v[214:215], v[214:215], 0, s[12:13]
	s_mov_b32 m0, s26
	ds_read_b128 v[182:185], v149 offset:49152
	ds_read_b128 v[186:189], v149 offset:50176
	ds_read_b128 v[190:193], v149 offset:51200
	ds_read_b128 v[194:197], v149 offset:52224
	ds_read_b128 v[198:201], v149 offset:53248
	ds_read_b128 v[202:205], v149 offset:54272
	ds_read_b128 v[206:209], v149 offset:55296
	ds_read_b128 v[210:213], v149 offset:56320
	global_load_lds_dwordx4 v[214:215], off
	s_add_i32 m0, s26, 0x2000
	s_add_u32 s26, s30, 0x30080
	v_lshl_add_u64 v[214:215], v[216:217], 0, s[12:13]
	s_addc_u32 s27, s31, 0
	s_add_i32 s30, s62, s38
	global_load_lds_dwordx4 v[214:215], off
	v_lshl_add_u64 v[214:215], s[26:27], 0, v[132:133]
	s_mov_b32 m0, s30
	s_nop 0
	global_load_lds_dwordx4 v[214:215], off
	v_lshl_add_u64 v[214:215], s[26:27], 0, v[128:129]
	s_add_i32 m0, s30, 0x2000
	s_nop 0
	global_load_lds_dwordx4 v[214:215], off
	v_lshl_add_u64 v[214:215], v[218:219], 0, s[12:13]
	s_mov_b32 m0, s46
	s_nop 0
	global_load_lds_dwordx4 v[214:215], off
	v_lshl_add_u64 v[214:215], v[220:221], 0, s[12:13]
	s_mov_b32 m0, s47
	s_nop 0
	global_load_lds_dwordx4 v[214:215], off
	s_waitcnt vmcnt(8)
	s_waitcnt lgkmcnt(0)
	s_barrier
	s_setprio 1
	s_waitcnt lgkmcnt(0)
	v_mfma_f32_16x16x32_bf16 v[60:63], v[150:153], v[182:185], v[60:63]
	v_mfma_f32_16x16x32_bf16 v[52:55], v[150:153], v[190:193], v[52:55]
	v_mfma_f32_16x16x32_bf16 v[40:43], v[150:153], v[198:201], v[40:43]
	v_mfma_f32_16x16x32_bf16 v[24:27], v[150:153], v[206:209], v[24:27]
	v_mfma_f32_16x16x32_bf16 v[16:19], v[158:161], v[206:209], v[16:19]
	v_mfma_f32_16x16x32_bf16 v[32:35], v[158:161], v[198:201], v[32:35]
	v_mfma_f32_16x16x32_bf16 v[48:51], v[158:161], v[190:193], v[48:51]
	v_mfma_f32_16x16x32_bf16 v[56:59], v[158:161], v[182:185], v[56:59]
	v_mfma_f32_16x16x32_bf16 v[60:63], v[154:157], v[186:189], v[60:63]
	v_mfma_f32_16x16x32_bf16 v[52:55], v[154:157], v[194:197], v[52:55]
	v_mfma_f32_16x16x32_bf16 v[40:43], v[154:157], v[202:205], v[40:43]
	v_mfma_f32_16x16x32_bf16 v[24:27], v[154:157], v[210:213], v[24:27]
	v_mfma_f32_16x16x32_bf16 v[16:19], v[162:165], v[210:213], v[16:19]
	v_mfma_f32_16x16x32_bf16 v[32:35], v[162:165], v[202:205], v[32:35]
	v_mfma_f32_16x16x32_bf16 v[48:51], v[162:165], v[194:197], v[48:51]
	v_mfma_f32_16x16x32_bf16 v[56:59], v[162:165], v[186:189], v[56:59]
	s_setprio 0
	s_setprio 1
	v_mfma_f32_16x16x32_bf16 v[44:47], v[166:169], v[182:185], v[44:47]
	v_mfma_f32_16x16x32_bf16 v[28:31], v[166:169], v[190:193], v[28:31]
	v_mfma_f32_16x16x32_bf16 v[12:15], v[166:169], v[198:201], v[12:15]
	v_mfma_f32_16x16x32_bf16 v[4:7], v[166:169], v[206:209], v[4:7]
	v_mfma_f32_16x16x32_bf16 v[0:3], v[174:177], v[206:209], v[0:3]
	v_mfma_f32_16x16x32_bf16 v[8:11], v[174:177], v[198:201], v[8:11]
	v_mfma_f32_16x16x32_bf16 v[20:23], v[174:177], v[190:193], v[20:23]
	v_mfma_f32_16x16x32_bf16 v[36:39], v[174:177], v[182:185], v[36:39]
	v_mfma_f32_16x16x32_bf16 v[44:47], v[170:173], v[186:189], v[44:47]
	v_mfma_f32_16x16x32_bf16 v[28:31], v[170:173], v[194:197], v[28:31]
	v_mfma_f32_16x16x32_bf16 v[12:15], v[170:173], v[202:205], v[12:15]
	v_mfma_f32_16x16x32_bf16 v[4:7], v[170:173], v[210:213], v[4:7]
	v_mfma_f32_16x16x32_bf16 v[0:3], v[178:181], v[210:213], v[0:3]
	v_mfma_f32_16x16x32_bf16 v[8:11], v[178:181], v[202:205], v[8:11]
	v_mfma_f32_16x16x32_bf16 v[20:23], v[178:181], v[194:197], v[20:23]
	v_mfma_f32_16x16x32_bf16 v[36:39], v[178:181], v[186:189], v[36:39]
	s_setprio 0
	s_barrier
	s_add_i32 s60, s60, 2
	s_add_u32 s58, s58, 0x100
	s_addc_u32 s59, s59, 0
	s_cmp_gt_u32 s60, 9
	s_mov_b64 s[26:27], s[28:29]
	s_cbranch_scc0 .LBB0_773
	s_and_b64 vcc, exec, s[14:15]
	s_cbranch_vccz .LBB0_776
	s_barrier

; #define PG8_STAGE(bufoff, gbase, voff) do { _Pragma("unroll") for (int _i = 0; _i < 2; ++_i) \
;         __builtin_amdgcn_global_load_lds((const unsigned*)((const char*)(gbase) + (voff)[_i]), (PG8_LAS unsigned*)(lds + (bufoff) + ldsw + _i * 8192), 16, 0, 0); } while (0)
; #define PG8_LDA(dst, b, h) do { _Pragma("unroll") for (int m = 0; m < 4; ++m) _Pragma("unroll") for (int k = 0; k < 2; ++k) dst[m][k] = *(const PG8_LAS bf16x8*)(lds + PG8_SA(b, h) + aoff + m * 2048 + k * 1024); } while (0)
; #define PG8_LDB(dst, b, h) do { _Pragma("unroll") for (int n = 0; n < 2; ++n) _Pragma("unroll") for (int k = 0; k < 2; ++k) dst[n][k] = *(const PG8_LAS bf16x8*)(lds + PG8_SB(b, h) + boff + n * 2048 + k * 1024); } while (0)
; #define PG8_MMA(ai, bj, At, Bt) do { __builtin_amdgcn_s_setprio(1); _Pragma("unroll") for (int m = 0; m < 4; ++m) _Pragma("unroll") for (int n = 0; n < 2; ++n) _Pragma("unroll") for (int k = 0; k < 2; ++k) \
;         acc[ai][bj][m][n] = __builtin_amdgcn_mfma_f32_16x16x32_bf16(Bt[n][k], At[m][k], acc[ai][bj][m][n], 0, 0, 0); __builtin_amdgcn_s_setprio(0); } while (0)
; #define PG8_BAR __builtin_amdgcn_s_barrier()
; template <class Epi, class Sched, bool ALIGN_EPI = false, bool SP2 = false>
; __device__ __forceinline__ void gemm_phase(PG8_LAS unsigned char* lds, const Gemm g, const Sched& S, const Epi& E, const int wid) {
;     ...
;             PG8_LDB(B0, 0, 0); PG8_LDB(B1, 0, 1); PG8_SCHED; PG8_LDA(At, 0, 0); PG8_STAGE(PG8_SA(1, 1), a1 + hsA, voffA);
;             PG8_WAIT_V(8); PG8_WAIT_L(0); PG8_BAR; PG8_MMA(0, 0, At, B0); PG8_MMA(0, 1, At, B1); PG8_BAR; PG8_SCHED;
;             PG8_LDA(At, 0, 1); PG8_STAGE(PG8_SB(0, 0), b2, voffB); PG8_STAGE(PG8_SB(0, 1), b2 + hsB, voffB); PG8_STAGE(PG8_SA(0, 0), a2, voffA);
;             PG8_WAIT_V(8); PG8_WAIT_L(0); PG8_BAR; PG8_MMA(1, 0, At, B0); PG8_MMA(1, 1, At, B1); PG8_BAR; PG8_SCHED;
;             PG8_LDB(B0, 1, 0); PG8_LDB(B1, 1, 1); PG8_SCHED; PG8_LDA(At, 1, 0); PG8_STAGE(PG8_SA(0, 1), a2 + hsA, voffA);
;             PG8_WAIT_V(8); PG8_WAIT_L(0); PG8_BAR; PG8_MMA(0, 0, At, B0); PG8_MMA(0, 1, At, B1); PG8_BAR; PG8_SCHED;
;             PG8_LDA(At, 1, 1); PG8_STAGE(PG8_SB(1, 0), b3, voffB); PG8_STAGE(PG8_SB(1, 1), b3 + hsB, voffB); PG8_STAGE(PG8_SA(1, 0), a3, voffA);
;             PG8_WAIT_V(8); PG8_WAIT_L(0); PG8_BAR; PG8_MMA(1, 0, At, B0); PG8_MMA(1, 1, At, B1); PG8_BAR; PG8_SCHED;
.LBB0_958:
	ds_read_b128 v[8:11], v164
	ds_read_b128 v[12:15], v164 offset:1024
	ds_read_b128 v[16:19], v164 offset:2048
	ds_read_b128 v[20:23], v164 offset:3072
	ds_read_b128 v[24:27], v165
	ds_read_b128 v[28:31], v165 offset:1024
	s_waitcnt vmcnt(0)
	ds_read_b128 v[32:35], v165 offset:2048
	ds_read_b128 v[36:39], v165 offset:3072
	s_add_u32 s66, s40, 0x600080
	s_addc_u32 s67, s41, 0
	s_add_i32 s78, s46, 0xc000
	v_lshl_add_u64 v[64:65], s[66:67], 0, v[150:151]
	s_mov_b32 m0, s78
	s_add_i32 s65, s46, 0xe000
	ds_read_b128 v[0:3], v163
	ds_read_b128 v[4:7], v163 offset:1024
	ds_read_b128 v[40:43], v163 offset:2048
	ds_read_b128 v[44:47], v163 offset:3072
	ds_read_b128 v[48:51], v163 offset:4096
	ds_read_b128 v[52:55], v163 offset:5120
	ds_read_b128 v[56:59], v163 offset:6144
	ds_read_b128 v[60:63], v163 offset:7168
	global_load_lds_dwordx4 v[64:65], off
	v_lshl_add_u64 v[64:65], s[66:67], 0, v[146:147]
	s_mov_b32 m0, s65
	s_nop 0
	global_load_lds_dwordx4 v[64:65], off
	s_waitcnt vmcnt(8)
	s_waitcnt lgkmcnt(0)
	s_barrier
	s_setprio 1
	s_waitcnt lgkmcnt(0)
	v_mfma_f32_16x16x32_bf16 v[64:67], v[8:11], v[0:3], 0
	v_mfma_f32_16x16x32_bf16 v[68:71], v[16:19], v[0:3], 0
	v_mfma_f32_16x16x32_bf16 v[72:75], v[8:11], v[40:43], 0
	v_mfma_f32_16x16x32_bf16 v[76:79], v[16:19], v[40:43], 0
	v_mfma_f32_16x16x32_bf16 v[80:83], v[8:11], v[48:51], 0
	v_mfma_f32_16x16x32_bf16 v[84:87], v[16:19], v[48:51], 0
	v_mfma_f32_16x16x32_bf16 v[88:91], v[8:11], v[56:59], 0
	v_mfma_f32_16x16x32_bf16 v[92:95], v[16:19], v[56:59], 0
	v_mfma_f32_16x16x32_bf16 v[64:67], v[12:15], v[4:7], v[64:67]
	v_mfma_f32_16x16x32_bf16 v[68:71], v[20:23], v[4:7], v[68:71]
	v_mfma_f32_16x16x32_bf16 v[72:75], v[12:15], v[44:47], v[72:75]
	v_mfma_f32_16x16x32_bf16 v[76:79], v[20:23], v[44:47], v[76:79]
	v_mfma_f32_16x16x32_bf16 v[80:83], v[12:15], v[52:55], v[80:83]
	v_mfma_f32_16x16x32_bf16 v[84:87], v[20:23], v[52:55], v[84:87]
	v_mfma_f32_16x16x32_bf16 v[88:91], v[12:15], v[60:63], v[88:91]
	v_mfma_f32_16x16x32_bf16 v[92:95], v[20:23], v[60:63], v[92:95]
	s_setprio 0
	s_setprio 1
	v_mfma_f32_16x16x32_bf16 v[96:99], v[24:27], v[0:3], 0
	v_mfma_f32_16x16x32_bf16 v[0:3], v[32:35], v[0:3], 0
	v_mfma_f32_16x16x32_bf16 v[100:103], v[36:39], v[4:7], v[0:3]
	v_mfma_f32_16x16x32_bf16 v[0:3], v[24:27], v[40:43], 0
	v_mfma_f32_16x16x32_bf16 v[104:107], v[28:31], v[44:47], v[0:3]
	v_mfma_f32_16x16x32_bf16 v[0:3], v[32:35], v[40:43], 0
	v_mfma_f32_16x16x32_bf16 v[40:43], v[36:39], v[44:47], v[0:3]
	v_mfma_f32_16x16x32_bf16 v[0:3], v[24:27], v[48:51], 0
	v_mfma_f32_16x16x32_bf16 v[44:47], v[28:31], v[52:55], v[0:3]
	v_mfma_f32_16x16x32_bf16 v[0:3], v[32:35], v[48:51], 0
	v_mfma_f32_16x16x32_bf16 v[48:51], v[36:39], v[52:55], v[0:3]
	v_mfma_f32_16x16x32_bf16 v[0:3], v[24:27], v[56:59], 0
	v_mfma_f32_16x16x32_bf16 v[52:55], v[28:31], v[60:63], v[0:3]
	v_mfma_f32_16x16x32_bf16 v[0:3], v[32:35], v[56:59], 0
	v_mfma_f32_16x16x32_bf16 v[96:99], v[28:31], v[4:7], v[96:99]
	v_mfma_f32_16x16x32_bf16 v[56:59], v[36:39], v[60:63], v[0:3]
	s_setprio 0
	s_barrier
	s_nop 3
	v_lshl_add_u64 v[0:1], s[42:43], 0, v[148:149]
	s_add_i32 s75, s57, s3
	v_lshl_add_u64 v[2:3], v[0:1], 0, s[20:21]
	s_mov_b32 m0, s75
	s_add_i32 s66, s75, 0x2000
	ds_read_b128 v[60:63], v163 offset:16384
	ds_read_b128 v[108:111], v163 offset:17408
	ds_read_b128 v[112:115], v163 offset:18432
	ds_read_b128 v[116:119], v163 offset:19456
	ds_read_b128 v[120:123], v163 offset:20480
	ds_read_b128 v[124:127], v163 offset:21504
	ds_read_b128 v[128:131], v163 offset:22528
	ds_read_b128 v[132:135], v163 offset:23552
	global_load_lds_dwordx4 v[2:3], off
	v_lshl_add_u64 v[2:3], s[42:43], 0, v[144:145]
	s_add_u32 s76, s42, 0x18100
	v_lshl_add_u64 v[4:5], v[2:3], 0, s[20:21]
	s_mov_b32 m0, s66
	s_addc_u32 s77, s43, 0
	s_add_i32 s67, s58, s3
	global_load_lds_dwordx4 v[4:5], off
	v_lshl_add_u64 v[4:5], s[76:77], 0, v[148:149]
	s_mov_b32 m0, s67
	s_add_i32 s74, s67, 0x2000
	global_load_lds_dwordx4 v[4:5], off
	v_lshl_add_u64 v[4:5], s[76:77], 0, v[144:145]
	s_mov_b32 m0, s74
	s_nop 0
	global_load_lds_dwordx4 v[4:5], off
	v_lshl_add_u64 v[4:5], s[40:41], 0, v[150:151]
	v_lshl_add_u64 v[6:7], v[4:5], 0, s[20:21]
	s_mov_b32 m0, s46
	s_nop 0
	global_load_lds_dwordx4 v[6:7], off
	v_lshl_add_u64 v[6:7], s[40:41], 0, v[146:147]
	v_lshl_add_u64 v[136:137], v[6:7], 0, s[20:21]
	s_mov_b32 m0, s47
	s_nop 0
	global_load_lds_dwordx4 v[136:137], off
	s_waitcnt vmcnt(8)
	s_waitcnt lgkmcnt(0)
	s_barrier
	s_setprio 1
	s_waitcnt lgkmcnt(0)
	v_mfma_f32_16x16x32_bf16 v[136:139], v[8:11], v[60:63], 0
	v_mfma_f32_16x16x32_bf16 v[158:161], v[8:11], v[112:115], 0
	v_mfma_f32_16x16x32_bf16 v[170:173], v[8:11], v[120:123], 0
	v_mfma_f32_16x16x32_bf16 v[8:11], v[8:11], v[128:131], 0
	v_mfma_f32_16x16x32_bf16 v[136:139], v[12:15], v[108:111], v[136:139]
	v_mfma_f32_16x16x32_bf16 v[140:143], v[16:19], v[60:63], 0
	v_mfma_f32_16x16x32_bf16 v[158:161], v[12:15], v[116:119], v[158:161]
	v_mfma_f32_16x16x32_bf16 v[166:169], v[16:19], v[112:115], 0
	v_mfma_f32_16x16x32_bf16 v[170:173], v[12:15], v[124:127], v[170:173]
	v_mfma_f32_16x16x32_bf16 v[174:177], v[16:19], v[120:123], 0
	v_mfma_f32_16x16x32_bf16 v[10:13], v[12:15], v[132:135], v[8:11]
	v_mfma_f32_16x16x32_bf16 v[14:17], v[16:19], v[128:131], 0
	v_mfma_f32_16x16x32_bf16 v[14:17], v[20:23], v[132:135], v[14:17]
	v_mfma_f32_16x16x32_bf16 v[140:143], v[20:23], v[108:111], v[140:143]
	v_mfma_f32_16x16x32_bf16 v[166:169], v[20:23], v[116:119], v[166:169]
	v_mfma_f32_16x16x32_bf16 v[174:177], v[20:23], v[124:127], v[174:177]
	s_setprio 0
	s_setprio 1
	v_mfma_f32_16x16x32_bf16 v[18:21], v[24:27], v[60:63], 0
	v_mfma_f32_16x16x32_bf16 v[60:63], v[32:35], v[60:63], 0
	v_mfma_f32_16x16x32_bf16 v[18:21], v[28:31], v[108:111], v[18:21]
	v_mfma_f32_16x16x32_bf16 v[60:63], v[36:39], v[108:111], v[60:63]
	v_mfma_f32_16x16x32_bf16 v[108:111], v[24:27], v[112:115], 0
	v_mfma_f32_16x16x32_bf16 v[112:115], v[32:35], v[112:115], 0
	v_mfma_f32_16x16x32_bf16 v[108:111], v[28:31], v[116:119], v[108:111]
	v_mfma_f32_16x16x32_bf16 v[112:115], v[36:39], v[116:119], v[112:115]
	v_mfma_f32_16x16x32_bf16 v[116:119], v[24:27], v[120:123], 0
	v_mfma_f32_16x16x32_bf16 v[22:25], v[24:27], v[128:131], 0
	v_mfma_f32_16x16x32_bf16 v[116:119], v[28:31], v[124:127], v[116:119]
	v_mfma_f32_16x16x32_bf16 v[22:25], v[28:31], v[132:135], v[22:25]
	v_mfma_f32_16x16x32_bf16 v[26:29], v[32:35], v[128:131], 0
	v_mfma_f32_16x16x32_bf16 v[120:123], v[32:35], v[120:123], 0
	v_mfma_f32_16x16x32_bf16 v[26:29], v[36:39], v[132:135], v[26:29]
	v_mfma_f32_16x16x32_bf16 v[120:123], v[36:39], v[124:127], v[120:123]
	s_setprio 0
	s_barrier
; #define PG8_STAGE(bufoff, gbase, voff) do { _Pragma("unroll") for (int _i = 0; _i < 2; ++_i) \
;         __builtin_amdgcn_global_load_lds((const unsigned*)((const char*)(gbase) + (voff)[_i]), (PG8_LAS unsigned*)(lds + (bufoff) + ldsw + _i * 8192), 16, 0, 0); } while (0)
; #define PG8_LDA(dst, b, h) do { _Pragma("unroll") for (int m = 0; m < 4; ++m) _Pragma("unroll") for (int k = 0; k < 2; ++k) dst[m][k] = *(const PG8_LAS bf16x8*)(lds + PG8_SA(b, h) + aoff + m * 2048 + k * 1024); } while (0)
; #define PG8_LDB(dst, b, h) do { _Pragma("unroll") for (int n = 0; n < 2; ++n) _Pragma("unroll") for (int k = 0; k < 2; ++k) dst[n][k] = *(const PG8_LAS bf16x8*)(lds + PG8_SB(b, h) + boff + n * 2048 + k * 1024); } while (0)
; #define PG8_MMA(ai, bj, At, Bt) do { __builtin_amdgcn_s_setprio(1); _Pragma("unroll") for (int m = 0; m < 4; ++m) _Pragma("unroll") for (int n = 0; n < 2; ++n) _Pragma("unroll") for (int k = 0; k < 2; ++k) \
;         acc[ai][bj][m][n] = __builtin_amdgcn_mfma_f32_16x16x32_bf16(Bt[n][k], At[m][k], acc[ai][bj][m][n], 0, 0, 0); __builtin_amdgcn_s_setprio(0); } while (0)
; #define PG8_BAR __builtin_amdgcn_s_barrier()
; template <class Epi, class Sched, bool ALIGN_EPI = false, bool SP2 = false>
; __device__ __forceinline__ void gemm_phase(PG8_LAS unsigned char* lds, const Gemm g, const Sched& S, const Epi& E, const int wid) {
;     ...
;             PG8_LDB(B0, 0, 0); PG8_LDB(B1, 0, 1); PG8_SCHED; PG8_LDA(At, 0, 0); PG8_STAGE(PG8_SA(1, 1), a1 + hsA, voffA);
;             PG8_WAIT_V(8); PG8_WAIT_L(0); PG8_BAR; PG8_MMA(0, 0, At, B0); PG8_MMA(0, 1, At, B1); PG8_BAR; PG8_SCHED;
;             PG8_LDA(At, 0, 1); PG8_STAGE(PG8_SB(0, 0), b2, voffB); PG8_STAGE(PG8_SB(0, 1), b2 + hsB, voffB); PG8_STAGE(PG8_SA(0, 0), a2, voffA);
;             PG8_WAIT_V(8); PG8_WAIT_L(0); PG8_BAR; PG8_MMA(1, 0, At, B0); PG8_MMA(1, 1, At, B1); PG8_BAR; PG8_SCHED;
;             PG8_LDB(B0, 1, 0); PG8_LDB(B1, 1, 1); PG8_SCHED; PG8_LDA(At, 1, 0); PG8_STAGE(PG8_SA(0, 1), a2 + hsA, voffA);
;             PG8_WAIT_V(8); PG8_WAIT_L(0); PG8_BAR; PG8_MMA(0, 0, At, B0); PG8_MMA(0, 1, At, B1); PG8_BAR; PG8_SCHED;
;             PG8_LDA(At, 1, 1); PG8_STAGE(PG8_SB(1, 0), b3, voffB); PG8_STAGE(PG8_SB(1, 1), b3 + hsB, voffB); PG8_STAGE(PG8_SA(1, 0), a3, voffA);
;             PG8_WAIT_V(8); PG8_WAIT_L(0); PG8_BAR; PG8_MMA(1, 0, At, B0); PG8_MMA(1, 1, At, B1); PG8_BAR; PG8_SCHED;
	s_add_i32 s81, 0, 0x18000
	s_add_i32 s79, 0, 0x1c000
	v_add_u32_e32 v8, s81, v162
	v_add_u32_e32 v9, s79, v162
	ds_read_b128 v[30:33], v8
	ds_read_b128 v[34:37], v8 offset:1024
	ds_read_b128 v[124:127], v8 offset:2048
	ds_read_b128 v[128:131], v8 offset:3072
	ds_read_b128 v[132:135], v9
	ds_read_b128 v[178:181], v9 offset:1024
	ds_read_b128 v[182:185], v9 offset:2048
	ds_read_b128 v[186:189], v9 offset:3072
	s_add_u32 s76, s40, 0x600100
	s_addc_u32 s77, s41, 0
	s_mov_b32 m0, s48
	v_lshl_add_u64 v[38:39], s[76:77], 0, v[150:151]
	ds_read_b128 v[190:193], v163 offset:32768
	ds_read_b128 v[194:197], v163 offset:33792
	ds_read_b128 v[198:201], v163 offset:34816
	ds_read_b128 v[202:205], v163 offset:35840
	ds_read_b128 v[206:209], v163 offset:36864
	ds_read_b128 v[210:213], v163 offset:37888
	ds_read_b128 v[214:217], v163 offset:38912
	ds_read_b128 v[218:221], v163 offset:39936
	global_load_lds_dwordx4 v[38:39], off
	v_lshl_add_u64 v[38:39], s[76:77], 0, v[146:147]
	s_mov_b32 m0, s49
	s_nop 0
	global_load_lds_dwordx4 v[38:39], off
	s_waitcnt vmcnt(8)
	s_waitcnt lgkmcnt(0)
	s_barrier
	s_setprio 1
	s_waitcnt lgkmcnt(0)
	v_mfma_f32_16x16x32_bf16 v[64:67], v[30:33], v[190:193], v[64:67]
	v_mfma_f32_16x16x32_bf16 v[72:75], v[30:33], v[198:201], v[72:75]
	v_mfma_f32_16x16x32_bf16 v[80:83], v[30:33], v[206:209], v[80:83]
	v_mfma_f32_16x16x32_bf16 v[88:91], v[30:33], v[214:217], v[88:91]
	v_mfma_f32_16x16x32_bf16 v[92:95], v[124:127], v[214:217], v[92:95]
	v_mfma_f32_16x16x32_bf16 v[84:87], v[124:127], v[206:209], v[84:87]
	v_mfma_f32_16x16x32_bf16 v[76:79], v[124:127], v[198:201], v[76:79]
	v_mfma_f32_16x16x32_bf16 v[68:71], v[124:127], v[190:193], v[68:71]
	v_mfma_f32_16x16x32_bf16 v[64:67], v[34:37], v[194:197], v[64:67]
	v_mfma_f32_16x16x32_bf16 v[72:75], v[34:37], v[202:205], v[72:75]
	v_mfma_f32_16x16x32_bf16 v[80:83], v[34:37], v[210:213], v[80:83]
	v_mfma_f32_16x16x32_bf16 v[88:91], v[34:37], v[218:221], v[88:91]
	v_mfma_f32_16x16x32_bf16 v[92:95], v[128:131], v[218:221], v[92:95]
	v_mfma_f32_16x16x32_bf16 v[84:87], v[128:131], v[210:213], v[84:87]
	v_mfma_f32_16x16x32_bf16 v[76:79], v[128:131], v[202:205], v[76:79]
	v_mfma_f32_16x16x32_bf16 v[68:71], v[128:131], v[194:197], v[68:71]
	s_setprio 0
	s_setprio 1
	v_mfma_f32_16x16x32_bf16 v[96:99], v[132:135], v[190:193], v[96:99]
	v_mfma_f32_16x16x32_bf16 v[100:103], v[182:185], v[190:193], v[100:103]
	v_mfma_f32_16x16x32_bf16 v[104:107], v[132:135], v[198:201], v[104:107]
	v_mfma_f32_16x16x32_bf16 v[38:41], v[182:185], v[198:201], v[40:43]
	v_mfma_f32_16x16x32_bf16 v[42:45], v[132:135], v[206:209], v[44:47]
	v_mfma_f32_16x16x32_bf16 v[46:49], v[182:185], v[206:209], v[48:51]
	v_mfma_f32_16x16x32_bf16 v[50:53], v[132:135], v[214:217], v[52:55]
	v_mfma_f32_16x16x32_bf16 v[54:57], v[182:185], v[214:217], v[56:59]
	v_mfma_f32_16x16x32_bf16 v[96:99], v[178:181], v[194:197], v[96:99]
	v_mfma_f32_16x16x32_bf16 v[100:103], v[186:189], v[194:197], v[100:103]
	v_mfma_f32_16x16x32_bf16 v[104:107], v[178:181], v[202:205], v[104:107]
	v_mfma_f32_16x16x32_bf16 v[38:41], v[186:189], v[202:205], v[38:41]
	v_mfma_f32_16x16x32_bf16 v[42:45], v[178:181], v[210:213], v[42:45]
	v_mfma_f32_16x16x32_bf16 v[46:49], v[186:189], v[210:213], v[46:49]
	v_mfma_f32_16x16x32_bf16 v[50:53], v[178:181], v[218:221], v[50:53]
	v_mfma_f32_16x16x32_bf16 v[54:57], v[186:189], v[218:221], v[54:57]
	s_setprio 0
	s_barrier
	s_add_i32 s81, s81, s3
	s_add_i32 s76, s81, 0x2000
	v_lshl_add_u64 v[58:59], v[0:1], 0, s[22:23]
	s_mov_b32 m0, s81
	s_add_u32 s82, s42, 0x18180
	ds_read_b128 v[190:193], v163 offset:49152
	ds_read_b128 v[194:197], v163 offset:50176
	ds_read_b128 v[198:201], v163 offset:51200
	ds_read_b128 v[202:205], v163 offset:52224
	ds_read_b128 v[206:209], v163 offset:53248
	ds_read_b128 v[210:213], v163 offset:54272
	ds_read_b128 v[214:217], v163 offset:55296
	ds_read_b128 v[218:221], v163 offset:56320
	global_load_lds_dwordx4 v[58:59], off
	v_lshl_add_u64 v[58:59], v[2:3], 0, s[22:23]
	s_mov_b32 m0, s76
	s_addc_u32 s83, s43, 0
	s_add_i32 s77, s79, s3
	global_load_lds_dwordx4 v[58:59], off
	v_lshl_add_u64 v[58:59], s[82:83], 0, v[148:149]
	s_mov_b32 m0, s77
	s_add_i32 s79, s77, 0x2000
	global_load_lds_dwordx4 v[58:59], off
	v_lshl_add_u64 v[58:59], s[82:83], 0, v[144:145]
	s_mov_b32 m0, s79
	s_nop 0
	global_load_lds_dwordx4 v[58:59], off
	v_lshl_add_u64 v[58:59], v[4:5], 0, s[22:23]
	s_mov_b32 m0, s53
	s_nop 0
	global_load_lds_dwordx4 v[58:59], off
	v_lshl_add_u64 v[58:59], v[6:7], 0, s[22:23]
	s_mov_b32 m0, s54
	s_nop 0
	global_load_lds_dwordx4 v[58:59], off
	s_waitcnt vmcnt(8)
	s_waitcnt lgkmcnt(0)
	s_barrier
; #define PG8_STAGE(bufoff, gbase, voff) do { _Pragma("unroll") for (int _i = 0; _i < 2; ++_i) \
;         __builtin_amdgcn_global_load_lds((const unsigned*)((const char*)(gbase) + (voff)[_i]), (PG8_LAS unsigned*)(lds + (bufoff) + ldsw + _i * 8192), 16, 0, 0); } while (0)
; #define PG8_LDA(dst, b, h) do { _Pragma("unroll") for (int m = 0; m < 4; ++m) _Pragma("unroll") for (int k = 0; k < 2; ++k) dst[m][k] = *(const PG8_LAS bf16x8*)(lds + PG8_SA(b, h) + aoff + m * 2048 + k * 1024); } while (0)
; #define PG8_LDB(dst, b, h) do { _Pragma("unroll") for (int n = 0; n < 2; ++n) _Pragma("unroll") for (int k = 0; k < 2; ++k) dst[n][k] = *(const PG8_LAS bf16x8*)(lds + PG8_SB(b, h) + boff + n * 2048 + k * 1024); } while (0)
; #define PG8_MMA(ai, bj, At, Bt) do { __builtin_amdgcn_s_setprio(1); _Pragma("unroll") for (int m = 0; m < 4; ++m) _Pragma("unroll") for (int n = 0; n < 2; ++n) _Pragma("unroll") for (int k = 0; k < 2; ++k) \
;         acc[ai][bj][m][n] = __builtin_amdgcn_mfma_f32_16x16x32_bf16(Bt[n][k], At[m][k], acc[ai][bj][m][n], 0, 0, 0); __builtin_amdgcn_s_setprio(0); } while (0)
; #define PG8_BAR __builtin_amdgcn_s_barrier()
; template <class Epi, class Sched, bool ALIGN_EPI = false, bool SP2 = false>
; __device__ __forceinline__ void gemm_phase(PG8_LAS unsigned char* lds, const Gemm g, const Sched& S, const Epi& E, const int wid) {
;     ...
;             PG8_LDB(B0, 0, 0); PG8_LDB(B1, 0, 1); PG8_SCHED; PG8_LDA(At, 0, 0); PG8_STAGE(PG8_SA(1, 1), a1 + hsA, voffA);
;             PG8_WAIT_V(8); PG8_WAIT_L(0); PG8_BAR; PG8_MMA(0, 0, At, B0); PG8_MMA(0, 1, At, B1); PG8_BAR; PG8_SCHED;
;             PG8_LDA(At, 0, 1); PG8_STAGE(PG8_SB(0, 0), b2, voffB); PG8_STAGE(PG8_SB(0, 1), b2 + hsB, voffB); PG8_STAGE(PG8_SA(0, 0), a2, voffA);
;             PG8_WAIT_V(8); PG8_WAIT_L(0); PG8_BAR; PG8_MMA(1, 0, At, B0); PG8_MMA(1, 1, At, B1); PG8_BAR; PG8_SCHED;
;             PG8_LDB(B0, 1, 0); PG8_LDB(B1, 1, 1); PG8_SCHED; PG8_LDA(At, 1, 0); PG8_STAGE(PG8_SA(0, 1), a2 + hsA, voffA);
;             PG8_WAIT_V(8); PG8_WAIT_L(0); PG8_BAR; PG8_MMA(0, 0, At, B0); PG8_MMA(0, 1, At, B1); PG8_BAR; PG8_SCHED;
;             PG8_LDA(At, 1, 1); PG8_STAGE(PG8_SB(1, 0), b3, voffB); PG8_STAGE(PG8_SB(1, 1), b3 + hsB, voffB); PG8_STAGE(PG8_SA(1, 0), a3, voffA);
;             PG8_WAIT_V(8); PG8_WAIT_L(0); PG8_BAR; PG8_MMA(1, 0, At, B0); PG8_MMA(1, 1, At, B1); PG8_BAR; PG8_SCHED;
	s_setprio 1
	s_waitcnt lgkmcnt(0)
	v_mfma_f32_16x16x32_bf16 v[136:139], v[30:33], v[190:193], v[136:139]
	v_mfma_f32_16x16x32_bf16 v[10:13], v[30:33], v[214:217], v[10:13]
	v_mfma_f32_16x16x32_bf16 v[14:17], v[124:127], v[214:217], v[14:17]
	v_mfma_f32_16x16x32_bf16 v[136:139], v[34:37], v[194:197], v[136:139]
	v_mfma_f32_16x16x32_bf16 v[140:143], v[124:127], v[190:193], v[140:143]
	v_mfma_f32_16x16x32_bf16 v[158:161], v[30:33], v[198:201], v[158:161]
	v_mfma_f32_16x16x32_bf16 v[166:169], v[124:127], v[198:201], v[166:169]
	v_mfma_f32_16x16x32_bf16 v[170:173], v[30:33], v[206:209], v[170:173]
	v_mfma_f32_16x16x32_bf16 v[174:177], v[124:127], v[206:209], v[174:177]
	v_mfma_f32_16x16x32_bf16 v[10:13], v[34:37], v[218:221], v[10:13]
	v_mfma_f32_16x16x32_bf16 v[14:17], v[128:131], v[218:221], v[14:17]
	v_mfma_f32_16x16x32_bf16 v[140:143], v[128:131], v[194:197], v[140:143]
	v_mfma_f32_16x16x32_bf16 v[158:161], v[34:37], v[202:205], v[158:161]
	v_mfma_f32_16x16x32_bf16 v[166:169], v[128:131], v[202:205], v[166:169]
	v_mfma_f32_16x16x32_bf16 v[170:173], v[34:37], v[210:213], v[170:173]
	v_mfma_f32_16x16x32_bf16 v[174:177], v[128:131], v[210:213], v[174:177]
	s_setprio 0
	s_setprio 1
	v_mfma_f32_16x16x32_bf16 v[30:33], v[182:185], v[190:193], v[60:63]
	v_mfma_f32_16x16x32_bf16 v[34:37], v[132:135], v[198:201], v[108:111]
	v_mfma_f32_16x16x32_bf16 v[58:61], v[182:185], v[198:201], v[112:115]
	v_mfma_f32_16x16x32_bf16 v[108:111], v[132:135], v[206:209], v[116:119]
	v_mfma_f32_16x16x32_bf16 v[112:115], v[182:185], v[206:209], v[120:123]
	v_mfma_f32_16x16x32_bf16 v[22:25], v[132:135], v[214:217], v[22:25]
	v_mfma_f32_16x16x32_bf16 v[26:29], v[182:185], v[214:217], v[26:29]
	v_mfma_f32_16x16x32_bf16 v[18:21], v[132:135], v[190:193], v[18:21]
	v_mfma_f32_16x16x32_bf16 v[30:33], v[186:189], v[194:197], v[30:33]
	v_mfma_f32_16x16x32_bf16 v[34:37], v[178:181], v[202:205], v[34:37]
	v_mfma_f32_16x16x32_bf16 v[58:61], v[186:189], v[202:205], v[58:61]
	v_mfma_f32_16x16x32_bf16 v[108:111], v[178:181], v[210:213], v[108:111]
	v_mfma_f32_16x16x32_bf16 v[112:115], v[186:189], v[210:213], v[112:115]
	v_mfma_f32_16x16x32_bf16 v[22:25], v[178:181], v[218:221], v[22:25]
	v_mfma_f32_16x16x32_bf16 v[26:29], v[186:189], v[218:221], v[26:29]
	v_mfma_f32_16x16x32_bf16 v[18:21], v[178:181], v[194:197], v[18:21]
	s_setprio 0
	s_barrier
	ds_read_b128 v[116:119], v164
	ds_read_b128 v[120:123], v164 offset:1024
	ds_read_b128 v[124:127], v164 offset:2048
	ds_read_b128 v[128:131], v164 offset:3072
	ds_read_b128 v[132:135], v165
	ds_read_b128 v[178:181], v165 offset:1024
	ds_read_b128 v[182:185], v165 offset:2048
	ds_read_b128 v[186:189], v165 offset:3072
	s_add_u32 s82, s40, 0x600180
	s_addc_u32 s83, s41, 0
	s_mov_b32 m0, s78
	v_lshl_add_u64 v[62:63], s[82:83], 0, v[150:151]
	ds_read_b128 v[190:193], v163
	ds_read_b128 v[194:197], v163 offset:1024
	ds_read_b128 v[198:201], v163 offset:2048
	ds_read_b128 v[202:205], v163 offset:3072
	ds_read_b128 v[206:209], v163 offset:4096
	ds_read_b128 v[210:213], v163 offset:5120
	ds_read_b128 v[214:217], v163 offset:6144
	ds_read_b128 v[218:221], v163 offset:7168
	global_load_lds_dwordx4 v[62:63], off
	v_lshl_add_u64 v[62:63], s[82:83], 0, v[146:147]
	s_mov_b32 m0, s65
	s_nop 0
	global_load_lds_dwordx4 v[62:63], off
	s_waitcnt vmcnt(8)
	s_waitcnt lgkmcnt(0)
	s_barrier
	s_setprio 1
	s_waitcnt lgkmcnt(0)
	v_mfma_f32_16x16x32_bf16 v[62:65], v[116:119], v[190:193], v[64:67]
	v_mfma_f32_16x16x32_bf16 v[66:69], v[124:127], v[190:193], v[68:71]
	v_mfma_f32_16x16x32_bf16 v[70:73], v[116:119], v[198:201], v[72:75]
	v_mfma_f32_16x16x32_bf16 v[74:77], v[124:127], v[198:201], v[76:79]
	v_mfma_f32_16x16x32_bf16 v[78:81], v[116:119], v[206:209], v[80:83]
	v_mfma_f32_16x16x32_bf16 v[82:85], v[124:127], v[206:209], v[84:87]
	v_mfma_f32_16x16x32_bf16 v[86:89], v[116:119], v[214:217], v[88:91]
	v_mfma_f32_16x16x32_bf16 v[90:93], v[124:127], v[214:217], v[92:95]
	v_mfma_f32_16x16x32_bf16 v[62:65], v[120:123], v[194:197], v[62:65]
	v_mfma_f32_16x16x32_bf16 v[66:69], v[128:131], v[194:197], v[66:69]
	v_mfma_f32_16x16x32_bf16 v[70:73], v[120:123], v[202:205], v[70:73]
	v_mfma_f32_16x16x32_bf16 v[74:77], v[128:131], v[202:205], v[74:77]
	v_mfma_f32_16x16x32_bf16 v[78:81], v[120:123], v[210:213], v[78:81]
	v_mfma_f32_16x16x32_bf16 v[82:85], v[128:131], v[210:213], v[82:85]
	v_mfma_f32_16x16x32_bf16 v[86:89], v[120:123], v[218:221], v[86:89]
	v_mfma_f32_16x16x32_bf16 v[90:93], v[128:131], v[218:221], v[90:93]
	s_setprio 0
	s_setprio 1
	v_mfma_f32_16x16x32_bf16 v[94:97], v[132:135], v[190:193], v[96:99]
	v_mfma_f32_16x16x32_bf16 v[98:101], v[182:185], v[190:193], v[100:103]
	v_mfma_f32_16x16x32_bf16 v[102:105], v[132:135], v[198:201], v[104:107]
	v_mfma_f32_16x16x32_bf16 v[38:41], v[182:185], v[198:201], v[38:41]
	v_mfma_f32_16x16x32_bf16 v[42:45], v[132:135], v[206:209], v[42:45]
	v_mfma_f32_16x16x32_bf16 v[46:49], v[182:185], v[206:209], v[46:49]
	v_mfma_f32_16x16x32_bf16 v[50:53], v[132:135], v[214:217], v[50:53]
	v_mfma_f32_16x16x32_bf16 v[54:57], v[182:185], v[214:217], v[54:57]
	v_mfma_f32_16x16x32_bf16 v[94:97], v[178:181], v[194:197], v[94:97]
	v_mfma_f32_16x16x32_bf16 v[98:101], v[186:189], v[194:197], v[98:101]
	v_mfma_f32_16x16x32_bf16 v[102:105], v[178:181], v[202:205], v[102:105]
	v_mfma_f32_16x16x32_bf16 v[38:41], v[186:189], v[202:205], v[38:41]
	v_mfma_f32_16x16x32_bf16 v[42:45], v[178:181], v[210:213], v[42:45]
	v_mfma_f32_16x16x32_bf16 v[46:49], v[186:189], v[210:213], v[46:49]
	v_mfma_f32_16x16x32_bf16 v[50:53], v[178:181], v[218:221], v[50:53]
	v_mfma_f32_16x16x32_bf16 v[54:57], v[186:189], v[218:221], v[54:57]
	s_setprio 0
	s_barrier
; #define PG8_STAGE(bufoff, gbase, voff) do { _Pragma("unroll") for (int _i = 0; _i < 2; ++_i) \
;         __builtin_amdgcn_global_load_lds((const unsigned*)((const char*)(gbase) + (voff)[_i]), (PG8_LAS unsigned*)(lds + (bufoff) + ldsw + _i * 8192), 16, 0, 0); } while (0)
; #define PG8_LDA(dst, b, h) do { _Pragma("unroll") for (int m = 0; m < 4; ++m) _Pragma("unroll") for (int k = 0; k < 2; ++k) dst[m][k] = *(const PG8_LAS bf16x8*)(lds + PG8_SA(b, h) + aoff + m * 2048 + k * 1024); } while (0)
; #define PG8_LDB(dst, b, h) do { _Pragma("unroll") for (int n = 0; n < 2; ++n) _Pragma("unroll") for (int k = 0; k < 2; ++k) dst[n][k] = *(const PG8_LAS bf16x8*)(lds + PG8_SB(b, h) + boff + n * 2048 + k * 1024); } while (0)
; #define PG8_MMA(ai, bj, At, Bt) do { __builtin_amdgcn_s_setprio(1); _Pragma("unroll") for (int m = 0; m < 4; ++m) _Pragma("unroll") for (int n = 0; n < 2; ++n) _Pragma("unroll") for (int k = 0; k < 2; ++k) \
;         acc[ai][bj][m][n] = __builtin_amdgcn_mfma_f32_16x16x32_bf16(Bt[n][k], At[m][k], acc[ai][bj][m][n], 0, 0, 0); __builtin_amdgcn_s_setprio(0); } while (0)
; #define PG8_BAR __builtin_amdgcn_s_barrier()
; template <class Epi, class Sched, bool ALIGN_EPI = false, bool SP2 = false>
; __device__ __forceinline__ void gemm_phase(PG8_LAS unsigned char* lds, const Gemm g, const Sched& S, const Epi& E, const int wid) {
;     ...
;             PG8_LDB(B0, 0, 0); PG8_LDB(B1, 0, 1); PG8_SCHED; PG8_LDA(At, 0, 0); PG8_STAGE(PG8_SA(1, 1), a1 + hsA, voffA);
;             PG8_WAIT_V(8); PG8_WAIT_L(0); PG8_BAR; PG8_MMA(0, 0, At, B0); PG8_MMA(0, 1, At, B1); PG8_BAR; PG8_SCHED;
;             PG8_LDA(At, 0, 1); PG8_STAGE(PG8_SB(0, 0), b2, voffB); PG8_STAGE(PG8_SB(0, 1), b2 + hsB, voffB); PG8_STAGE(PG8_SA(0, 0), a2, voffA);
;             PG8_WAIT_V(8); PG8_WAIT_L(0); PG8_BAR; PG8_MMA(1, 0, At, B0); PG8_MMA(1, 1, At, B1); PG8_BAR; PG8_SCHED;
;             PG8_LDB(B0, 1, 0); PG8_LDB(B1, 1, 1); PG8_SCHED; PG8_LDA(At, 1, 0); PG8_STAGE(PG8_SA(0, 1), a2 + hsA, voffA);
;             PG8_WAIT_V(8); PG8_WAIT_L(0); PG8_BAR; PG8_MMA(0, 0, At, B0); PG8_MMA(0, 1, At, B1); PG8_BAR; PG8_SCHED;
;             PG8_LDA(At, 1, 1); PG8_STAGE(PG8_SB(1, 0), b3, voffB); PG8_STAGE(PG8_SB(1, 1), b3 + hsB, voffB); PG8_STAGE(PG8_SA(1, 0), a3, voffA);
;             PG8_WAIT_V(8); PG8_WAIT_L(0); PG8_BAR; PG8_MMA(1, 0, At, B0); PG8_MMA(1, 1, At, B1); PG8_BAR; PG8_SCHED;
	s_mov_b32 m0, s75
	v_lshl_add_u64 v[106:107], v[0:1], 0, s[24:25]
	s_add_u32 s82, s42, 0x18200
	ds_read_b128 v[190:193], v163 offset:16384
	ds_read_b128 v[194:197], v163 offset:17408
	ds_read_b128 v[198:201], v163 offset:18432
	ds_read_b128 v[202:205], v163 offset:19456
	ds_read_b128 v[206:209], v163 offset:20480
	ds_read_b128 v[210:213], v163 offset:21504
	ds_read_b128 v[214:217], v163 offset:22528
	ds_read_b128 v[218:221], v163 offset:23552
	global_load_lds_dwordx4 v[106:107], off
	v_lshl_add_u64 v[106:107], v[2:3], 0, s[24:25]
	s_mov_b32 m0, s66
	s_addc_u32 s83, s43, 0
	global_load_lds_dwordx4 v[106:107], off
	v_lshl_add_u64 v[106:107], s[82:83], 0, v[148:149]
	s_mov_b32 m0, s67
	s_nop 0
	global_load_lds_dwordx4 v[106:107], off
	v_lshl_add_u64 v[106:107], s[82:83], 0, v[144:145]
	s_mov_b32 m0, s74
	s_nop 0
	global_load_lds_dwordx4 v[106:107], off
	v_lshl_add_u64 v[106:107], v[4:5], 0, s[24:25]
	s_mov_b32 m0, s46
	s_nop 0
	global_load_lds_dwordx4 v[106:107], off
	v_lshl_add_u64 v[106:107], v[6:7], 0, s[24:25]
	s_mov_b32 m0, s47
	s_nop 0
	global_load_lds_dwordx4 v[106:107], off
	s_waitcnt vmcnt(8)
	s_waitcnt lgkmcnt(0)
	s_barrier
	s_setprio 1
	s_waitcnt lgkmcnt(0)
	v_mfma_f32_16x16x32_bf16 v[136:139], v[116:119], v[190:193], v[136:139]
	v_mfma_f32_16x16x32_bf16 v[10:13], v[116:119], v[214:217], v[10:13]
	v_mfma_f32_16x16x32_bf16 v[14:17], v[124:127], v[214:217], v[14:17]
	v_mfma_f32_16x16x32_bf16 v[136:139], v[120:123], v[194:197], v[136:139]
	v_mfma_f32_16x16x32_bf16 v[140:143], v[124:127], v[190:193], v[140:143]
	v_mfma_f32_16x16x32_bf16 v[158:161], v[116:119], v[198:201], v[158:161]
	v_mfma_f32_16x16x32_bf16 v[166:169], v[124:127], v[198:201], v[166:169]
	v_mfma_f32_16x16x32_bf16 v[170:173], v[116:119], v[206:209], v[170:173]
	v_mfma_f32_16x16x32_bf16 v[174:177], v[124:127], v[206:209], v[174:177]
	v_mfma_f32_16x16x32_bf16 v[10:13], v[120:123], v[218:221], v[10:13]
	v_mfma_f32_16x16x32_bf16 v[14:17], v[128:131], v[218:221], v[14:17]
	v_mfma_f32_16x16x32_bf16 v[140:143], v[128:131], v[194:197], v[140:143]
	v_mfma_f32_16x16x32_bf16 v[158:161], v[120:123], v[202:205], v[158:161]
	v_mfma_f32_16x16x32_bf16 v[166:169], v[128:131], v[202:205], v[166:169]
	v_mfma_f32_16x16x32_bf16 v[170:173], v[120:123], v[210:213], v[170:173]
	v_mfma_f32_16x16x32_bf16 v[174:177], v[128:131], v[210:213], v[174:177]
	s_setprio 0
	s_setprio 1
	v_mfma_f32_16x16x32_bf16 v[30:33], v[182:185], v[190:193], v[30:33]
	v_mfma_f32_16x16x32_bf16 v[34:37], v[132:135], v[198:201], v[34:37]
	v_mfma_f32_16x16x32_bf16 v[58:61], v[182:185], v[198:201], v[58:61]
	v_mfma_f32_16x16x32_bf16 v[106:109], v[132:135], v[206:209], v[108:111]
	v_mfma_f32_16x16x32_bf16 v[110:113], v[182:185], v[206:209], v[112:115]
	v_mfma_f32_16x16x32_bf16 v[22:25], v[132:135], v[214:217], v[22:25]
	v_mfma_f32_16x16x32_bf16 v[26:29], v[182:185], v[214:217], v[26:29]
	v_mfma_f32_16x16x32_bf16 v[18:21], v[132:135], v[190:193], v[18:21]
	v_mfma_f32_16x16x32_bf16 v[30:33], v[186:189], v[194:197], v[30:33]
	v_mfma_f32_16x16x32_bf16 v[34:37], v[178:181], v[202:205], v[34:37]
	v_mfma_f32_16x16x32_bf16 v[58:61], v[186:189], v[202:205], v[58:61]
	v_mfma_f32_16x16x32_bf16 v[106:109], v[178:181], v[210:213], v[106:109]
	v_mfma_f32_16x16x32_bf16 v[110:113], v[186:189], v[210:213], v[110:113]
	v_mfma_f32_16x16x32_bf16 v[22:25], v[178:181], v[218:221], v[22:25]
	v_mfma_f32_16x16x32_bf16 v[26:29], v[186:189], v[218:221], v[26:29]
	v_mfma_f32_16x16x32_bf16 v[18:21], v[178:181], v[194:197], v[18:21]
	s_setprio 0
	s_barrier
	ds_read_b128 v[114:117], v8
	ds_read_b128 v[118:121], v8 offset:1024
	ds_read_b128 v[122:125], v8 offset:2048
	ds_read_b128 v[126:129], v8 offset:3072
	ds_read_b128 v[130:133], v9
	ds_read_b128 v[178:181], v9 offset:1024
	ds_read_b128 v[182:185], v9 offset:2048
	ds_read_b128 v[186:189], v9 offset:3072
	s_add_u32 s82, s40, 0x600200
	s_addc_u32 s83, s41, 0
	s_mov_b32 m0, s48
	v_lshl_add_u64 v[134:135], s[82:83], 0, v[150:151]
	ds_read_b128 v[190:193], v163 offset:32768
	ds_read_b128 v[194:197], v163 offset:33792
	ds_read_b128 v[198:201], v163 offset:34816
	ds_read_b128 v[202:205], v163 offset:35840
	ds_read_b128 v[206:209], v163 offset:36864
	ds_read_b128 v[210:213], v163 offset:37888
	ds_read_b128 v[214:217], v163 offset:38912
	ds_read_b128 v[218:221], v163 offset:39936
	global_load_lds_dwordx4 v[134:135], off
	v_lshl_add_u64 v[134:135], s[82:83], 0, v[146:147]
	s_mov_b32 m0, s49
	s_nop 0
	global_load_lds_dwordx4 v[134:135], off
	s_waitcnt vmcnt(8)
	s_waitcnt lgkmcnt(0)
	s_barrier
; #define PG8_STAGE(bufoff, gbase, voff) do { _Pragma("unroll") for (int _i = 0; _i < 2; ++_i) \
;         __builtin_amdgcn_global_load_lds((const unsigned*)((const char*)(gbase) + (voff)[_i]), (PG8_LAS unsigned*)(lds + (bufoff) + ldsw + _i * 8192), 16, 0, 0); } while (0)
; #define PG8_LDA(dst, b, h) do { _Pragma("unroll") for (int m = 0; m < 4; ++m) _Pragma("unroll") for (int k = 0; k < 2; ++k) dst[m][k] = *(const PG8_LAS bf16x8*)(lds + PG8_SA(b, h) + aoff + m * 2048 + k * 1024); } while (0)
; #define PG8_LDB(dst, b, h) do { _Pragma("unroll") for (int n = 0; n < 2; ++n) _Pragma("unroll") for (int k = 0; k < 2; ++k) dst[n][k] = *(const PG8_LAS bf16x8*)(lds + PG8_SB(b, h) + boff + n * 2048 + k * 1024); } while (0)
; #define PG8_MMA(ai, bj, At, Bt) do { __builtin_amdgcn_s_setprio(1); _Pragma("unroll") for (int m = 0; m < 4; ++m) _Pragma("unroll") for (int n = 0; n < 2; ++n) _Pragma("unroll") for (int k = 0; k < 2; ++k) \
;         acc[ai][bj][m][n] = __builtin_amdgcn_mfma_f32_16x16x32_bf16(Bt[n][k], At[m][k], acc[ai][bj][m][n], 0, 0, 0); __builtin_amdgcn_s_setprio(0); } while (0)
; #define PG8_BAR __builtin_amdgcn_s_barrier()
; template <class Epi, class Sched, bool ALIGN_EPI = false, bool SP2 = false>
; __device__ __forceinline__ void gemm_phase(PG8_LAS unsigned char* lds, const Gemm g, const Sched& S, const Epi& E, const int wid) {
;     ...
;             PG8_LDB(B0, 0, 0); PG8_LDB(B1, 0, 1); PG8_SCHED; PG8_LDA(At, 0, 0); PG8_STAGE(PG8_SA(1, 1), a1 + hsA, voffA);
;             PG8_WAIT_V(8); PG8_WAIT_L(0); PG8_BAR; PG8_MMA(0, 0, At, B0); PG8_MMA(0, 1, At, B1); PG8_BAR; PG8_SCHED;
;             PG8_LDA(At, 0, 1); PG8_STAGE(PG8_SB(0, 0), b2, voffB); PG8_STAGE(PG8_SB(0, 1), b2 + hsB, voffB); PG8_STAGE(PG8_SA(0, 0), a2, voffA);
;             PG8_WAIT_V(8); PG8_WAIT_L(0); PG8_BAR; PG8_MMA(1, 0, At, B0); PG8_MMA(1, 1, At, B1); PG8_BAR; PG8_SCHED;
;             PG8_LDB(B0, 1, 0); PG8_LDB(B1, 1, 1); PG8_SCHED; PG8_LDA(At, 1, 0); PG8_STAGE(PG8_SA(0, 1), a2 + hsA, voffA);
;             PG8_WAIT_V(8); PG8_WAIT_L(0); PG8_BAR; PG8_MMA(0, 0, At, B0); PG8_MMA(0, 1, At, B1); PG8_BAR; PG8_SCHED;
;             PG8_LDA(At, 1, 1); PG8_STAGE(PG8_SB(1, 0), b3, voffB); PG8_STAGE(PG8_SB(1, 1), b3 + hsB, voffB); PG8_STAGE(PG8_SA(1, 0), a3, voffA);
;             PG8_WAIT_V(8); PG8_WAIT_L(0); PG8_BAR; PG8_MMA(1, 0, At, B0); PG8_MMA(1, 1, At, B1); PG8_BAR; PG8_SCHED;
	s_setprio 1
	s_waitcnt lgkmcnt(0)
	v_mfma_f32_16x16x32_bf16 v[62:65], v[114:117], v[190:193], v[62:65]
	v_mfma_f32_16x16x32_bf16 v[70:73], v[114:117], v[198:201], v[70:73]
	v_mfma_f32_16x16x32_bf16 v[78:81], v[114:117], v[206:209], v[78:81]
	v_mfma_f32_16x16x32_bf16 v[86:89], v[114:117], v[214:217], v[86:89]
	v_mfma_f32_16x16x32_bf16 v[90:93], v[122:125], v[214:217], v[90:93]
	v_mfma_f32_16x16x32_bf16 v[82:85], v[122:125], v[206:209], v[82:85]
	v_mfma_f32_16x16x32_bf16 v[74:77], v[122:125], v[198:201], v[74:77]
	v_mfma_f32_16x16x32_bf16 v[66:69], v[122:125], v[190:193], v[66:69]
	v_mfma_f32_16x16x32_bf16 v[62:65], v[118:121], v[194:197], v[62:65]
	v_mfma_f32_16x16x32_bf16 v[70:73], v[118:121], v[202:205], v[70:73]
	v_mfma_f32_16x16x32_bf16 v[78:81], v[118:121], v[210:213], v[78:81]
	v_mfma_f32_16x16x32_bf16 v[86:89], v[118:121], v[218:221], v[86:89]
	v_mfma_f32_16x16x32_bf16 v[90:93], v[126:129], v[218:221], v[90:93]
	v_mfma_f32_16x16x32_bf16 v[82:85], v[126:129], v[210:213], v[82:85]
	v_mfma_f32_16x16x32_bf16 v[74:77], v[126:129], v[202:205], v[74:77]
	v_mfma_f32_16x16x32_bf16 v[66:69], v[126:129], v[194:197], v[66:69]
	s_setprio 0
	s_setprio 1
	v_mfma_f32_16x16x32_bf16 v[94:97], v[130:133], v[190:193], v[94:97]
	v_mfma_f32_16x16x32_bf16 v[102:105], v[130:133], v[198:201], v[102:105]
	v_mfma_f32_16x16x32_bf16 v[42:45], v[130:133], v[206:209], v[42:45]
	v_mfma_f32_16x16x32_bf16 v[50:53], v[130:133], v[214:217], v[50:53]
	v_mfma_f32_16x16x32_bf16 v[54:57], v[182:185], v[214:217], v[54:57]
	v_mfma_f32_16x16x32_bf16 v[46:49], v[182:185], v[206:209], v[46:49]
	v_mfma_f32_16x16x32_bf16 v[38:41], v[182:185], v[198:201], v[38:41]
	v_mfma_f32_16x16x32_bf16 v[98:101], v[182:185], v[190:193], v[98:101]
	v_mfma_f32_16x16x32_bf16 v[94:97], v[178:181], v[194:197], v[94:97]
	v_mfma_f32_16x16x32_bf16 v[102:105], v[178:181], v[202:205], v[102:105]
	v_mfma_f32_16x16x32_bf16 v[42:45], v[178:181], v[210:213], v[42:45]
	v_mfma_f32_16x16x32_bf16 v[50:53], v[178:181], v[218:221], v[50:53]
	v_mfma_f32_16x16x32_bf16 v[54:57], v[186:189], v[218:221], v[54:57]
	v_mfma_f32_16x16x32_bf16 v[46:49], v[186:189], v[210:213], v[46:49]
	v_mfma_f32_16x16x32_bf16 v[38:41], v[186:189], v[202:205], v[38:41]
	v_mfma_f32_16x16x32_bf16 v[98:101], v[186:189], v[194:197], v[98:101]
	s_setprio 0
	s_barrier
	s_mov_b32 m0, s81
	v_lshl_add_u64 v[0:1], v[0:1], 0, s[26:27]
	s_add_u32 s42, s42, 0x18280
	ds_read_b128 v[190:193], v163 offset:49152
	ds_read_b128 v[194:197], v163 offset:50176
	ds_read_b128 v[198:201], v163 offset:51200
	ds_read_b128 v[202:205], v163 offset:52224
	ds_read_b128 v[206:209], v163 offset:53248
	ds_read_b128 v[210:213], v163 offset:54272
	ds_read_b128 v[214:217], v163 offset:55296
	ds_read_b128 v[218:221], v163 offset:56320
	global_load_lds_dwordx4 v[0:1], off
	v_lshl_add_u64 v[0:1], v[2:3], 0, s[26:27]
	s_mov_b32 m0, s76
	s_addc_u32 s43, s43, 0
	global_load_lds_dwordx4 v[0:1], off
	v_lshl_add_u64 v[0:1], s[42:43], 0, v[148:149]
	s_mov_b32 m0, s77
	s_nop 0
	global_load_lds_dwordx4 v[0:1], off
	v_lshl_add_u64 v[0:1], s[42:43], 0, v[144:145]
	s_mov_b32 m0, s79
	s_nop 0
	global_load_lds_dwordx4 v[0:1], off
	v_lshl_add_u64 v[0:1], v[4:5], 0, s[26:27]
	s_mov_b32 m0, s53
	s_nop 0
	global_load_lds_dwordx4 v[0:1], off
	v_lshl_add_u64 v[0:1], v[6:7], 0, s[26:27]
	s_mov_b32 m0, s54
	s_nop 0
	global_load_lds_dwordx4 v[0:1], off
	s_waitcnt vmcnt(8)
	s_waitcnt lgkmcnt(0)
	s_barrier
	s_setprio 1
	s_waitcnt lgkmcnt(0)
	v_mfma_f32_16x16x32_bf16 v[0:3], v[114:117], v[190:193], v[136:139]
	v_mfma_f32_16x16x32_bf16 v[4:7], v[122:125], v[190:193], v[140:143]
	v_mfma_f32_16x16x32_bf16 v[134:137], v[114:117], v[198:201], v[158:161]
	v_mfma_f32_16x16x32_bf16 v[138:141], v[122:125], v[198:201], v[166:169]
	v_mfma_f32_16x16x32_bf16 v[10:13], v[114:117], v[214:217], v[10:13]
	v_mfma_f32_16x16x32_bf16 v[14:17], v[122:125], v[214:217], v[14:17]
	v_mfma_f32_16x16x32_bf16 v[0:3], v[118:121], v[194:197], v[0:3]
	v_mfma_f32_16x16x32_bf16 v[4:7], v[126:129], v[194:197], v[4:7]
	v_mfma_f32_16x16x32_bf16 v[134:137], v[118:121], v[202:205], v[134:137]
	v_mfma_f32_16x16x32_bf16 v[138:141], v[126:129], v[202:205], v[138:141]
	v_mfma_f32_16x16x32_bf16 v[158:161], v[114:117], v[206:209], v[170:173]
	v_mfma_f32_16x16x32_bf16 v[166:169], v[122:125], v[206:209], v[174:177]
	v_mfma_f32_16x16x32_bf16 v[10:13], v[118:121], v[218:221], v[10:13]
	v_mfma_f32_16x16x32_bf16 v[14:17], v[126:129], v[218:221], v[14:17]
	v_mfma_f32_16x16x32_bf16 v[158:161], v[118:121], v[210:213], v[158:161]
	v_mfma_f32_16x16x32_bf16 v[166:169], v[126:129], v[210:213], v[166:169]
	s_setprio 0
	s_setprio 1
	v_mfma_f32_16x16x32_bf16 v[30:33], v[182:185], v[190:193], v[30:33]
	v_mfma_f32_16x16x32_bf16 v[34:37], v[130:133], v[198:201], v[34:37]
	v_mfma_f32_16x16x32_bf16 v[58:61], v[182:185], v[198:201], v[58:61]
	v_mfma_f32_16x16x32_bf16 v[106:109], v[130:133], v[206:209], v[106:109]
	v_mfma_f32_16x16x32_bf16 v[110:113], v[182:185], v[206:209], v[110:113]
	v_mfma_f32_16x16x32_bf16 v[22:25], v[130:133], v[214:217], v[22:25]
	v_mfma_f32_16x16x32_bf16 v[26:29], v[182:185], v[214:217], v[26:29]
	v_mfma_f32_16x16x32_bf16 v[18:21], v[130:133], v[190:193], v[18:21]
	v_mfma_f32_16x16x32_bf16 v[30:33], v[186:189], v[194:197], v[30:33]
	v_mfma_f32_16x16x32_bf16 v[34:37], v[178:181], v[202:205], v[34:37]
	v_mfma_f32_16x16x32_bf16 v[58:61], v[186:189], v[202:205], v[58:61]
	v_mfma_f32_16x16x32_bf16 v[106:109], v[178:181], v[210:213], v[106:109]
	v_mfma_f32_16x16x32_bf16 v[110:113], v[186:189], v[210:213], v[110:113]
	v_mfma_f32_16x16x32_bf16 v[22:25], v[178:181], v[218:221], v[22:25]
	v_mfma_f32_16x16x32_bf16 v[26:29], v[186:189], v[218:221], v[26:29]
	v_mfma_f32_16x16x32_bf16 v[18:21], v[178:181], v[194:197], v[18:21]
	s_setprio 0
	s_barrier
; #define PG8_STAGE(bufoff, gbase, voff) do { _Pragma("unroll") for (int _i = 0; _i < 2; ++_i) \
;         __builtin_amdgcn_global_load_lds((const unsigned*)((const char*)(gbase) + (voff)[_i]), (PG8_LAS unsigned*)(lds + (bufoff) + ldsw + _i * 8192), 16, 0, 0); } while (0)
; #define PG8_LDA(dst, b, h) do { _Pragma("unroll") for (int m = 0; m < 4; ++m) _Pragma("unroll") for (int k = 0; k < 2; ++k) dst[m][k] = *(const PG8_LAS bf16x8*)(lds + PG8_SA(b, h) + aoff + m * 2048 + k * 1024); } while (0)
; #define PG8_LDB(dst, b, h) do { _Pragma("unroll") for (int n = 0; n < 2; ++n) _Pragma("unroll") for (int k = 0; k < 2; ++k) dst[n][k] = *(const PG8_LAS bf16x8*)(lds + PG8_SB(b, h) + boff + n * 2048 + k * 1024); } while (0)
; #define PG8_MMA(ai, bj, At, Bt) do { __builtin_amdgcn_s_setprio(1); _Pragma("unroll") for (int m = 0; m < 4; ++m) _Pragma("unroll") for (int n = 0; n < 2; ++n) _Pragma("unroll") for (int k = 0; k < 2; ++k) \
;         acc[ai][bj][m][n] = __builtin_amdgcn_mfma_f32_16x16x32_bf16(Bt[n][k], At[m][k], acc[ai][bj][m][n], 0, 0, 0); __builtin_amdgcn_s_setprio(0); } while (0)
; #define PG8_BAR __builtin_amdgcn_s_barrier()
; template <class Epi, class Sched, bool ALIGN_EPI = false, bool SP2 = false>
; __device__ __forceinline__ void gemm_phase(PG8_LAS unsigned char* lds, const Gemm g, const Sched& S, const Epi& E, const int wid) {
;     ...
;             PG8_LDB(B0, 0, 0); PG8_LDB(B1, 0, 1); PG8_SCHED; PG8_LDA(At, 0, 0); PG8_STAGE(PG8_SA(1, 1), a1 + hsA, voffA);
;             PG8_WAIT_V(8); PG8_WAIT_L(0); PG8_BAR; PG8_MMA(0, 0, At, B0); PG8_MMA(0, 1, At, B1); PG8_BAR; PG8_SCHED;
;             PG8_LDA(At, 0, 1); PG8_STAGE(PG8_SB(0, 0), b2, voffB); PG8_STAGE(PG8_SB(0, 1), b2 + hsB, voffB); PG8_STAGE(PG8_SA(0, 0), a2, voffA);
;             PG8_WAIT_V(8); PG8_WAIT_L(0); PG8_BAR; PG8_MMA(1, 0, At, B0); PG8_MMA(1, 1, At, B1); PG8_BAR; PG8_SCHED;
;             PG8_LDB(B0, 1, 0); PG8_LDB(B1, 1, 1); PG8_SCHED; PG8_LDA(At, 1, 0); PG8_STAGE(PG8_SA(0, 1), a2 + hsA, voffA);
;             PG8_WAIT_V(8); PG8_WAIT_L(0); PG8_BAR; PG8_MMA(0, 0, At, B0); PG8_MMA(0, 1, At, B1); PG8_BAR; PG8_SCHED;
;             PG8_LDA(At, 1, 1); PG8_STAGE(PG8_SB(1, 0), b3, voffB); PG8_STAGE(PG8_SB(1, 1), b3 + hsB, voffB); PG8_STAGE(PG8_SA(1, 0), a3, voffA);
;             PG8_WAIT_V(8); PG8_WAIT_L(0); PG8_BAR; PG8_MMA(1, 0, At, B0); PG8_MMA(1, 1, At, B1); PG8_BAR; PG8_SCHED;
	ds_read_b128 v[114:117], v164
	ds_read_b128 v[118:121], v164 offset:1024
	ds_read_b128 v[122:125], v164 offset:2048
	ds_read_b128 v[126:129], v164 offset:3072
	ds_read_b128 v[130:133], v165
	ds_read_b128 v[170:173], v165 offset:1024
	ds_read_b128 v[174:177], v165 offset:2048
	ds_read_b128 v[178:181], v165 offset:3072
	s_add_u32 s40, s40, 0x600280
	s_addc_u32 s41, s41, 0
	s_mov_b32 m0, s78
	v_lshl_add_u64 v[142:143], s[40:41], 0, v[150:151]
	ds_read_b128 v[182:185], v163
	ds_read_b128 v[186:189], v163 offset:1024
	ds_read_b128 v[190:193], v163 offset:2048
	ds_read_b128 v[194:197], v163 offset:3072
	ds_read_b128 v[198:201], v163 offset:4096
	ds_read_b128 v[202:205], v163 offset:5120
	ds_read_b128 v[206:209], v163 offset:6144
	ds_read_b128 v[210:213], v163 offset:7168
	global_load_lds_dwordx4 v[142:143], off
	v_lshl_add_u64 v[142:143], s[40:41], 0, v[146:147]
	s_mov_b32 m0, s65
	s_nop 0
	global_load_lds_dwordx4 v[142:143], off
	s_waitcnt vmcnt(8)
	s_waitcnt lgkmcnt(0)
	s_barrier
	s_setprio 1
	s_waitcnt lgkmcnt(0)
	v_mfma_f32_16x16x32_bf16 v[62:65], v[114:117], v[182:185], v[62:65]
	v_mfma_f32_16x16x32_bf16 v[70:73], v[114:117], v[190:193], v[70:73]
	v_mfma_f32_16x16x32_bf16 v[78:81], v[114:117], v[198:201], v[78:81]
	v_mfma_f32_16x16x32_bf16 v[86:89], v[114:117], v[206:209], v[86:89]
	v_mfma_f32_16x16x32_bf16 v[90:93], v[122:125], v[206:209], v[90:93]
	v_mfma_f32_16x16x32_bf16 v[82:85], v[122:125], v[198:201], v[82:85]
	v_mfma_f32_16x16x32_bf16 v[74:77], v[122:125], v[190:193], v[74:77]
	v_mfma_f32_16x16x32_bf16 v[66:69], v[122:125], v[182:185], v[66:69]
	v_mfma_f32_16x16x32_bf16 v[62:65], v[118:121], v[186:189], v[62:65]
	v_mfma_f32_16x16x32_bf16 v[70:73], v[118:121], v[194:197], v[70:73]
	v_mfma_f32_16x16x32_bf16 v[78:81], v[118:121], v[202:205], v[78:81]
	v_mfma_f32_16x16x32_bf16 v[86:89], v[118:121], v[210:213], v[86:89]
	v_mfma_f32_16x16x32_bf16 v[90:93], v[126:129], v[210:213], v[90:93]
	v_mfma_f32_16x16x32_bf16 v[82:85], v[126:129], v[202:205], v[82:85]
	v_mfma_f32_16x16x32_bf16 v[74:77], v[126:129], v[194:197], v[74:77]
	v_mfma_f32_16x16x32_bf16 v[66:69], v[126:129], v[186:189], v[66:69]
	s_setprio 0
	s_setprio 1
	v_mfma_f32_16x16x32_bf16 v[94:97], v[130:133], v[182:185], v[94:97]
	v_mfma_f32_16x16x32_bf16 v[214:217], v[170:173], v[186:189], v[94:97]
	v_mfma_f32_16x16x32_bf16 v[94:97], v[174:177], v[182:185], v[98:101]
	v_mfma_f32_16x16x32_bf16 v[38:41], v[174:177], v[190:193], v[38:41]
	v_mfma_f32_16x16x32_bf16 v[42:45], v[130:133], v[198:201], v[42:45]
	v_mfma_f32_16x16x32_bf16 v[46:49], v[174:177], v[198:201], v[46:49]
	v_mfma_f32_16x16x32_bf16 v[50:53], v[130:133], v[206:209], v[50:53]
	v_mfma_f32_16x16x32_bf16 v[54:57], v[174:177], v[206:209], v[54:57]
	v_mfma_f32_16x16x32_bf16 v[182:185], v[178:181], v[186:189], v[94:97]
	v_mfma_f32_16x16x32_bf16 v[94:97], v[130:133], v[190:193], v[102:105]
	v_mfma_f32_16x16x32_bf16 v[38:41], v[178:181], v[194:197], v[38:41]
	v_mfma_f32_16x16x32_bf16 v[42:45], v[170:173], v[202:205], v[42:45]
	v_mfma_f32_16x16x32_bf16 v[46:49], v[178:181], v[202:205], v[46:49]
	v_mfma_f32_16x16x32_bf16 v[50:53], v[170:173], v[210:213], v[50:53]
	v_mfma_f32_16x16x32_bf16 v[54:57], v[178:181], v[210:213], v[54:57]
	v_mfma_f32_16x16x32_bf16 v[186:189], v[170:173], v[194:197], v[94:97]
	s_setprio 0
	s_barrier
	s_mov_b32 m0, s75
	v_lshl_add_u64 v[250:251], s[38:39], 0, v[148:149]
	s_add_u32 s40, s38, 0x18000
	ds_read_b128 v[94:97], v163 offset:16384
	ds_read_b128 v[98:101], v163 offset:17408
	ds_read_b128 v[102:105], v163 offset:18432
	ds_read_b128 v[190:193], v163 offset:19456
	ds_read_b128 v[194:197], v163 offset:20480
	ds_read_b128 v[198:201], v163 offset:21504
	ds_read_b128 v[202:205], v163 offset:22528
	ds_read_b128 v[206:209], v163 offset:23552
	global_load_lds_dwordx4 v[250:251], off
	v_lshl_add_u64 v[252:253], s[38:39], 0, v[144:145]
	s_mov_b32 m0, s66
	s_addc_u32 s41, s39, 0
	global_load_lds_dwordx4 v[252:253], off
	v_lshl_add_u64 v[142:143], s[40:41], 0, v[148:149]
	s_mov_b32 m0, s67
	v_lshl_add_u64 v[154:155], s[4:5], 0, v[150:151]
	global_load_lds_dwordx4 v[142:143], off
	v_lshl_add_u64 v[142:143], s[40:41], 0, v[144:145]
	s_mov_b32 m0, s74
	v_lshl_add_u64 v[156:157], s[4:5], 0, v[146:147]
	global_load_lds_dwordx4 v[142:143], off
	s_mov_b32 m0, s46
	s_nop 0
	global_load_lds_dwordx4 v[154:155], off
	s_mov_b32 m0, s47
	s_nop 0
	global_load_lds_dwordx4 v[156:157], off
	s_waitcnt vmcnt(8)
	s_waitcnt lgkmcnt(0)
	s_barrier
	s_setprio 1
	s_waitcnt lgkmcnt(0)
	v_mfma_f32_16x16x32_bf16 v[134:137], v[114:117], v[102:105], v[134:137]
	v_mfma_f32_16x16x32_bf16 v[210:213], v[118:121], v[190:193], v[134:137]
	v_mfma_f32_16x16x32_bf16 v[134:137], v[122:125], v[102:105], v[138:141]
	v_mfma_f32_16x16x32_bf16 v[0:3], v[114:117], v[94:97], v[0:3]
	v_mfma_f32_16x16x32_bf16 v[4:7], v[122:125], v[94:97], v[4:7]
	v_mfma_f32_16x16x32_bf16 v[140:143], v[126:129], v[190:193], v[134:137]
	v_mfma_f32_16x16x32_bf16 v[134:137], v[114:117], v[194:197], v[158:161]
	v_mfma_f32_16x16x32_bf16 v[10:13], v[114:117], v[202:205], v[10:13]
	v_mfma_f32_16x16x32_bf16 v[14:17], v[122:125], v[202:205], v[14:17]
	v_mfma_f32_16x16x32_bf16 v[0:3], v[118:121], v[98:101], v[0:3]
	v_mfma_f32_16x16x32_bf16 v[4:7], v[126:129], v[98:101], v[4:7]
	v_mfma_f32_16x16x32_bf16 v[158:161], v[118:121], v[198:201], v[134:137]
	v_mfma_f32_16x16x32_bf16 v[134:137], v[122:125], v[194:197], v[166:169]
	v_mfma_f32_16x16x32_bf16 v[10:13], v[118:121], v[206:209], v[10:13]
	v_mfma_f32_16x16x32_bf16 v[14:17], v[126:129], v[206:209], v[14:17]
	v_mfma_f32_16x16x32_bf16 v[166:169], v[126:129], v[198:201], v[134:137]
	s_setprio 0
	s_setprio 1
	v_mfma_f32_16x16x32_bf16 v[30:33], v[174:177], v[94:97], v[30:33]
	v_mfma_f32_16x16x32_bf16 v[120:123], v[178:181], v[98:101], v[30:33]
	v_mfma_f32_16x16x32_bf16 v[30:33], v[130:133], v[102:105], v[34:37]
	v_mfma_f32_16x16x32_bf16 v[218:221], v[170:173], v[190:193], v[30:33]
	v_mfma_f32_16x16x32_bf16 v[30:33], v[174:177], v[102:105], v[58:61]
	v_mfma_f32_16x16x32_bf16 v[18:21], v[130:133], v[94:97], v[18:21]
	v_mfma_f32_16x16x32_bf16 v[190:193], v[178:181], v[190:193], v[30:33]
	v_mfma_f32_16x16x32_bf16 v[30:33], v[130:133], v[194:197], v[106:109]
	v_mfma_f32_16x16x32_bf16 v[22:25], v[130:133], v[202:205], v[22:25]
	v_mfma_f32_16x16x32_bf16 v[18:21], v[170:173], v[98:101], v[18:21]
	v_mfma_f32_16x16x32_bf16 v[222:225], v[170:173], v[198:201], v[30:33]
	v_mfma_f32_16x16x32_bf16 v[30:33], v[174:177], v[194:197], v[110:113]
	v_mfma_f32_16x16x32_bf16 v[170:173], v[170:173], v[206:209], v[22:25]
	v_mfma_f32_16x16x32_bf16 v[22:25], v[174:177], v[202:205], v[26:29]
	v_mfma_f32_16x16x32_bf16 v[194:197], v[178:181], v[198:201], v[30:33]
	v_mfma_f32_16x16x32_bf16 v[174:177], v[178:181], v[206:209], v[22:25]
	s_setprio 0
	s_barrier
; #define PG8_STAGE(bufoff, gbase, voff) do { _Pragma("unroll") for (int _i = 0; _i < 2; ++_i) \
;         __builtin_amdgcn_global_load_lds((const unsigned*)((const char*)(gbase) + (voff)[_i]), (PG8_LAS unsigned*)(lds + (bufoff) + ldsw + _i * 8192), 16, 0, 0); } while (0)
; #define PG8_LDA(dst, b, h) do { _Pragma("unroll") for (int m = 0; m < 4; ++m) _Pragma("unroll") for (int k = 0; k < 2; ++k) dst[m][k] = *(const PG8_LAS bf16x8*)(lds + PG8_SA(b, h) + aoff + m * 2048 + k * 1024); } while (0)
; #define PG8_LDB(dst, b, h) do { _Pragma("unroll") for (int n = 0; n < 2; ++n) _Pragma("unroll") for (int k = 0; k < 2; ++k) dst[n][k] = *(const PG8_LAS bf16x8*)(lds + PG8_SB(b, h) + boff + n * 2048 + k * 1024); } while (0)
; #define PG8_MMA(ai, bj, At, Bt) do { __builtin_amdgcn_s_setprio(1); _Pragma("unroll") for (int m = 0; m < 4; ++m) _Pragma("unroll") for (int n = 0; n < 2; ++n) _Pragma("unroll") for (int k = 0; k < 2; ++k) \
;         acc[ai][bj][m][n] = __builtin_amdgcn_mfma_f32_16x16x32_bf16(Bt[n][k], At[m][k], acc[ai][bj][m][n], 0, 0, 0); __builtin_amdgcn_s_setprio(0); } while (0)
; #define PG8_WAIT_V(n) asm volatile("s_waitcnt vmcnt(" #n ")" ::: "memory")
; #define PG8_WAIT_L(n) asm volatile("s_waitcnt lgkmcnt(" #n ")" ::: "memory")
; template <class Epi, class Sched, bool ALIGN_EPI = false, bool SP2 = false>
; __device__ __forceinline__ void gemm_phase(PG8_LAS unsigned char* lds, const Gemm g, const Sched& S, const Epi& E, const int wid) {
;     ...
;             PG8_LDA(At, 0, 1); PG8_STAGE(PG8_SB(0, 0), b2, voffB); PG8_STAGE(PG8_SB(0, 1), b2 + hsB, voffB); PG8_STAGE(PG8_SA(0, 0), a2, voffA);
;             PG8_WAIT_V(8); PG8_WAIT_L(0); PG8_BAR; PG8_MMA(1, 0, At, B0); PG8_MMA(1, 1, At, B1); PG8_BAR; PG8_SCHED;
;             PG8_LDB(B0, 1, 0); PG8_LDB(B1, 1, 1); PG8_SCHED; PG8_LDA(At, 1, 0); PG8_STAGE(PG8_SA(0, 1), a2 + hsA, voffA);
;             PG8_WAIT_V(8); PG8_WAIT_L(0); PG8_BAR; PG8_MMA(0, 0, At, B0); PG8_MMA(0, 1, At, B1); PG8_BAR; PG8_SCHED;
;             PG8_LDA(At, 1, 1); PG8_STAGE(PG8_SB(1, 0), b3, voffB); PG8_STAGE(PG8_SB(1, 1), b3 + hsB, voffB); PG8_STAGE(PG8_SA(1, 0), a3, voffA);
;             PG8_WAIT_V(8); PG8_WAIT_L(0); PG8_BAR; PG8_MMA(1, 0, At, B0); PG8_MMA(1, 1, At, B1); PG8_BAR; PG8_SCHED;
;     ...
;         if constexpr (ALIGN_EPI) { if (wr == 0) PG8_BAR; }
;         E(acc, cur, wr, wc, fr, fq);
;         if (!has_next) break;
	s_nop 3
	ds_read_b128 v[22:25], v8
	ds_read_b128 v[26:29], v8 offset:1024
	ds_read_b128 v[58:61], v8 offset:2048
	ds_read_b128 v[178:181], v8 offset:3072
	ds_read_b128 v[198:201], v9
	ds_read_b128 v[202:205], v9 offset:1024
	ds_read_b128 v[206:209], v9 offset:2048
	ds_read_b128 v[226:229], v9 offset:3072
	s_add_u32 s40, s4, 0x600000
	s_addc_u32 s41, s5, 0
	s_mov_b32 m0, s48
	v_lshl_add_u64 v[8:9], s[40:41], 0, v[150:151]
	ds_read_b128 v[30:33], v163 offset:32768
	ds_read_b128 v[34:37], v163 offset:33792
	ds_read_b128 v[108:111], v163 offset:34816
	ds_read_b128 v[230:233], v163 offset:35840
	ds_read_b128 v[234:237], v163 offset:36864
	ds_read_b128 v[238:241], v163 offset:37888
	ds_read_b128 v[242:245], v163 offset:38912
	ds_read_b128 v[246:249], v163 offset:39936
	global_load_lds_dwordx4 v[8:9], off
	v_lshl_add_u64 v[8:9], s[40:41], 0, v[146:147]
	s_mov_b32 m0, s49
	s_nop 0
	global_load_lds_dwordx4 v[8:9], off
	s_waitcnt vmcnt(8)
	s_waitcnt lgkmcnt(0)
	s_barrier
	s_setprio 1
	s_waitcnt lgkmcnt(0)
	v_mfma_f32_16x16x32_bf16 v[62:65], v[22:25], v[30:33], v[62:65]
	v_mfma_f32_16x16x32_bf16 v[132:135], v[26:29], v[34:37], v[62:65]
	v_mfma_f32_16x16x32_bf16 v[62:65], v[58:61], v[30:33], v[66:69]
	v_mfma_f32_16x16x32_bf16 v[136:139], v[178:181], v[34:37], v[62:65]
	v_mfma_f32_16x16x32_bf16 v[62:65], v[22:25], v[108:111], v[70:73]
	v_mfma_f32_16x16x32_bf16 v[112:115], v[26:29], v[230:233], v[62:65]
	v_mfma_f32_16x16x32_bf16 v[62:65], v[58:61], v[108:111], v[74:77]
	v_mfma_f32_16x16x32_bf16 v[116:119], v[178:181], v[230:233], v[62:65]
	v_mfma_f32_16x16x32_bf16 v[62:65], v[22:25], v[234:237], v[78:81]
	v_mfma_f32_16x16x32_bf16 v[96:99], v[26:29], v[238:241], v[62:65]
	v_mfma_f32_16x16x32_bf16 v[62:65], v[58:61], v[234:237], v[82:85]
	v_mfma_f32_16x16x32_bf16 v[100:103], v[178:181], v[238:241], v[62:65]
	v_mfma_f32_16x16x32_bf16 v[62:65], v[22:25], v[242:245], v[86:89]
	v_mfma_f32_16x16x32_bf16 v[80:83], v[26:29], v[246:249], v[62:65]
	v_mfma_f32_16x16x32_bf16 v[62:65], v[58:61], v[242:245], v[90:93]
	v_mfma_f32_16x16x32_bf16 v[84:87], v[178:181], v[246:249], v[62:65]
	s_setprio 0
	s_setprio 1
	v_mfma_f32_16x16x32_bf16 v[62:65], v[198:201], v[30:33], v[214:217]
	v_mfma_f32_16x16x32_bf16 v[30:33], v[206:209], v[30:33], v[182:185]
	v_mfma_f32_16x16x32_bf16 v[128:131], v[226:229], v[34:37], v[30:33]
	v_mfma_f32_16x16x32_bf16 v[30:33], v[198:201], v[108:111], v[186:189]
	v_mfma_f32_16x16x32_bf16 v[104:107], v[202:205], v[230:233], v[30:33]
	v_mfma_f32_16x16x32_bf16 v[30:33], v[206:209], v[108:111], v[38:41]
	v_mfma_f32_16x16x32_bf16 v[108:111], v[226:229], v[230:233], v[30:33]
	v_mfma_f32_16x16x32_bf16 v[30:33], v[198:201], v[234:237], v[42:45]
	v_mfma_f32_16x16x32_bf16 v[88:91], v[202:205], v[238:241], v[30:33]
	v_mfma_f32_16x16x32_bf16 v[30:33], v[206:209], v[234:237], v[46:49]
	v_mfma_f32_16x16x32_bf16 v[92:95], v[226:229], v[238:241], v[30:33]
	v_mfma_f32_16x16x32_bf16 v[30:33], v[198:201], v[242:245], v[50:53]
	v_mfma_f32_16x16x32_bf16 v[72:75], v[202:205], v[246:249], v[30:33]
	v_mfma_f32_16x16x32_bf16 v[30:33], v[206:209], v[242:245], v[54:57]
	v_mfma_f32_16x16x32_bf16 v[124:127], v[202:205], v[34:37], v[62:65]
	v_mfma_f32_16x16x32_bf16 v[76:79], v[226:229], v[246:249], v[30:33]
	s_setprio 0
	s_barrier
	s_mov_b32 m0, s81
	v_lshl_add_u64 v[8:9], v[250:251], 0, s[14:15]
	s_add_u32 s40, s38, 0x18080
	ds_read_b128 v[40:43], v163 offset:49152
	ds_read_b128 v[44:47], v163 offset:50176
	ds_read_b128 v[182:185], v163 offset:51200
	ds_read_b128 v[186:189], v163 offset:52224
	ds_read_b128 v[214:217], v163 offset:53248
	ds_read_b128 v[230:233], v163 offset:54272
	ds_read_b128 v[234:237], v163 offset:55296
	ds_read_b128 v[238:241], v163 offset:56320
	global_load_lds_dwordx4 v[8:9], off
	v_lshl_add_u64 v[8:9], v[252:253], 0, s[14:15]
	s_mov_b32 m0, s76
	s_addc_u32 s41, s39, 0
	global_load_lds_dwordx4 v[8:9], off
	v_lshl_add_u64 v[8:9], s[40:41], 0, v[148:149]
	s_mov_b32 m0, s77
	s_nop 0
	global_load_lds_dwordx4 v[8:9], off
	v_lshl_add_u64 v[8:9], s[40:41], 0, v[144:145]
	s_mov_b32 m0, s79
	s_nop 0
	global_load_lds_dwordx4 v[8:9], off
	v_lshl_add_u64 v[8:9], v[154:155], 0, s[14:15]
	s_mov_b32 m0, s53
	s_nop 0
	global_load_lds_dwordx4 v[8:9], off
	v_lshl_add_u64 v[8:9], v[156:157], 0, s[14:15]
	s_mov_b32 m0, s54
	s_nop 0
	global_load_lds_dwordx4 v[8:9], off
	s_waitcnt vmcnt(8)
	s_waitcnt lgkmcnt(0)
	s_barrier
	s_setprio 1
	s_waitcnt lgkmcnt(0)
	v_mfma_f32_16x16x32_bf16 v[0:3], v[22:25], v[40:43], v[0:3]
	v_mfma_f32_16x16x32_bf16 v[64:67], v[26:29], v[44:47], v[0:3]
	v_mfma_f32_16x16x32_bf16 v[0:3], v[58:61], v[40:43], v[4:7]
	v_mfma_f32_16x16x32_bf16 v[68:71], v[178:181], v[44:47], v[0:3]
	v_mfma_f32_16x16x32_bf16 v[0:3], v[22:25], v[182:185], v[210:213]
	v_mfma_f32_16x16x32_bf16 v[48:51], v[26:29], v[186:189], v[0:3]
	v_mfma_f32_16x16x32_bf16 v[0:3], v[58:61], v[182:185], v[140:143]
	v_mfma_f32_16x16x32_bf16 v[52:55], v[178:181], v[186:189], v[0:3]
	v_mfma_f32_16x16x32_bf16 v[0:3], v[22:25], v[214:217], v[158:161]
	v_mfma_f32_16x16x32_bf16 v[32:35], v[26:29], v[230:233], v[0:3]
	v_mfma_f32_16x16x32_bf16 v[0:3], v[58:61], v[214:217], v[166:169]
	v_mfma_f32_16x16x32_bf16 v[36:39], v[178:181], v[230:233], v[0:3]
	v_mfma_f32_16x16x32_bf16 v[0:3], v[22:25], v[234:237], v[10:13]
	v_mfma_f32_16x16x32_bf16 v[8:11], v[26:29], v[238:241], v[0:3]
	v_mfma_f32_16x16x32_bf16 v[0:3], v[58:61], v[234:237], v[14:17]
	v_mfma_f32_16x16x32_bf16 v[12:15], v[178:181], v[238:241], v[0:3]
	s_setprio 0
	s_setprio 1
	v_mfma_f32_16x16x32_bf16 v[0:3], v[198:201], v[40:43], v[18:21]
	v_mfma_f32_16x16x32_bf16 v[56:59], v[202:205], v[44:47], v[0:3]
	v_mfma_f32_16x16x32_bf16 v[0:3], v[206:209], v[40:43], v[120:123]
	v_mfma_f32_16x16x32_bf16 v[60:63], v[226:229], v[44:47], v[0:3]
	v_mfma_f32_16x16x32_bf16 v[0:3], v[198:201], v[182:185], v[218:221]
	v_mfma_f32_16x16x32_bf16 v[40:43], v[202:205], v[186:189], v[0:3]
	v_mfma_f32_16x16x32_bf16 v[0:3], v[206:209], v[182:185], v[190:193]
	v_mfma_f32_16x16x32_bf16 v[44:47], v[226:229], v[186:189], v[0:3]
	v_mfma_f32_16x16x32_bf16 v[0:3], v[198:201], v[214:217], v[222:225]
	v_mfma_f32_16x16x32_bf16 v[24:27], v[202:205], v[230:233], v[0:3]
	v_mfma_f32_16x16x32_bf16 v[0:3], v[206:209], v[214:217], v[194:197]
	v_mfma_f32_16x16x32_bf16 v[28:31], v[226:229], v[230:233], v[0:3]
	v_mfma_f32_16x16x32_bf16 v[0:3], v[198:201], v[234:237], v[170:173]
	v_mfma_f32_16x16x32_bf16 v[4:7], v[206:209], v[234:237], v[174:177]
	v_mfma_f32_16x16x32_bf16 v[0:3], v[202:205], v[238:241], v[0:3]
	v_mfma_f32_16x16x32_bf16 v[4:7], v[226:229], v[238:241], v[4:7]
	s_setprio 0
	s_barrier
	s_andn2_b64 vcc, exec, s[16:17]
	s_cbranch_vccnz .LBB0_960
	s_barrier

; #define PG8_STAGE(bufoff, gbase, voff) do { _Pragma("unroll") for (int _i = 0; _i < 2; ++_i) \
;         __builtin_amdgcn_global_load_lds((const unsigned*)((const char*)(gbase) + (voff)[_i]), (PG8_LAS unsigned*)(lds + (bufoff) + ldsw + _i * 8192), 16, 0, 0); } while (0)
; #define PG8_LDA(dst, b, h) do { _Pragma("unroll") for (int m = 0; m < 4; ++m) _Pragma("unroll") for (int k = 0; k < 2; ++k) dst[m][k] = *(const PG8_LAS bf16x8*)(lds + PG8_SA(b, h) + aoff + m * 2048 + k * 1024); } while (0)
; #define PG8_LDB(dst, b, h) do { _Pragma("unroll") for (int n = 0; n < 2; ++n) _Pragma("unroll") for (int k = 0; k < 2; ++k) dst[n][k] = *(const PG8_LAS bf16x8*)(lds + PG8_SB(b, h) + boff + n * 2048 + k * 1024); } while (0)
; #define PG8_MMA(ai, bj, At, Bt) do { __builtin_amdgcn_s_setprio(1); _Pragma("unroll") for (int m = 0; m < 4; ++m) _Pragma("unroll") for (int n = 0; n < 2; ++n) _Pragma("unroll") for (int k = 0; k < 2; ++k) \
;         acc[ai][bj][m][n] = __builtin_amdgcn_mfma_f32_16x16x32_bf16(Bt[n][k], At[m][k], acc[ai][bj][m][n], 0, 0, 0); __builtin_amdgcn_s_setprio(0); } while (0)
; #define PG8_WAIT_V(n) asm volatile("s_waitcnt vmcnt(" #n ")" ::: "memory")
; #define PG8_WAIT_L(n) asm volatile("s_waitcnt lgkmcnt(" #n ")" ::: "memory")
; #define PG8_BAR __builtin_amdgcn_s_barrier()
; #define PG8_SCHED __builtin_amdgcn_sched_barrier(0)
; template <class Epi, class Sched, bool ALIGN_EPI = false, bool SP2 = false>
; __device__ __forceinline__ void gemm_phase(PG8_LAS unsigned char* lds, const Gemm g, const Sched& S, const Epi& E, const int wid) {
;     ...
;             PG8_LDB(B0, 0, 0); PG8_LDB(B1, 0, 1); PG8_SCHED; PG8_LDA(At, 0, 0); PG8_STAGE(PG8_SA(1, 1), a1 + hsA, voffA);
;             PG8_WAIT_V(8); PG8_WAIT_L(0); PG8_BAR; PG8_MMA(0, 0, At, B0); PG8_MMA(0, 1, At, B1); PG8_BAR; PG8_SCHED;
;             PG8_LDA(At, 0, 1); PG8_STAGE(PG8_SB(0, 0), b2, voffB); PG8_STAGE(PG8_SB(0, 1), b2 + hsB, voffB); PG8_STAGE(PG8_SA(0, 0), a2, voffA);
;             PG8_WAIT_V(8); PG8_WAIT_L(0); PG8_BAR; PG8_MMA(1, 0, At, B0); PG8_MMA(1, 1, At, B1); PG8_BAR; PG8_SCHED;
.LBB0_1177:
	ds_read_b128 v[128:131], v205
	ds_read_b128 v[132:135], v205 offset:1024
	ds_read_b128 v[136:139], v205 offset:2048
	ds_read_b128 v[140:143], v205 offset:3072
	ds_read_b128 v[144:147], v206
	ds_read_b128 v[148:151], v206 offset:1024
	ds_read_b128 v[152:155], v206 offset:2048
	ds_read_b128 v[156:159], v206 offset:3072
	s_add_u32 s40, s38, 0xfffc0080
	s_addc_u32 s41, s39, -1
	s_cmp_eq_u32 s64, 12
	s_cselect_b32 s43, s29, s41
	s_cselect_b32 s42, s60, s40
	s_cselect_b32 s41, s27, s63
	s_cselect_b32 s40, s61, s62
	v_lshl_add_u64 v[200:201], s[38:39], 0, v[170:171]
	s_add_i32 m0, s37, 0xc000
	ds_read_b128 v[176:179], v207
	ds_read_b128 v[180:183], v207 offset:1024
	ds_read_b128 v[184:187], v207 offset:2048
	ds_read_b128 v[188:191], v207 offset:3072
	ds_read_b128 v[192:195], v207 offset:4096
	ds_read_b128 v[196:199], v207 offset:5120
	ds_read_b128 v[208:211], v207 offset:6144
	ds_read_b128 v[212:215], v207 offset:7168
	global_load_lds_dwordx4 v[200:201], off
	v_lshl_add_u64 v[200:201], s[38:39], 0, v[168:169]
	s_add_i32 m0, s37, 0xe000
	s_nop 0
	global_load_lds_dwordx4 v[200:201], off
	s_waitcnt vmcnt(8)
	s_waitcnt lgkmcnt(0)
	s_barrier
	s_setprio 1
	s_waitcnt lgkmcnt(0)
	v_mfma_f32_16x16x32_bf16 v[124:127], v[128:131], v[176:179], v[124:127]
	v_mfma_f32_16x16x32_bf16 v[116:119], v[128:131], v[184:187], v[116:119]
	v_mfma_f32_16x16x32_bf16 v[108:111], v[128:131], v[192:195], v[108:111]
	v_mfma_f32_16x16x32_bf16 v[100:103], v[128:131], v[208:211], v[100:103]
	v_mfma_f32_16x16x32_bf16 v[96:99], v[136:139], v[208:211], v[96:99]
	v_mfma_f32_16x16x32_bf16 v[104:107], v[136:139], v[192:195], v[104:107]
	v_mfma_f32_16x16x32_bf16 v[112:115], v[136:139], v[184:187], v[112:115]
	v_mfma_f32_16x16x32_bf16 v[120:123], v[136:139], v[176:179], v[120:123]
	v_mfma_f32_16x16x32_bf16 v[124:127], v[132:135], v[180:183], v[124:127]
	v_mfma_f32_16x16x32_bf16 v[116:119], v[132:135], v[188:191], v[116:119]
	v_mfma_f32_16x16x32_bf16 v[108:111], v[132:135], v[196:199], v[108:111]
	v_mfma_f32_16x16x32_bf16 v[100:103], v[132:135], v[212:215], v[100:103]
	v_mfma_f32_16x16x32_bf16 v[96:99], v[140:143], v[212:215], v[96:99]
	v_mfma_f32_16x16x32_bf16 v[104:107], v[140:143], v[196:199], v[104:107]
	v_mfma_f32_16x16x32_bf16 v[112:115], v[140:143], v[188:191], v[112:115]
	v_mfma_f32_16x16x32_bf16 v[120:123], v[140:143], v[180:183], v[120:123]
	s_setprio 0
	s_setprio 1
	v_mfma_f32_16x16x32_bf16 v[60:63], v[144:147], v[176:179], v[60:63]
	v_mfma_f32_16x16x32_bf16 v[52:55], v[144:147], v[184:187], v[52:55]
	v_mfma_f32_16x16x32_bf16 v[44:47], v[144:147], v[192:195], v[44:47]
	v_mfma_f32_16x16x32_bf16 v[36:39], v[144:147], v[208:211], v[36:39]
	v_mfma_f32_16x16x32_bf16 v[32:35], v[152:155], v[208:211], v[32:35]
	v_mfma_f32_16x16x32_bf16 v[40:43], v[152:155], v[192:195], v[40:43]
	v_mfma_f32_16x16x32_bf16 v[48:51], v[152:155], v[184:187], v[48:51]
	v_mfma_f32_16x16x32_bf16 v[56:59], v[152:155], v[176:179], v[56:59]
	v_mfma_f32_16x16x32_bf16 v[60:63], v[148:151], v[180:183], v[60:63]
	v_mfma_f32_16x16x32_bf16 v[52:55], v[148:151], v[188:191], v[52:55]
	v_mfma_f32_16x16x32_bf16 v[44:47], v[148:151], v[196:199], v[44:47]
	v_mfma_f32_16x16x32_bf16 v[36:39], v[148:151], v[212:215], v[36:39]
	v_mfma_f32_16x16x32_bf16 v[32:35], v[156:159], v[212:215], v[32:35]
	v_mfma_f32_16x16x32_bf16 v[40:43], v[156:159], v[196:199], v[40:43]
	v_mfma_f32_16x16x32_bf16 v[48:51], v[156:159], v[188:191], v[48:51]
	v_mfma_f32_16x16x32_bf16 v[56:59], v[156:159], v[180:183], v[56:59]
	s_setprio 0
	s_barrier
	s_add_i32 s65, s54, s45
	v_lshl_add_u64 v[200:201], s[40:41], 0, v[162:163]
	s_mov_b32 m0, s65
	ds_read_b128 v[176:179], v207 offset:16384
	ds_read_b128 v[180:183], v207 offset:17408
	ds_read_b128 v[184:187], v207 offset:18432
	ds_read_b128 v[188:191], v207 offset:19456
	ds_read_b128 v[192:195], v207 offset:20480
	ds_read_b128 v[196:199], v207 offset:21504
	ds_read_b128 v[208:211], v207 offset:22528
	ds_read_b128 v[212:215], v207 offset:23552
	global_load_lds_dwordx4 v[200:201], off
	s_add_i32 m0, s65, 0x2000
	s_add_u32 s66, s40, 0x40000
	v_lshl_add_u64 v[216:217], s[40:41], 0, v[166:167]
	s_addc_u32 s67, s41, 0
	s_add_i32 s65, s55, s45
	global_load_lds_dwordx4 v[216:217], off
	v_lshl_add_u64 v[218:219], s[66:67], 0, v[162:163]
	s_mov_b32 m0, s65
	v_lshl_add_u64 v[220:221], s[42:43], 0, v[164:165]
	global_load_lds_dwordx4 v[218:219], off
	v_lshl_add_u64 v[218:219], s[66:67], 0, v[166:167]
	s_add_i32 m0, s65, 0x2000
	s_nop 0
	global_load_lds_dwordx4 v[218:219], off
	v_lshl_add_u64 v[218:219], s[42:43], 0, v[160:161]
	s_mov_b32 m0, s37
	s_nop 0
	global_load_lds_dwordx4 v[218:219], off
	s_mov_b32 m0, s46
	s_nop 0
	global_load_lds_dwordx4 v[220:221], off
	s_waitcnt vmcnt(8)
	s_waitcnt lgkmcnt(0)
	s_barrier
; #define PG8_STAGE(bufoff, gbase, voff) do { _Pragma("unroll") for (int _i = 0; _i < 2; ++_i) \
;         __builtin_amdgcn_global_load_lds((const unsigned*)((const char*)(gbase) + (voff)[_i]), (PG8_LAS unsigned*)(lds + (bufoff) + ldsw + _i * 8192), 16, 0, 0); } while (0)
; #define PG8_LDA(dst, b, h) do { _Pragma("unroll") for (int m = 0; m < 4; ++m) _Pragma("unroll") for (int k = 0; k < 2; ++k) dst[m][k] = *(const PG8_LAS bf16x8*)(lds + PG8_SA(b, h) + aoff + m * 2048 + k * 1024); } while (0)
; #define PG8_LDB(dst, b, h) do { _Pragma("unroll") for (int n = 0; n < 2; ++n) _Pragma("unroll") for (int k = 0; k < 2; ++k) dst[n][k] = *(const PG8_LAS bf16x8*)(lds + PG8_SB(b, h) + boff + n * 2048 + k * 1024); } while (0)
; #define PG8_MMA(ai, bj, At, Bt) do { __builtin_amdgcn_s_setprio(1); _Pragma("unroll") for (int m = 0; m < 4; ++m) _Pragma("unroll") for (int n = 0; n < 2; ++n) _Pragma("unroll") for (int k = 0; k < 2; ++k) \
;         acc[ai][bj][m][n] = __builtin_amdgcn_mfma_f32_16x16x32_bf16(Bt[n][k], At[m][k], acc[ai][bj][m][n], 0, 0, 0); __builtin_amdgcn_s_setprio(0); } while (0)
; #define PG8_WAIT_V(n) asm volatile("s_waitcnt vmcnt(" #n ")" ::: "memory")
; #define PG8_WAIT_L(n) asm volatile("s_waitcnt lgkmcnt(" #n ")" ::: "memory")
; #define PG8_BAR __builtin_amdgcn_s_barrier()
; #define PG8_SCHED __builtin_amdgcn_sched_barrier(0)
; template <class Epi, class Sched, bool ALIGN_EPI = false, bool SP2 = false>
; __device__ __forceinline__ void gemm_phase(PG8_LAS unsigned char* lds, const Gemm g, const Sched& S, const Epi& E, const int wid) {
;     ...
;             PG8_WAIT_V(8); PG8_WAIT_L(0); PG8_BAR; PG8_MMA(1, 0, At, B0); PG8_MMA(1, 1, At, B1); PG8_BAR; PG8_SCHED;
;             PG8_LDB(B0, 1, 0); PG8_LDB(B1, 1, 1); PG8_SCHED; PG8_LDA(At, 1, 0); PG8_STAGE(PG8_SA(0, 1), a2 + hsA, voffA);
;             PG8_WAIT_V(8); PG8_WAIT_L(0); PG8_BAR; PG8_MMA(0, 0, At, B0); PG8_MMA(0, 1, At, B1); PG8_BAR; PG8_SCHED;
	s_setprio 1
	s_waitcnt lgkmcnt(0)
	v_mfma_f32_16x16x32_bf16 v[92:95], v[128:131], v[176:179], v[92:95]
	v_mfma_f32_16x16x32_bf16 v[84:87], v[128:131], v[184:187], v[84:87]
	v_mfma_f32_16x16x32_bf16 v[76:79], v[128:131], v[192:195], v[76:79]
	v_mfma_f32_16x16x32_bf16 v[68:71], v[128:131], v[208:211], v[68:71]
	v_mfma_f32_16x16x32_bf16 v[64:67], v[136:139], v[208:211], v[64:67]
	v_mfma_f32_16x16x32_bf16 v[72:75], v[136:139], v[192:195], v[72:75]
	v_mfma_f32_16x16x32_bf16 v[80:83], v[136:139], v[184:187], v[80:83]
	v_mfma_f32_16x16x32_bf16 v[88:91], v[136:139], v[176:179], v[88:91]
	v_mfma_f32_16x16x32_bf16 v[92:95], v[132:135], v[180:183], v[92:95]
	v_mfma_f32_16x16x32_bf16 v[84:87], v[132:135], v[188:191], v[84:87]
	v_mfma_f32_16x16x32_bf16 v[76:79], v[132:135], v[196:199], v[76:79]
	v_mfma_f32_16x16x32_bf16 v[68:71], v[132:135], v[212:215], v[68:71]
	v_mfma_f32_16x16x32_bf16 v[64:67], v[140:143], v[212:215], v[64:67]
	v_mfma_f32_16x16x32_bf16 v[72:75], v[140:143], v[196:199], v[72:75]
	v_mfma_f32_16x16x32_bf16 v[80:83], v[140:143], v[188:191], v[80:83]
	v_mfma_f32_16x16x32_bf16 v[88:91], v[140:143], v[180:183], v[88:91]
	s_setprio 0
	s_setprio 1
	v_mfma_f32_16x16x32_bf16 v[28:31], v[144:147], v[176:179], v[28:31]
	v_mfma_f32_16x16x32_bf16 v[20:23], v[144:147], v[184:187], v[20:23]
	v_mfma_f32_16x16x32_bf16 v[12:15], v[144:147], v[192:195], v[12:15]
	v_mfma_f32_16x16x32_bf16 v[4:7], v[144:147], v[208:211], v[4:7]
	v_mfma_f32_16x16x32_bf16 v[0:3], v[152:155], v[208:211], v[0:3]
	v_mfma_f32_16x16x32_bf16 v[8:11], v[152:155], v[192:195], v[8:11]
	v_mfma_f32_16x16x32_bf16 v[16:19], v[152:155], v[184:187], v[16:19]
	v_mfma_f32_16x16x32_bf16 v[24:27], v[152:155], v[176:179], v[24:27]
	v_mfma_f32_16x16x32_bf16 v[28:31], v[148:151], v[180:183], v[28:31]
	v_mfma_f32_16x16x32_bf16 v[20:23], v[148:151], v[188:191], v[20:23]
	v_mfma_f32_16x16x32_bf16 v[12:15], v[148:151], v[196:199], v[12:15]
	v_mfma_f32_16x16x32_bf16 v[4:7], v[148:151], v[212:215], v[4:7]
	v_mfma_f32_16x16x32_bf16 v[0:3], v[156:159], v[212:215], v[0:3]
	v_mfma_f32_16x16x32_bf16 v[8:11], v[156:159], v[196:199], v[8:11]
	v_mfma_f32_16x16x32_bf16 v[16:19], v[156:159], v[188:191], v[16:19]
	v_mfma_f32_16x16x32_bf16 v[24:27], v[156:159], v[180:183], v[24:27]
	s_setprio 0
	s_barrier
	s_add_i32 s65, 0, 0x18000
	s_add_i32 s66, 0, 0x1c000
	v_add_u32_e32 v140, s65, v203
	v_add_u32_e32 v156, s66, v203
	ds_read_b128 v[128:131], v140
	ds_read_b128 v[132:135], v140 offset:1024
	ds_read_b128 v[136:139], v140 offset:2048
	ds_read_b128 v[140:143], v140 offset:3072
	ds_read_b128 v[144:147], v156
	ds_read_b128 v[148:151], v156 offset:1024
	ds_read_b128 v[152:155], v156 offset:2048
	ds_read_b128 v[156:159], v156 offset:3072
	s_add_u32 s42, s42, 0x40000
	s_addc_u32 s43, s43, 0
	s_mov_b32 m0, s47
	v_lshl_add_u64 v[222:223], s[42:43], 0, v[160:161]
	ds_read_b128 v[176:179], v207 offset:32768
	ds_read_b128 v[180:183], v207 offset:33792
	ds_read_b128 v[184:187], v207 offset:34816
	ds_read_b128 v[188:191], v207 offset:35840
	ds_read_b128 v[192:195], v207 offset:36864
	ds_read_b128 v[196:199], v207 offset:37888
	ds_read_b128 v[208:211], v207 offset:38912
	ds_read_b128 v[212:215], v207 offset:39936
	global_load_lds_dwordx4 v[222:223], off
	v_lshl_add_u64 v[222:223], s[42:43], 0, v[164:165]
	s_mov_b32 m0, s48
	s_nop 0
	global_load_lds_dwordx4 v[222:223], off
	s_waitcnt vmcnt(8)
	s_waitcnt lgkmcnt(0)
	s_barrier
	s_setprio 1
	s_waitcnt lgkmcnt(0)
	v_mfma_f32_16x16x32_bf16 v[124:127], v[128:131], v[176:179], v[124:127]
	v_mfma_f32_16x16x32_bf16 v[116:119], v[128:131], v[184:187], v[116:119]
	v_mfma_f32_16x16x32_bf16 v[108:111], v[128:131], v[192:195], v[108:111]
	v_mfma_f32_16x16x32_bf16 v[100:103], v[128:131], v[208:211], v[100:103]
	v_mfma_f32_16x16x32_bf16 v[96:99], v[136:139], v[208:211], v[96:99]
	v_mfma_f32_16x16x32_bf16 v[104:107], v[136:139], v[192:195], v[104:107]
	v_mfma_f32_16x16x32_bf16 v[112:115], v[136:139], v[184:187], v[112:115]
	v_mfma_f32_16x16x32_bf16 v[120:123], v[136:139], v[176:179], v[120:123]
	v_mfma_f32_16x16x32_bf16 v[124:127], v[132:135], v[180:183], v[124:127]
	v_mfma_f32_16x16x32_bf16 v[116:119], v[132:135], v[188:191], v[116:119]
	v_mfma_f32_16x16x32_bf16 v[108:111], v[132:135], v[196:199], v[108:111]
	v_mfma_f32_16x16x32_bf16 v[100:103], v[132:135], v[212:215], v[100:103]
	v_mfma_f32_16x16x32_bf16 v[96:99], v[140:143], v[212:215], v[96:99]
	v_mfma_f32_16x16x32_bf16 v[104:107], v[140:143], v[196:199], v[104:107]
	v_mfma_f32_16x16x32_bf16 v[112:115], v[140:143], v[188:191], v[112:115]
	v_mfma_f32_16x16x32_bf16 v[120:123], v[140:143], v[180:183], v[120:123]
	s_setprio 0
	s_setprio 1
	v_mfma_f32_16x16x32_bf16 v[60:63], v[144:147], v[176:179], v[60:63]
	v_mfma_f32_16x16x32_bf16 v[52:55], v[144:147], v[184:187], v[52:55]
	v_mfma_f32_16x16x32_bf16 v[44:47], v[144:147], v[192:195], v[44:47]
	v_mfma_f32_16x16x32_bf16 v[36:39], v[144:147], v[208:211], v[36:39]
	v_mfma_f32_16x16x32_bf16 v[32:35], v[152:155], v[208:211], v[32:35]
	v_mfma_f32_16x16x32_bf16 v[40:43], v[152:155], v[192:195], v[40:43]
	v_mfma_f32_16x16x32_bf16 v[48:51], v[152:155], v[184:187], v[48:51]
	v_mfma_f32_16x16x32_bf16 v[56:59], v[152:155], v[176:179], v[56:59]
	v_mfma_f32_16x16x32_bf16 v[60:63], v[148:151], v[180:183], v[60:63]
	v_mfma_f32_16x16x32_bf16 v[52:55], v[148:151], v[188:191], v[52:55]
	v_mfma_f32_16x16x32_bf16 v[44:47], v[148:151], v[196:199], v[44:47]
	v_mfma_f32_16x16x32_bf16 v[36:39], v[148:151], v[212:215], v[36:39]
	v_mfma_f32_16x16x32_bf16 v[32:35], v[156:159], v[212:215], v[32:35]
	v_mfma_f32_16x16x32_bf16 v[40:43], v[156:159], v[196:199], v[40:43]
	v_mfma_f32_16x16x32_bf16 v[48:51], v[156:159], v[188:191], v[48:51]
	v_mfma_f32_16x16x32_bf16 v[56:59], v[156:159], v[180:183], v[56:59]
	s_setprio 0
	s_barrier
; #define PG8_STAGE(bufoff, gbase, voff) do { _Pragma("unroll") for (int _i = 0; _i < 2; ++_i) \
;         __builtin_amdgcn_global_load_lds((const unsigned*)((const char*)(gbase) + (voff)[_i]), (PG8_LAS unsigned*)(lds + (bufoff) + ldsw + _i * 8192), 16, 0, 0); } while (0)
; #define PG8_LDA(dst, b, h) do { _Pragma("unroll") for (int m = 0; m < 4; ++m) _Pragma("unroll") for (int k = 0; k < 2; ++k) dst[m][k] = *(const PG8_LAS bf16x8*)(lds + PG8_SA(b, h) + aoff + m * 2048 + k * 1024); } while (0)
; #define PG8_MMA(ai, bj, At, Bt) do { __builtin_amdgcn_s_setprio(1); _Pragma("unroll") for (int m = 0; m < 4; ++m) _Pragma("unroll") for (int n = 0; n < 2; ++n) _Pragma("unroll") for (int k = 0; k < 2; ++k) \
;         acc[ai][bj][m][n] = __builtin_amdgcn_mfma_f32_16x16x32_bf16(Bt[n][k], At[m][k], acc[ai][bj][m][n], 0, 0, 0); __builtin_amdgcn_s_setprio(0); } while (0)
; #define PG8_WAIT_V(n) asm volatile("s_waitcnt vmcnt(" #n ")" ::: "memory")
; #define PG8_WAIT_L(n) asm volatile("s_waitcnt lgkmcnt(" #n ")" ::: "memory")
; #define PG8_BAR __builtin_amdgcn_s_barrier()
; #define PG8_SCHED __builtin_amdgcn_sched_barrier(0)
; template <class Epi, class Sched, bool ALIGN_EPI = false, bool SP2 = false>
; __device__ __forceinline__ void gemm_phase(PG8_LAS unsigned char* lds, const Gemm g, const Sched& S, const Epi& E, const int wid) {
;     ...
;         for (int t = 0; t < nt; t += 2) {
;     ...
;             PG8_LDA(At, 1, 1); PG8_STAGE(PG8_SB(1, 0), b3, voffB); PG8_STAGE(PG8_SB(1, 1), b3 + hsB, voffB); PG8_STAGE(PG8_SA(1, 0), a3, voffA);
;             PG8_WAIT_V(8); PG8_WAIT_L(0); PG8_BAR; PG8_MMA(1, 0, At, B0); PG8_MMA(1, 1, At, B1); PG8_BAR; PG8_SCHED;
	s_add_i32 s42, s65, s45
	v_lshl_add_u64 v[200:201], v[200:201], 0, s[16:17]
	s_mov_b32 m0, s42
	ds_read_b128 v[176:179], v207 offset:49152
	ds_read_b128 v[180:183], v207 offset:50176
	ds_read_b128 v[184:187], v207 offset:51200
	ds_read_b128 v[188:191], v207 offset:52224
	ds_read_b128 v[192:195], v207 offset:53248
	ds_read_b128 v[196:199], v207 offset:54272
	ds_read_b128 v[208:211], v207 offset:55296
	ds_read_b128 v[212:215], v207 offset:56320
	global_load_lds_dwordx4 v[200:201], off
	s_add_i32 m0, s42, 0x2000
	s_add_u32 s40, s40, 0x40080
	v_lshl_add_u64 v[200:201], v[216:217], 0, s[16:17]
	s_addc_u32 s41, s41, 0
	s_add_i32 s42, s66, s45
	global_load_lds_dwordx4 v[200:201], off
	v_lshl_add_u64 v[200:201], s[40:41], 0, v[162:163]
	s_mov_b32 m0, s42
	s_nop 0
	global_load_lds_dwordx4 v[200:201], off
	v_lshl_add_u64 v[200:201], s[40:41], 0, v[166:167]
	s_add_i32 m0, s42, 0x2000
	s_nop 0
	global_load_lds_dwordx4 v[200:201], off
	v_lshl_add_u64 v[200:201], v[218:219], 0, s[16:17]
	s_mov_b32 m0, s50
	s_nop 0
	global_load_lds_dwordx4 v[200:201], off
	v_lshl_add_u64 v[200:201], v[220:221], 0, s[16:17]
	s_mov_b32 m0, s51
	s_nop 0
	global_load_lds_dwordx4 v[200:201], off
	s_waitcnt vmcnt(8)
	s_waitcnt lgkmcnt(0)
	s_barrier
	s_setprio 1
	s_waitcnt lgkmcnt(0)
	v_mfma_f32_16x16x32_bf16 v[92:95], v[128:131], v[176:179], v[92:95]
	v_mfma_f32_16x16x32_bf16 v[84:87], v[128:131], v[184:187], v[84:87]
	v_mfma_f32_16x16x32_bf16 v[76:79], v[128:131], v[192:195], v[76:79]
	v_mfma_f32_16x16x32_bf16 v[68:71], v[128:131], v[208:211], v[68:71]
	v_mfma_f32_16x16x32_bf16 v[64:67], v[136:139], v[208:211], v[64:67]
	v_mfma_f32_16x16x32_bf16 v[72:75], v[136:139], v[192:195], v[72:75]
	v_mfma_f32_16x16x32_bf16 v[80:83], v[136:139], v[184:187], v[80:83]
	v_mfma_f32_16x16x32_bf16 v[88:91], v[136:139], v[176:179], v[88:91]
	v_mfma_f32_16x16x32_bf16 v[92:95], v[132:135], v[180:183], v[92:95]
	v_mfma_f32_16x16x32_bf16 v[84:87], v[132:135], v[188:191], v[84:87]
	v_mfma_f32_16x16x32_bf16 v[76:79], v[132:135], v[196:199], v[76:79]
	v_mfma_f32_16x16x32_bf16 v[68:71], v[132:135], v[212:215], v[68:71]
	v_mfma_f32_16x16x32_bf16 v[64:67], v[140:143], v[212:215], v[64:67]
	v_mfma_f32_16x16x32_bf16 v[72:75], v[140:143], v[196:199], v[72:75]
	v_mfma_f32_16x16x32_bf16 v[80:83], v[140:143], v[188:191], v[80:83]
	v_mfma_f32_16x16x32_bf16 v[88:91], v[140:143], v[180:183], v[88:91]
	s_setprio 0
	s_setprio 1
	v_mfma_f32_16x16x32_bf16 v[28:31], v[144:147], v[176:179], v[28:31]
	v_mfma_f32_16x16x32_bf16 v[20:23], v[144:147], v[184:187], v[20:23]
	v_mfma_f32_16x16x32_bf16 v[12:15], v[144:147], v[192:195], v[12:15]
	v_mfma_f32_16x16x32_bf16 v[4:7], v[144:147], v[208:211], v[4:7]
	v_mfma_f32_16x16x32_bf16 v[0:3], v[152:155], v[208:211], v[0:3]
	v_mfma_f32_16x16x32_bf16 v[8:11], v[152:155], v[192:195], v[8:11]
	v_mfma_f32_16x16x32_bf16 v[16:19], v[152:155], v[184:187], v[16:19]
	v_mfma_f32_16x16x32_bf16 v[24:27], v[152:155], v[176:179], v[24:27]
	v_mfma_f32_16x16x32_bf16 v[28:31], v[148:151], v[180:183], v[28:31]
	v_mfma_f32_16x16x32_bf16 v[20:23], v[148:151], v[188:191], v[20:23]
	v_mfma_f32_16x16x32_bf16 v[12:15], v[148:151], v[196:199], v[12:15]
	v_mfma_f32_16x16x32_bf16 v[4:7], v[148:151], v[212:215], v[4:7]
	v_mfma_f32_16x16x32_bf16 v[0:3], v[156:159], v[212:215], v[0:3]
	v_mfma_f32_16x16x32_bf16 v[8:11], v[156:159], v[196:199], v[8:11]
	v_mfma_f32_16x16x32_bf16 v[16:19], v[156:159], v[188:191], v[16:19]
	v_mfma_f32_16x16x32_bf16 v[24:27], v[156:159], v[180:183], v[24:27]
	s_setprio 0
	s_barrier
	s_add_i32 s64, s64, 2
	s_add_u32 s62, s62, 0x100
	s_addc_u32 s63, s63, 0
	s_add_u32 s38, s38, 0x100
	s_addc_u32 s39, s39, 0
	s_cmp_gt_u32 s64, 13
	s_cbranch_scc0 .LBB0_1177
	s_and_b64 vcc, exec, s[18:19]
	s_cbranch_vccz .LBB0_1180
	s_barrier

; #define PG8_STAGE(bufoff, gbase, voff) do { _Pragma("unroll") for (int _i = 0; _i < 2; ++_i) \
;         __builtin_amdgcn_global_load_lds((const unsigned*)((const char*)(gbase) + (voff)[_i]), (PG8_LAS unsigned*)(lds + (bufoff) + ldsw + _i * 8192), 16, 0, 0); } while (0)
; #define PG8_LDA(dst, b, h) do { _Pragma("unroll") for (int m = 0; m < 4; ++m) _Pragma("unroll") for (int k = 0; k < 2; ++k) dst[m][k] = *(const PG8_LAS bf16x8*)(lds + PG8_SA(b, h) + aoff + m * 2048 + k * 1024); } while (0)
; #define PG8_LDB(dst, b, h) do { _Pragma("unroll") for (int n = 0; n < 2; ++n) _Pragma("unroll") for (int k = 0; k < 2; ++k) dst[n][k] = *(const PG8_LAS bf16x8*)(lds + PG8_SB(b, h) + boff + n * 2048 + k * 1024); } while (0)
; #define PG8_MMA(ai, bj, At, Bt) do { __builtin_amdgcn_s_setprio(1); _Pragma("unroll") for (int m = 0; m < 4; ++m) _Pragma("unroll") for (int n = 0; n < 2; ++n) _Pragma("unroll") for (int k = 0; k < 2; ++k) \
;         acc[ai][bj][m][n] = __builtin_amdgcn_mfma_f32_16x16x32_bf16(Bt[n][k], At[m][k], acc[ai][bj][m][n], 0, 0, 0); __builtin_amdgcn_s_setprio(0); } while (0)
; #define PG8_WAIT_V(n) asm volatile("s_waitcnt vmcnt(" #n ")" ::: "memory")
; #define PG8_WAIT_L(n) asm volatile("s_waitcnt lgkmcnt(" #n ")" ::: "memory")
; #define PG8_BAR __builtin_amdgcn_s_barrier()
; #define PG8_SCHED __builtin_amdgcn_sched_barrier(0)
; template <class Epi, class Sched, bool ALIGN_EPI = false, bool SP2 = false>
; __device__ __forceinline__ void gemm_phase(PG8_LAS unsigned char* lds, const Gemm g, const Sched& S, const Epi& E, const int wid) {
;     ...
;             PG8_LDB(B0, 0, 0); PG8_LDB(B1, 0, 1); PG8_SCHED; PG8_LDA(At, 0, 0); PG8_STAGE(PG8_SA(1, 1), a1 + hsA, voffA);
;             PG8_WAIT_V(8); PG8_WAIT_L(0); PG8_BAR; PG8_MMA(0, 0, At, B0); PG8_MMA(0, 1, At, B1); PG8_BAR; PG8_SCHED;
;             PG8_LDA(At, 0, 1); PG8_STAGE(PG8_SB(0, 0), b2, voffB); PG8_STAGE(PG8_SB(0, 1), b2 + hsB, voffB); PG8_STAGE(PG8_SA(0, 0), a2, voffA);
;             PG8_WAIT_V(8); PG8_WAIT_L(0); PG8_BAR; PG8_MMA(1, 0, At, B0); PG8_MMA(1, 1, At, B1); PG8_BAR; PG8_SCHED;
.LBB0_1304:
	ds_read_b128 v[64:67], v199
	ds_read_b128 v[72:75], v199 offset:1024
	ds_read_b128 v[80:83], v199 offset:2048
	ds_read_b128 v[84:87], v199 offset:3072
	ds_read_b128 v[88:91], v200
	ds_read_b128 v[92:95], v200 offset:1024
	ds_read_b128 v[100:103], v200 offset:2048
	ds_read_b128 v[104:107], v200 offset:3072
	s_add_u32 s38, s36, 0xfff80080
	s_addc_u32 s39, s37, -1
	s_cmp_eq_u32 s61, 28
	s_cselect_b32 s41, s5, s39
	s_cselect_b32 s40, s27, s38
	s_cselect_b32 s39, s25, s60
	s_cselect_b32 s38, s58, s59
	v_lshl_add_u64 v[196:197], s[36:37], 0, v[182:183]
	s_add_i32 m0, s35, 0xc000
	ds_read_b128 v[160:163], v201
	ds_read_b128 v[164:167], v201 offset:1024
	ds_read_b128 v[168:171], v201 offset:2048
	ds_read_b128 v[172:175], v201 offset:3072
	ds_read_b128 v[188:191], v201 offset:4096
	ds_read_b128 v[192:195], v201 offset:5120
	ds_read_b128 v[204:207], v201 offset:6144
	ds_read_b128 v[208:211], v201 offset:7168
	global_load_lds_dwordx4 v[196:197], off
	v_lshl_add_u64 v[196:197], s[36:37], 0, v[180:181]
	s_add_i32 m0, s35, 0xe000
	s_nop 0
	global_load_lds_dwordx4 v[196:197], off
	s_waitcnt vmcnt(8)
	s_waitcnt lgkmcnt(0)
	s_barrier
	s_setprio 1
	s_waitcnt lgkmcnt(0)
	v_mfma_f32_16x16x32_bf16 v[156:159], v[64:67], v[160:163], v[156:159]
	v_mfma_f32_16x16x32_bf16 v[140:143], v[64:67], v[168:171], v[140:143]
	v_mfma_f32_16x16x32_bf16 v[124:127], v[64:67], v[188:191], v[124:127]
	v_mfma_f32_16x16x32_bf16 v[108:111], v[64:67], v[204:207], v[108:111]
	v_mfma_f32_16x16x32_bf16 v[96:99], v[80:83], v[204:207], v[96:99]
	v_mfma_f32_16x16x32_bf16 v[120:123], v[80:83], v[188:191], v[120:123]
	v_mfma_f32_16x16x32_bf16 v[136:139], v[80:83], v[168:171], v[136:139]
	v_mfma_f32_16x16x32_bf16 v[152:155], v[80:83], v[160:163], v[152:155]
	v_mfma_f32_16x16x32_bf16 v[156:159], v[72:75], v[164:167], v[156:159]
	v_mfma_f32_16x16x32_bf16 v[140:143], v[72:75], v[172:175], v[140:143]
	v_mfma_f32_16x16x32_bf16 v[124:127], v[72:75], v[192:195], v[124:127]
	v_mfma_f32_16x16x32_bf16 v[108:111], v[72:75], v[208:211], v[108:111]
	v_mfma_f32_16x16x32_bf16 v[96:99], v[84:87], v[208:211], v[96:99]
	v_mfma_f32_16x16x32_bf16 v[120:123], v[84:87], v[192:195], v[120:123]
	v_mfma_f32_16x16x32_bf16 v[136:139], v[84:87], v[172:175], v[136:139]
	v_mfma_f32_16x16x32_bf16 v[152:155], v[84:87], v[164:167], v[152:155]
	s_setprio 0
	s_setprio 1
	v_mfma_f32_16x16x32_bf16 v[148:151], v[88:91], v[160:163], v[148:151]
	v_mfma_f32_16x16x32_bf16 v[132:135], v[88:91], v[168:171], v[132:135]
	v_mfma_f32_16x16x32_bf16 v[116:119], v[88:91], v[188:191], v[116:119]
	v_mfma_f32_16x16x32_bf16 v[76:79], v[88:91], v[204:207], v[76:79]
	v_mfma_f32_16x16x32_bf16 v[68:71], v[100:103], v[204:207], v[68:71]
	v_mfma_f32_16x16x32_bf16 v[112:115], v[100:103], v[188:191], v[112:115]
	v_mfma_f32_16x16x32_bf16 v[128:131], v[100:103], v[168:171], v[128:131]
	v_mfma_f32_16x16x32_bf16 v[144:147], v[100:103], v[160:163], v[144:147]
	v_mfma_f32_16x16x32_bf16 v[148:151], v[92:95], v[164:167], v[148:151]
	v_mfma_f32_16x16x32_bf16 v[132:135], v[92:95], v[172:175], v[132:135]
	v_mfma_f32_16x16x32_bf16 v[116:119], v[92:95], v[192:195], v[116:119]
	v_mfma_f32_16x16x32_bf16 v[76:79], v[92:95], v[208:211], v[76:79]
	v_mfma_f32_16x16x32_bf16 v[68:71], v[104:107], v[208:211], v[68:71]
	v_mfma_f32_16x16x32_bf16 v[112:115], v[104:107], v[192:195], v[112:115]
	v_mfma_f32_16x16x32_bf16 v[128:131], v[104:107], v[172:175], v[128:131]
	v_mfma_f32_16x16x32_bf16 v[144:147], v[104:107], v[164:167], v[144:147]
	s_setprio 0
	s_barrier
	s_add_i32 s62, s56, s44
	v_lshl_add_u64 v[196:197], s[38:39], 0, v[176:177]
	s_mov_b32 m0, s62
	ds_read_b128 v[160:163], v201 offset:16384
	ds_read_b128 v[164:167], v201 offset:17408
	ds_read_b128 v[168:171], v201 offset:18432
	ds_read_b128 v[172:175], v201 offset:19456
	ds_read_b128 v[188:191], v201 offset:20480
	ds_read_b128 v[192:195], v201 offset:21504
	ds_read_b128 v[204:207], v201 offset:22528
	ds_read_b128 v[208:211], v201 offset:23552
	global_load_lds_dwordx4 v[196:197], off
	s_add_i32 m0, s62, 0x2000
	s_add_u32 s62, s38, 0x80000
	v_lshl_add_u64 v[212:213], s[38:39], 0, v[178:179]
	s_addc_u32 s63, s39, 0
	s_add_i32 s64, s57, s44
	global_load_lds_dwordx4 v[212:213], off
	v_lshl_add_u64 v[214:215], s[62:63], 0, v[176:177]
	s_mov_b32 m0, s64
	v_lshl_add_u64 v[216:217], s[40:41], 0, v[178:179]
	global_load_lds_dwordx4 v[214:215], off
	v_lshl_add_u64 v[214:215], s[62:63], 0, v[178:179]
	s_add_i32 m0, s64, 0x2000
	s_nop 0
	global_load_lds_dwordx4 v[214:215], off
	v_lshl_add_u64 v[214:215], s[40:41], 0, v[176:177]
	s_mov_b32 m0, s35
	s_nop 0
	global_load_lds_dwordx4 v[214:215], off
	s_mov_b32 m0, s45
	s_nop 0
	global_load_lds_dwordx4 v[216:217], off
	s_waitcnt vmcnt(8)
	s_waitcnt lgkmcnt(0)
	s_barrier
; #define PG8_STAGE(bufoff, gbase, voff) do { _Pragma("unroll") for (int _i = 0; _i < 2; ++_i) \
;         __builtin_amdgcn_global_load_lds((const unsigned*)((const char*)(gbase) + (voff)[_i]), (PG8_LAS unsigned*)(lds + (bufoff) + ldsw + _i * 8192), 16, 0, 0); } while (0)
; #define PG8_LDA(dst, b, h) do { _Pragma("unroll") for (int m = 0; m < 4; ++m) _Pragma("unroll") for (int k = 0; k < 2; ++k) dst[m][k] = *(const PG8_LAS bf16x8*)(lds + PG8_SA(b, h) + aoff + m * 2048 + k * 1024); } while (0)
; #define PG8_LDB(dst, b, h) do { _Pragma("unroll") for (int n = 0; n < 2; ++n) _Pragma("unroll") for (int k = 0; k < 2; ++k) dst[n][k] = *(const PG8_LAS bf16x8*)(lds + PG8_SB(b, h) + boff + n * 2048 + k * 1024); } while (0)
; #define PG8_MMA(ai, bj, At, Bt) do { __builtin_amdgcn_s_setprio(1); _Pragma("unroll") for (int m = 0; m < 4; ++m) _Pragma("unroll") for (int n = 0; n < 2; ++n) _Pragma("unroll") for (int k = 0; k < 2; ++k) \
;         acc[ai][bj][m][n] = __builtin_amdgcn_mfma_f32_16x16x32_bf16(Bt[n][k], At[m][k], acc[ai][bj][m][n], 0, 0, 0); __builtin_amdgcn_s_setprio(0); } while (0)
; #define PG8_WAIT_V(n) asm volatile("s_waitcnt vmcnt(" #n ")" ::: "memory")
; #define PG8_WAIT_L(n) asm volatile("s_waitcnt lgkmcnt(" #n ")" ::: "memory")
; #define PG8_BAR __builtin_amdgcn_s_barrier()
; #define PG8_SCHED __builtin_amdgcn_sched_barrier(0)
; template <class Epi, class Sched, bool ALIGN_EPI = false, bool SP2 = false>
; __device__ __forceinline__ void gemm_phase(PG8_LAS unsigned char* lds, const Gemm g, const Sched& S, const Epi& E, const int wid) {
;     ...
;             PG8_WAIT_V(8); PG8_WAIT_L(0); PG8_BAR; PG8_MMA(1, 0, At, B0); PG8_MMA(1, 1, At, B1); PG8_BAR; PG8_SCHED;
;             PG8_LDB(B0, 1, 0); PG8_LDB(B1, 1, 1); PG8_SCHED; PG8_LDA(At, 1, 0); PG8_STAGE(PG8_SA(0, 1), a2 + hsA, voffA);
;             PG8_WAIT_V(8); PG8_WAIT_L(0); PG8_BAR; PG8_MMA(0, 0, At, B0); PG8_MMA(0, 1, At, B1); PG8_BAR; PG8_SCHED;
	s_setprio 1
	s_waitcnt lgkmcnt(0)
	v_mfma_f32_16x16x32_bf16 v[60:63], v[64:67], v[160:163], v[60:63]
	v_mfma_f32_16x16x32_bf16 v[44:47], v[64:67], v[168:171], v[44:47]
	v_mfma_f32_16x16x32_bf16 v[28:31], v[64:67], v[188:191], v[28:31]
	v_mfma_f32_16x16x32_bf16 v[12:15], v[64:67], v[204:207], v[12:15]
	v_mfma_f32_16x16x32_bf16 v[8:11], v[80:83], v[204:207], v[8:11]
	v_mfma_f32_16x16x32_bf16 v[24:27], v[80:83], v[188:191], v[24:27]
	v_mfma_f32_16x16x32_bf16 v[40:43], v[80:83], v[168:171], v[40:43]
	v_mfma_f32_16x16x32_bf16 v[56:59], v[80:83], v[160:163], v[56:59]
	v_mfma_f32_16x16x32_bf16 v[60:63], v[72:75], v[164:167], v[60:63]
	v_mfma_f32_16x16x32_bf16 v[44:47], v[72:75], v[172:175], v[44:47]
	v_mfma_f32_16x16x32_bf16 v[28:31], v[72:75], v[192:195], v[28:31]
	v_mfma_f32_16x16x32_bf16 v[12:15], v[72:75], v[208:211], v[12:15]
	v_mfma_f32_16x16x32_bf16 v[8:11], v[84:87], v[208:211], v[8:11]
	v_mfma_f32_16x16x32_bf16 v[24:27], v[84:87], v[192:195], v[24:27]
	v_mfma_f32_16x16x32_bf16 v[40:43], v[84:87], v[172:175], v[40:43]
	v_mfma_f32_16x16x32_bf16 v[56:59], v[84:87], v[164:167], v[56:59]
	s_setprio 0
	s_setprio 1
	v_mfma_f32_16x16x32_bf16 v[52:55], v[88:91], v[160:163], v[52:55]
	v_mfma_f32_16x16x32_bf16 v[36:39], v[88:91], v[168:171], v[36:39]
	v_mfma_f32_16x16x32_bf16 v[20:23], v[88:91], v[188:191], v[20:23]
	v_mfma_f32_16x16x32_bf16 v[4:7], v[88:91], v[204:207], v[4:7]
	v_mfma_f32_16x16x32_bf16 v[0:3], v[100:103], v[204:207], v[0:3]
	v_mfma_f32_16x16x32_bf16 v[16:19], v[100:103], v[188:191], v[16:19]
	v_mfma_f32_16x16x32_bf16 v[32:35], v[100:103], v[168:171], v[32:35]
	v_mfma_f32_16x16x32_bf16 v[48:51], v[100:103], v[160:163], v[48:51]
	v_mfma_f32_16x16x32_bf16 v[52:55], v[92:95], v[164:167], v[52:55]
	v_mfma_f32_16x16x32_bf16 v[36:39], v[92:95], v[172:175], v[36:39]
	v_mfma_f32_16x16x32_bf16 v[20:23], v[92:95], v[192:195], v[20:23]
	v_mfma_f32_16x16x32_bf16 v[4:7], v[92:95], v[208:211], v[4:7]
	v_mfma_f32_16x16x32_bf16 v[0:3], v[104:107], v[208:211], v[0:3]
	v_mfma_f32_16x16x32_bf16 v[16:19], v[104:107], v[192:195], v[16:19]
	v_mfma_f32_16x16x32_bf16 v[32:35], v[104:107], v[172:175], v[32:35]
	v_mfma_f32_16x16x32_bf16 v[48:51], v[104:107], v[164:167], v[48:51]
	s_setprio 0
	s_barrier
	s_add_i32 s62, 0, 0x18000
	s_add_i32 s63, 0, 0x1c000
	v_add_u32_e32 v84, s62, v198
	v_add_u32_e32 v104, s63, v198
	ds_read_b128 v[64:67], v84
	ds_read_b128 v[72:75], v84 offset:1024
	ds_read_b128 v[80:83], v84 offset:2048
	ds_read_b128 v[84:87], v84 offset:3072
	ds_read_b128 v[88:91], v104
	ds_read_b128 v[92:95], v104 offset:1024
	ds_read_b128 v[100:103], v104 offset:2048
	ds_read_b128 v[104:107], v104 offset:3072
	s_add_u32 s40, s40, 0x80000
	s_addc_u32 s41, s41, 0
	s_mov_b32 m0, s46
	v_lshl_add_u64 v[218:219], s[40:41], 0, v[176:177]
	ds_read_b128 v[160:163], v201 offset:32768
	ds_read_b128 v[164:167], v201 offset:33792
	ds_read_b128 v[168:171], v201 offset:34816
	ds_read_b128 v[172:175], v201 offset:35840
	ds_read_b128 v[188:191], v201 offset:36864
	ds_read_b128 v[192:195], v201 offset:37888
	ds_read_b128 v[204:207], v201 offset:38912
	ds_read_b128 v[208:211], v201 offset:39936
	global_load_lds_dwordx4 v[218:219], off
	v_lshl_add_u64 v[218:219], s[40:41], 0, v[178:179]
	s_mov_b32 m0, s47
	s_nop 0
	global_load_lds_dwordx4 v[218:219], off
	s_waitcnt vmcnt(8)
	s_waitcnt lgkmcnt(0)
	s_barrier
	s_setprio 1
	s_waitcnt lgkmcnt(0)
	v_mfma_f32_16x16x32_bf16 v[156:159], v[64:67], v[160:163], v[156:159]
	v_mfma_f32_16x16x32_bf16 v[140:143], v[64:67], v[168:171], v[140:143]
	v_mfma_f32_16x16x32_bf16 v[124:127], v[64:67], v[188:191], v[124:127]
	v_mfma_f32_16x16x32_bf16 v[108:111], v[64:67], v[204:207], v[108:111]
	v_mfma_f32_16x16x32_bf16 v[96:99], v[80:83], v[204:207], v[96:99]
	v_mfma_f32_16x16x32_bf16 v[120:123], v[80:83], v[188:191], v[120:123]
	v_mfma_f32_16x16x32_bf16 v[136:139], v[80:83], v[168:171], v[136:139]
	v_mfma_f32_16x16x32_bf16 v[152:155], v[80:83], v[160:163], v[152:155]
	v_mfma_f32_16x16x32_bf16 v[156:159], v[72:75], v[164:167], v[156:159]
	v_mfma_f32_16x16x32_bf16 v[140:143], v[72:75], v[172:175], v[140:143]
	v_mfma_f32_16x16x32_bf16 v[124:127], v[72:75], v[192:195], v[124:127]
	v_mfma_f32_16x16x32_bf16 v[108:111], v[72:75], v[208:211], v[108:111]
	v_mfma_f32_16x16x32_bf16 v[96:99], v[84:87], v[208:211], v[96:99]
	v_mfma_f32_16x16x32_bf16 v[120:123], v[84:87], v[192:195], v[120:123]
	v_mfma_f32_16x16x32_bf16 v[136:139], v[84:87], v[172:175], v[136:139]
	v_mfma_f32_16x16x32_bf16 v[152:155], v[84:87], v[164:167], v[152:155]
	s_setprio 0
	s_setprio 1
	v_mfma_f32_16x16x32_bf16 v[148:151], v[88:91], v[160:163], v[148:151]
	v_mfma_f32_16x16x32_bf16 v[132:135], v[88:91], v[168:171], v[132:135]
	v_mfma_f32_16x16x32_bf16 v[116:119], v[88:91], v[188:191], v[116:119]
	v_mfma_f32_16x16x32_bf16 v[76:79], v[88:91], v[204:207], v[76:79]
	v_mfma_f32_16x16x32_bf16 v[68:71], v[100:103], v[204:207], v[68:71]
	v_mfma_f32_16x16x32_bf16 v[112:115], v[100:103], v[188:191], v[112:115]
	v_mfma_f32_16x16x32_bf16 v[128:131], v[100:103], v[168:171], v[128:131]
	v_mfma_f32_16x16x32_bf16 v[144:147], v[100:103], v[160:163], v[144:147]
	v_mfma_f32_16x16x32_bf16 v[148:151], v[92:95], v[164:167], v[148:151]
	v_mfma_f32_16x16x32_bf16 v[132:135], v[92:95], v[172:175], v[132:135]
	v_mfma_f32_16x16x32_bf16 v[116:119], v[92:95], v[192:195], v[116:119]
	v_mfma_f32_16x16x32_bf16 v[76:79], v[92:95], v[208:211], v[76:79]
	v_mfma_f32_16x16x32_bf16 v[68:71], v[104:107], v[208:211], v[68:71]
	v_mfma_f32_16x16x32_bf16 v[112:115], v[104:107], v[192:195], v[112:115]
	v_mfma_f32_16x16x32_bf16 v[128:131], v[104:107], v[172:175], v[128:131]
	v_mfma_f32_16x16x32_bf16 v[144:147], v[104:107], v[164:167], v[144:147]
	s_setprio 0
	s_barrier
; #define PG8_STAGE(bufoff, gbase, voff) do { _Pragma("unroll") for (int _i = 0; _i < 2; ++_i) \
;         __builtin_amdgcn_global_load_lds((const unsigned*)((const char*)(gbase) + (voff)[_i]), (PG8_LAS unsigned*)(lds + (bufoff) + ldsw + _i * 8192), 16, 0, 0); } while (0)
; #define PG8_LDA(dst, b, h) do { _Pragma("unroll") for (int m = 0; m < 4; ++m) _Pragma("unroll") for (int k = 0; k < 2; ++k) dst[m][k] = *(const PG8_LAS bf16x8*)(lds + PG8_SA(b, h) + aoff + m * 2048 + k * 1024); } while (0)
; #define PG8_MMA(ai, bj, At, Bt) do { __builtin_amdgcn_s_setprio(1); _Pragma("unroll") for (int m = 0; m < 4; ++m) _Pragma("unroll") for (int n = 0; n < 2; ++n) _Pragma("unroll") for (int k = 0; k < 2; ++k) \
;         acc[ai][bj][m][n] = __builtin_amdgcn_mfma_f32_16x16x32_bf16(Bt[n][k], At[m][k], acc[ai][bj][m][n], 0, 0, 0); __builtin_amdgcn_s_setprio(0); } while (0)
; #define PG8_WAIT_V(n) asm volatile("s_waitcnt vmcnt(" #n ")" ::: "memory")
; #define PG8_WAIT_L(n) asm volatile("s_waitcnt lgkmcnt(" #n ")" ::: "memory")
; #define PG8_BAR __builtin_amdgcn_s_barrier()
; #define PG8_SCHED __builtin_amdgcn_sched_barrier(0)
; template <class Epi, class Sched, bool ALIGN_EPI = false, bool SP2 = false>
; __device__ __forceinline__ void gemm_phase(PG8_LAS unsigned char* lds, const Gemm g, const Sched& S, const Epi& E, const int wid) {
;     ...
;         for (int t = 0; t < nt; t += 2) {
;     ...
;             PG8_LDA(At, 1, 1); PG8_STAGE(PG8_SB(1, 0), b3, voffB); PG8_STAGE(PG8_SB(1, 1), b3 + hsB, voffB); PG8_STAGE(PG8_SA(1, 0), a3, voffA);
;             PG8_WAIT_V(8); PG8_WAIT_L(0); PG8_BAR; PG8_MMA(1, 0, At, B0); PG8_MMA(1, 1, At, B1); PG8_BAR; PG8_SCHED;
	s_add_i32 s40, s62, s44
	v_lshl_add_u64 v[196:197], v[196:197], 0, s[20:21]
	s_mov_b32 m0, s40
	ds_read_b128 v[160:163], v201 offset:49152
	ds_read_b128 v[164:167], v201 offset:50176
	ds_read_b128 v[168:171], v201 offset:51200
	ds_read_b128 v[172:175], v201 offset:52224
	ds_read_b128 v[188:191], v201 offset:53248
	ds_read_b128 v[192:195], v201 offset:54272
	ds_read_b128 v[204:207], v201 offset:55296
	ds_read_b128 v[208:211], v201 offset:56320
	global_load_lds_dwordx4 v[196:197], off
	s_add_i32 m0, s40, 0x2000
	s_add_u32 s38, s38, 0x80080
	v_lshl_add_u64 v[196:197], v[212:213], 0, s[20:21]
	s_addc_u32 s39, s39, 0
	s_add_i32 s40, s63, s44
	global_load_lds_dwordx4 v[196:197], off
	v_lshl_add_u64 v[196:197], s[38:39], 0, v[176:177]
	s_mov_b32 m0, s40
	s_nop 0
	global_load_lds_dwordx4 v[196:197], off
	v_lshl_add_u64 v[196:197], s[38:39], 0, v[178:179]
	s_add_i32 m0, s40, 0x2000
	s_nop 0
	global_load_lds_dwordx4 v[196:197], off
	v_lshl_add_u64 v[196:197], v[214:215], 0, s[20:21]
	s_mov_b32 m0, s51
	s_nop 0
	global_load_lds_dwordx4 v[196:197], off
	v_lshl_add_u64 v[196:197], v[216:217], 0, s[20:21]
	s_mov_b32 m0, s52
	s_nop 0
	global_load_lds_dwordx4 v[196:197], off
	s_waitcnt vmcnt(8)
	s_waitcnt lgkmcnt(0)
	s_barrier
	s_setprio 1
	s_waitcnt lgkmcnt(0)
	v_mfma_f32_16x16x32_bf16 v[60:63], v[64:67], v[160:163], v[60:63]
	v_mfma_f32_16x16x32_bf16 v[44:47], v[64:67], v[168:171], v[44:47]
	v_mfma_f32_16x16x32_bf16 v[28:31], v[64:67], v[188:191], v[28:31]
	v_mfma_f32_16x16x32_bf16 v[12:15], v[64:67], v[204:207], v[12:15]
	v_mfma_f32_16x16x32_bf16 v[8:11], v[80:83], v[204:207], v[8:11]
	v_mfma_f32_16x16x32_bf16 v[24:27], v[80:83], v[188:191], v[24:27]
	v_mfma_f32_16x16x32_bf16 v[40:43], v[80:83], v[168:171], v[40:43]
	v_mfma_f32_16x16x32_bf16 v[56:59], v[80:83], v[160:163], v[56:59]
	v_mfma_f32_16x16x32_bf16 v[60:63], v[72:75], v[164:167], v[60:63]
	v_mfma_f32_16x16x32_bf16 v[44:47], v[72:75], v[172:175], v[44:47]
	v_mfma_f32_16x16x32_bf16 v[28:31], v[72:75], v[192:195], v[28:31]
	v_mfma_f32_16x16x32_bf16 v[12:15], v[72:75], v[208:211], v[12:15]
	v_mfma_f32_16x16x32_bf16 v[8:11], v[84:87], v[208:211], v[8:11]
	v_mfma_f32_16x16x32_bf16 v[24:27], v[84:87], v[192:195], v[24:27]
	v_mfma_f32_16x16x32_bf16 v[40:43], v[84:87], v[172:175], v[40:43]
	v_mfma_f32_16x16x32_bf16 v[56:59], v[84:87], v[164:167], v[56:59]
	s_setprio 0
	s_setprio 1
	v_mfma_f32_16x16x32_bf16 v[52:55], v[88:91], v[160:163], v[52:55]
	v_mfma_f32_16x16x32_bf16 v[36:39], v[88:91], v[168:171], v[36:39]
	v_mfma_f32_16x16x32_bf16 v[20:23], v[88:91], v[188:191], v[20:23]
	v_mfma_f32_16x16x32_bf16 v[4:7], v[88:91], v[204:207], v[4:7]
	v_mfma_f32_16x16x32_bf16 v[0:3], v[100:103], v[204:207], v[0:3]
	v_mfma_f32_16x16x32_bf16 v[16:19], v[100:103], v[188:191], v[16:19]
	v_mfma_f32_16x16x32_bf16 v[32:35], v[100:103], v[168:171], v[32:35]
	v_mfma_f32_16x16x32_bf16 v[48:51], v[100:103], v[160:163], v[48:51]
	v_mfma_f32_16x16x32_bf16 v[52:55], v[92:95], v[164:167], v[52:55]
	v_mfma_f32_16x16x32_bf16 v[36:39], v[92:95], v[172:175], v[36:39]
	v_mfma_f32_16x16x32_bf16 v[20:23], v[92:95], v[192:195], v[20:23]
	v_mfma_f32_16x16x32_bf16 v[4:7], v[92:95], v[208:211], v[4:7]
	v_mfma_f32_16x16x32_bf16 v[0:3], v[104:107], v[208:211], v[0:3]
	v_mfma_f32_16x16x32_bf16 v[16:19], v[104:107], v[192:195], v[16:19]
	v_mfma_f32_16x16x32_bf16 v[32:35], v[104:107], v[172:175], v[32:35]
	v_mfma_f32_16x16x32_bf16 v[48:51], v[104:107], v[164:167], v[48:51]
	s_setprio 0
	s_barrier
	s_add_i32 s61, s61, 2
	s_add_u32 s59, s59, 0x100
	s_addc_u32 s60, s60, 0
	s_add_u32 s36, s36, 0x100
	s_addc_u32 s37, s37, 0
	s_cmp_gt_u32 s61, 29
	s_cbranch_scc0 .LBB0_1304
	s_and_b64 vcc, exec, s[22:23]
	s_cbranch_vccz .LBB0_1307
	s_barrier

; #define PG8_STAGE(bufoff, gbase, voff) do { _Pragma("unroll") for (int _i = 0; _i < 2; ++_i) \
;         __builtin_amdgcn_global_load_lds((const unsigned*)((const char*)(gbase) + (voff)[_i]), (PG8_LAS unsigned*)(lds + (bufoff) + ldsw + _i * 8192), 16, 0, 0); } while (0)
; #define PG8_LDA(dst, b, h) do { _Pragma("unroll") for (int m = 0; m < 4; ++m) _Pragma("unroll") for (int k = 0; k < 2; ++k) dst[m][k] = *(const PG8_LAS bf16x8*)(lds + PG8_SA(b, h) + aoff + m * 2048 + k * 1024); } while (0)
; #define PG8_LDB(dst, b, h) do { _Pragma("unroll") for (int n = 0; n < 2; ++n) _Pragma("unroll") for (int k = 0; k < 2; ++k) dst[n][k] = *(const PG8_LAS bf16x8*)(lds + PG8_SB(b, h) + boff + n * 2048 + k * 1024); } while (0)
; #define PG8_MMA(ai, bj, At, Bt) do { __builtin_amdgcn_s_setprio(1); _Pragma("unroll") for (int m = 0; m < 4; ++m) _Pragma("unroll") for (int n = 0; n < 2; ++n) _Pragma("unroll") for (int k = 0; k < 2; ++k) \
;         acc[ai][bj][m][n] = __builtin_amdgcn_mfma_f32_16x16x32_bf16(Bt[n][k], At[m][k], acc[ai][bj][m][n], 0, 0, 0); __builtin_amdgcn_s_setprio(0); } while (0)
; #define PG8_WAIT_V(n) asm volatile("s_waitcnt vmcnt(" #n ")" ::: "memory")
; #define PG8_WAIT_L(n) asm volatile("s_waitcnt lgkmcnt(" #n ")" ::: "memory")
; #define PG8_BAR __builtin_amdgcn_s_barrier()
; #define PG8_SCHED __builtin_amdgcn_sched_barrier(0)
; template <class Epi, class Sched, bool ALIGN_EPI = false, bool SP2 = false>
; __device__ __forceinline__ void gemm_phase(PG8_LAS unsigned char* lds, const Gemm g, const Sched& S, const Epi& E, const int wid) {
;     ...
;             PG8_LDB(B0, 0, 0); PG8_LDB(B1, 0, 1); PG8_SCHED; PG8_LDA(At, 0, 0); PG8_STAGE(PG8_SA(1, 1), a1 + hsA, voffA);
;             PG8_WAIT_V(8); PG8_WAIT_L(0); PG8_BAR; PG8_MMA(0, 0, At, B0); PG8_MMA(0, 1, At, B1); PG8_BAR; PG8_SCHED;
;             PG8_LDA(At, 0, 1); PG8_STAGE(PG8_SB(0, 0), b2, voffB); PG8_STAGE(PG8_SB(0, 1), b2 + hsB, voffB); PG8_STAGE(PG8_SA(0, 0), a2, voffA);
;             PG8_WAIT_V(8); PG8_WAIT_L(0); PG8_BAR; PG8_MMA(1, 0, At, B0); PG8_MMA(1, 1, At, B1); PG8_BAR; PG8_SCHED;
.LBB0_1385:
	ds_read_b128 v[128:131], v171
	ds_read_b128 v[132:135], v171 offset:1024
	ds_read_b128 v[136:139], v171 offset:2048
	ds_read_b128 v[140:143], v171 offset:3072
	ds_read_b128 v[160:163], v173
	ds_read_b128 v[164:167], v173 offset:1024
	ds_read_b128 v[180:183], v173 offset:2048
	ds_read_b128 v[184:187], v173 offset:3072
	s_add_u32 s8, s6, 0xfff80080
	s_addc_u32 s9, s7, -1
	s_cmp_eq_u32 s60, 28
	s_cselect_b32 s31, s5, s9
	s_cselect_b32 s30, s25, s8
	s_cselect_b32 s9, s23, s59
	s_cselect_b32 s8, s57, s58
	v_lshl_add_u64 v[220:221], s[6:7], 0, v[154:155]
	s_add_i32 m0, s39, 0xc000
	ds_read_b128 v[188:191], v175
	ds_read_b128 v[192:195], v175 offset:1024
	ds_read_b128 v[196:199], v175 offset:2048
	ds_read_b128 v[200:203], v175 offset:3072
	ds_read_b128 v[204:207], v175 offset:4096
	ds_read_b128 v[208:211], v175 offset:5120
	ds_read_b128 v[212:215], v175 offset:6144
	ds_read_b128 v[216:219], v175 offset:7168
	global_load_lds_dwordx4 v[220:221], off
	v_lshl_add_u64 v[220:221], s[6:7], 0, v[152:153]
	s_add_i32 m0, s39, 0xe000
	s_nop 0
	global_load_lds_dwordx4 v[220:221], off
	s_waitcnt vmcnt(8)
	s_waitcnt lgkmcnt(0)
	s_barrier
	s_setprio 1
	s_waitcnt lgkmcnt(0)
	v_mfma_f32_16x16x32_bf16 v[124:127], v[128:131], v[188:191], v[124:127]
	v_mfma_f32_16x16x32_bf16 v[108:111], v[128:131], v[196:199], v[108:111]
	v_mfma_f32_16x16x32_bf16 v[92:95], v[128:131], v[204:207], v[92:95]
	v_mfma_f32_16x16x32_bf16 v[76:79], v[128:131], v[212:215], v[76:79]
	v_mfma_f32_16x16x32_bf16 v[72:75], v[136:139], v[212:215], v[72:75]
	v_mfma_f32_16x16x32_bf16 v[88:91], v[136:139], v[204:207], v[88:91]
	v_mfma_f32_16x16x32_bf16 v[104:107], v[136:139], v[196:199], v[104:107]
	v_mfma_f32_16x16x32_bf16 v[120:123], v[136:139], v[188:191], v[120:123]
	v_mfma_f32_16x16x32_bf16 v[124:127], v[132:135], v[192:195], v[124:127]
	v_mfma_f32_16x16x32_bf16 v[108:111], v[132:135], v[200:203], v[108:111]
	v_mfma_f32_16x16x32_bf16 v[92:95], v[132:135], v[208:211], v[92:95]
	v_mfma_f32_16x16x32_bf16 v[76:79], v[132:135], v[216:219], v[76:79]
	v_mfma_f32_16x16x32_bf16 v[72:75], v[140:143], v[216:219], v[72:75]
	v_mfma_f32_16x16x32_bf16 v[88:91], v[140:143], v[208:211], v[88:91]
	v_mfma_f32_16x16x32_bf16 v[104:107], v[140:143], v[200:203], v[104:107]
	v_mfma_f32_16x16x32_bf16 v[120:123], v[140:143], v[192:195], v[120:123]
	s_setprio 0
	s_setprio 1
	v_mfma_f32_16x16x32_bf16 v[116:119], v[160:163], v[188:191], v[116:119]
	v_mfma_f32_16x16x32_bf16 v[100:103], v[160:163], v[196:199], v[100:103]
	v_mfma_f32_16x16x32_bf16 v[84:87], v[160:163], v[204:207], v[84:87]
	v_mfma_f32_16x16x32_bf16 v[68:71], v[160:163], v[212:215], v[68:71]
	v_mfma_f32_16x16x32_bf16 v[64:67], v[180:183], v[212:215], v[64:67]
	v_mfma_f32_16x16x32_bf16 v[80:83], v[180:183], v[204:207], v[80:83]
	v_mfma_f32_16x16x32_bf16 v[96:99], v[180:183], v[196:199], v[96:99]
	v_mfma_f32_16x16x32_bf16 v[112:115], v[180:183], v[188:191], v[112:115]
	v_mfma_f32_16x16x32_bf16 v[116:119], v[164:167], v[192:195], v[116:119]
	v_mfma_f32_16x16x32_bf16 v[100:103], v[164:167], v[200:203], v[100:103]
	v_mfma_f32_16x16x32_bf16 v[84:87], v[164:167], v[208:211], v[84:87]
	v_mfma_f32_16x16x32_bf16 v[68:71], v[164:167], v[216:219], v[68:71]
	v_mfma_f32_16x16x32_bf16 v[64:67], v[184:187], v[216:219], v[64:67]
	v_mfma_f32_16x16x32_bf16 v[80:83], v[184:187], v[208:211], v[80:83]
	v_mfma_f32_16x16x32_bf16 v[96:99], v[184:187], v[200:203], v[96:99]
	v_mfma_f32_16x16x32_bf16 v[112:115], v[184:187], v[192:195], v[112:115]
	s_setprio 0
	s_barrier
	s_add_i32 s61, s52, s36
	v_lshl_add_u64 v[220:221], s[8:9], 0, v[148:149]
	s_mov_b32 m0, s61
	ds_read_b128 v[188:191], v175 offset:16384
	ds_read_b128 v[192:195], v175 offset:17408
	ds_read_b128 v[196:199], v175 offset:18432
	ds_read_b128 v[200:203], v175 offset:19456
	ds_read_b128 v[204:207], v175 offset:20480
	ds_read_b128 v[208:211], v175 offset:21504
	ds_read_b128 v[212:215], v175 offset:22528
	ds_read_b128 v[216:219], v175 offset:23552
	global_load_lds_dwordx4 v[220:221], off
	s_add_i32 m0, s61, 0x2000
	s_add_u32 s62, s8, 0x80000
	v_lshl_add_u64 v[222:223], s[8:9], 0, v[144:145]
	s_addc_u32 s63, s9, 0
	s_add_i32 s61, s53, s36
	global_load_lds_dwordx4 v[222:223], off
	v_lshl_add_u64 v[224:225], s[62:63], 0, v[148:149]
	s_mov_b32 m0, s61
	v_lshl_add_u64 v[226:227], s[30:31], 0, v[146:147]
	global_load_lds_dwordx4 v[224:225], off
	v_lshl_add_u64 v[224:225], s[62:63], 0, v[144:145]
	s_add_i32 m0, s61, 0x2000
	s_nop 0
	global_load_lds_dwordx4 v[224:225], off
	v_lshl_add_u64 v[224:225], s[30:31], 0, v[150:151]
	s_mov_b32 m0, s39
	s_nop 0
	global_load_lds_dwordx4 v[224:225], off
	s_mov_b32 m0, s40
	s_nop 0
	global_load_lds_dwordx4 v[226:227], off
	s_waitcnt vmcnt(8)
	s_waitcnt lgkmcnt(0)
	s_barrier
; #define PG8_STAGE(bufoff, gbase, voff) do { _Pragma("unroll") for (int _i = 0; _i < 2; ++_i) \
;         __builtin_amdgcn_global_load_lds((const unsigned*)((const char*)(gbase) + (voff)[_i]), (PG8_LAS unsigned*)(lds + (bufoff) + ldsw + _i * 8192), 16, 0, 0); } while (0)
; #define PG8_LDA(dst, b, h) do { _Pragma("unroll") for (int m = 0; m < 4; ++m) _Pragma("unroll") for (int k = 0; k < 2; ++k) dst[m][k] = *(const PG8_LAS bf16x8*)(lds + PG8_SA(b, h) + aoff + m * 2048 + k * 1024); } while (0)
; #define PG8_LDB(dst, b, h) do { _Pragma("unroll") for (int n = 0; n < 2; ++n) _Pragma("unroll") for (int k = 0; k < 2; ++k) dst[n][k] = *(const PG8_LAS bf16x8*)(lds + PG8_SB(b, h) + boff + n * 2048 + k * 1024); } while (0)
; #define PG8_MMA(ai, bj, At, Bt) do { __builtin_amdgcn_s_setprio(1); _Pragma("unroll") for (int m = 0; m < 4; ++m) _Pragma("unroll") for (int n = 0; n < 2; ++n) _Pragma("unroll") for (int k = 0; k < 2; ++k) \
;         acc[ai][bj][m][n] = __builtin_amdgcn_mfma_f32_16x16x32_bf16(Bt[n][k], At[m][k], acc[ai][bj][m][n], 0, 0, 0); __builtin_amdgcn_s_setprio(0); } while (0)
; #define PG8_WAIT_V(n) asm volatile("s_waitcnt vmcnt(" #n ")" ::: "memory")
; #define PG8_WAIT_L(n) asm volatile("s_waitcnt lgkmcnt(" #n ")" ::: "memory")
; #define PG8_BAR __builtin_amdgcn_s_barrier()
; #define PG8_SCHED __builtin_amdgcn_sched_barrier(0)
; template <class Epi, class Sched, bool ALIGN_EPI = false, bool SP2 = false>
; __device__ __forceinline__ void gemm_phase(PG8_LAS unsigned char* lds, const Gemm g, const Sched& S, const Epi& E, const int wid) {
;     ...
;             PG8_WAIT_V(8); PG8_WAIT_L(0); PG8_BAR; PG8_MMA(1, 0, At, B0); PG8_MMA(1, 1, At, B1); PG8_BAR; PG8_SCHED;
;             PG8_LDB(B0, 1, 0); PG8_LDB(B1, 1, 1); PG8_SCHED; PG8_LDA(At, 1, 0); PG8_STAGE(PG8_SA(0, 1), a2 + hsA, voffA);
;             PG8_WAIT_V(8); PG8_WAIT_L(0); PG8_BAR; PG8_MMA(0, 0, At, B0); PG8_MMA(0, 1, At, B1); PG8_BAR; PG8_SCHED;
	s_setprio 1
	s_waitcnt lgkmcnt(0)
	v_mfma_f32_16x16x32_bf16 v[60:63], v[128:131], v[188:191], v[60:63]
	v_mfma_f32_16x16x32_bf16 v[44:47], v[128:131], v[196:199], v[44:47]
	v_mfma_f32_16x16x32_bf16 v[28:31], v[128:131], v[204:207], v[28:31]
	v_mfma_f32_16x16x32_bf16 v[12:15], v[128:131], v[212:215], v[12:15]
	v_mfma_f32_16x16x32_bf16 v[8:11], v[136:139], v[212:215], v[8:11]
	v_mfma_f32_16x16x32_bf16 v[24:27], v[136:139], v[204:207], v[24:27]
	v_mfma_f32_16x16x32_bf16 v[40:43], v[136:139], v[196:199], v[40:43]
	v_mfma_f32_16x16x32_bf16 v[56:59], v[136:139], v[188:191], v[56:59]
	v_mfma_f32_16x16x32_bf16 v[60:63], v[132:135], v[192:195], v[60:63]
	v_mfma_f32_16x16x32_bf16 v[44:47], v[132:135], v[200:203], v[44:47]
	v_mfma_f32_16x16x32_bf16 v[28:31], v[132:135], v[208:211], v[28:31]
	v_mfma_f32_16x16x32_bf16 v[12:15], v[132:135], v[216:219], v[12:15]
	v_mfma_f32_16x16x32_bf16 v[8:11], v[140:143], v[216:219], v[8:11]
	v_mfma_f32_16x16x32_bf16 v[24:27], v[140:143], v[208:211], v[24:27]
	v_mfma_f32_16x16x32_bf16 v[40:43], v[140:143], v[200:203], v[40:43]
	v_mfma_f32_16x16x32_bf16 v[56:59], v[140:143], v[192:195], v[56:59]
	s_setprio 0
	s_setprio 1
	v_mfma_f32_16x16x32_bf16 v[52:55], v[160:163], v[188:191], v[52:55]
	v_mfma_f32_16x16x32_bf16 v[36:39], v[160:163], v[196:199], v[36:39]
	v_mfma_f32_16x16x32_bf16 v[20:23], v[160:163], v[204:207], v[20:23]
	v_mfma_f32_16x16x32_bf16 v[4:7], v[160:163], v[212:215], v[4:7]
	v_mfma_f32_16x16x32_bf16 v[0:3], v[180:183], v[212:215], v[0:3]
	v_mfma_f32_16x16x32_bf16 v[16:19], v[180:183], v[204:207], v[16:19]
	v_mfma_f32_16x16x32_bf16 v[32:35], v[180:183], v[196:199], v[32:35]
	v_mfma_f32_16x16x32_bf16 v[48:51], v[180:183], v[188:191], v[48:51]
	v_mfma_f32_16x16x32_bf16 v[52:55], v[164:167], v[192:195], v[52:55]
	v_mfma_f32_16x16x32_bf16 v[36:39], v[164:167], v[200:203], v[36:39]
	v_mfma_f32_16x16x32_bf16 v[20:23], v[164:167], v[208:211], v[20:23]
	v_mfma_f32_16x16x32_bf16 v[4:7], v[164:167], v[216:219], v[4:7]
	v_mfma_f32_16x16x32_bf16 v[0:3], v[184:187], v[216:219], v[0:3]
	v_mfma_f32_16x16x32_bf16 v[16:19], v[184:187], v[208:211], v[16:19]
	v_mfma_f32_16x16x32_bf16 v[32:35], v[184:187], v[200:203], v[32:35]
	v_mfma_f32_16x16x32_bf16 v[48:51], v[184:187], v[192:195], v[48:51]
	s_setprio 0
	s_barrier
	s_add_i32 s61, 0, 0x18000
	s_add_i32 s62, 0, 0x1c000
	v_add_u32_e32 v140, s61, v169
	v_add_u32_e32 v168, s62, v169
	ds_read_b128 v[128:131], v140
	ds_read_b128 v[132:135], v140 offset:1024
	ds_read_b128 v[136:139], v140 offset:2048
	ds_read_b128 v[140:143], v140 offset:3072
	ds_read_b128 v[160:163], v168
	ds_read_b128 v[164:167], v168 offset:1024
	ds_read_b128 v[180:183], v168 offset:2048
	ds_read_b128 v[184:187], v168 offset:3072
	s_add_u32 s30, s30, 0x80000
	s_addc_u32 s31, s31, 0
	s_mov_b32 m0, s41
	v_lshl_add_u64 v[228:229], s[30:31], 0, v[150:151]
	ds_read_b128 v[188:191], v175 offset:32768
	ds_read_b128 v[192:195], v175 offset:33792
	ds_read_b128 v[196:199], v175 offset:34816
	ds_read_b128 v[200:203], v175 offset:35840
	ds_read_b128 v[204:207], v175 offset:36864
	ds_read_b128 v[208:211], v175 offset:37888
	ds_read_b128 v[212:215], v175 offset:38912
	ds_read_b128 v[216:219], v175 offset:39936
	global_load_lds_dwordx4 v[228:229], off
	v_lshl_add_u64 v[228:229], s[30:31], 0, v[146:147]
	s_mov_b32 m0, s42
	s_nop 0
	global_load_lds_dwordx4 v[228:229], off
	s_waitcnt vmcnt(8)
	s_waitcnt lgkmcnt(0)
	s_barrier
	s_setprio 1
	s_waitcnt lgkmcnt(0)
	v_mfma_f32_16x16x32_bf16 v[124:127], v[128:131], v[188:191], v[124:127]
	v_mfma_f32_16x16x32_bf16 v[108:111], v[128:131], v[196:199], v[108:111]
	v_mfma_f32_16x16x32_bf16 v[92:95], v[128:131], v[204:207], v[92:95]
	v_mfma_f32_16x16x32_bf16 v[76:79], v[128:131], v[212:215], v[76:79]
	v_mfma_f32_16x16x32_bf16 v[72:75], v[136:139], v[212:215], v[72:75]
	v_mfma_f32_16x16x32_bf16 v[88:91], v[136:139], v[204:207], v[88:91]
	v_mfma_f32_16x16x32_bf16 v[104:107], v[136:139], v[196:199], v[104:107]
	v_mfma_f32_16x16x32_bf16 v[120:123], v[136:139], v[188:191], v[120:123]
	v_mfma_f32_16x16x32_bf16 v[124:127], v[132:135], v[192:195], v[124:127]
	v_mfma_f32_16x16x32_bf16 v[108:111], v[132:135], v[200:203], v[108:111]
	v_mfma_f32_16x16x32_bf16 v[92:95], v[132:135], v[208:211], v[92:95]
	v_mfma_f32_16x16x32_bf16 v[76:79], v[132:135], v[216:219], v[76:79]
	v_mfma_f32_16x16x32_bf16 v[72:75], v[140:143], v[216:219], v[72:75]
	v_mfma_f32_16x16x32_bf16 v[88:91], v[140:143], v[208:211], v[88:91]
	v_mfma_f32_16x16x32_bf16 v[104:107], v[140:143], v[200:203], v[104:107]
	v_mfma_f32_16x16x32_bf16 v[120:123], v[140:143], v[192:195], v[120:123]
	s_setprio 0
	s_setprio 1
	v_mfma_f32_16x16x32_bf16 v[116:119], v[160:163], v[188:191], v[116:119]
	v_mfma_f32_16x16x32_bf16 v[100:103], v[160:163], v[196:199], v[100:103]
	v_mfma_f32_16x16x32_bf16 v[84:87], v[160:163], v[204:207], v[84:87]
	v_mfma_f32_16x16x32_bf16 v[68:71], v[160:163], v[212:215], v[68:71]
	v_mfma_f32_16x16x32_bf16 v[64:67], v[180:183], v[212:215], v[64:67]
	v_mfma_f32_16x16x32_bf16 v[80:83], v[180:183], v[204:207], v[80:83]
	v_mfma_f32_16x16x32_bf16 v[96:99], v[180:183], v[196:199], v[96:99]
	v_mfma_f32_16x16x32_bf16 v[112:115], v[180:183], v[188:191], v[112:115]
	v_mfma_f32_16x16x32_bf16 v[116:119], v[164:167], v[192:195], v[116:119]
	v_mfma_f32_16x16x32_bf16 v[100:103], v[164:167], v[200:203], v[100:103]
	v_mfma_f32_16x16x32_bf16 v[84:87], v[164:167], v[208:211], v[84:87]
	v_mfma_f32_16x16x32_bf16 v[68:71], v[164:167], v[216:219], v[68:71]
	v_mfma_f32_16x16x32_bf16 v[64:67], v[184:187], v[216:219], v[64:67]
	v_mfma_f32_16x16x32_bf16 v[80:83], v[184:187], v[208:211], v[80:83]
	v_mfma_f32_16x16x32_bf16 v[96:99], v[184:187], v[200:203], v[96:99]
	v_mfma_f32_16x16x32_bf16 v[112:115], v[184:187], v[192:195], v[112:115]
	s_setprio 0
	s_barrier
; #define PG8_STAGE(bufoff, gbase, voff) do { _Pragma("unroll") for (int _i = 0; _i < 2; ++_i) \
;         __builtin_amdgcn_global_load_lds((const unsigned*)((const char*)(gbase) + (voff)[_i]), (PG8_LAS unsigned*)(lds + (bufoff) + ldsw + _i * 8192), 16, 0, 0); } while (0)
; #define PG8_LDA(dst, b, h) do { _Pragma("unroll") for (int m = 0; m < 4; ++m) _Pragma("unroll") for (int k = 0; k < 2; ++k) dst[m][k] = *(const PG8_LAS bf16x8*)(lds + PG8_SA(b, h) + aoff + m * 2048 + k * 1024); } while (0)
; #define PG8_MMA(ai, bj, At, Bt) do { __builtin_amdgcn_s_setprio(1); _Pragma("unroll") for (int m = 0; m < 4; ++m) _Pragma("unroll") for (int n = 0; n < 2; ++n) _Pragma("unroll") for (int k = 0; k < 2; ++k) \
;         acc[ai][bj][m][n] = __builtin_amdgcn_mfma_f32_16x16x32_bf16(Bt[n][k], At[m][k], acc[ai][bj][m][n], 0, 0, 0); __builtin_amdgcn_s_setprio(0); } while (0)
; #define PG8_WAIT_V(n) asm volatile("s_waitcnt vmcnt(" #n ")" ::: "memory")
; #define PG8_WAIT_L(n) asm volatile("s_waitcnt lgkmcnt(" #n ")" ::: "memory")
; #define PG8_BAR __builtin_amdgcn_s_barrier()
; #define PG8_SCHED __builtin_amdgcn_sched_barrier(0)
; template <class Epi, class Sched, bool ALIGN_EPI = false, bool SP2 = false>
; __device__ __forceinline__ void gemm_phase(PG8_LAS unsigned char* lds, const Gemm g, const Sched& S, const Epi& E, const int wid) {
;     ...
;         for (int t = 0; t < nt; t += 2) {
;     ...
;             PG8_LDA(At, 1, 1); PG8_STAGE(PG8_SB(1, 0), b3, voffB); PG8_STAGE(PG8_SB(1, 1), b3 + hsB, voffB); PG8_STAGE(PG8_SA(1, 0), a3, voffA);
;             PG8_WAIT_V(8); PG8_WAIT_L(0); PG8_BAR; PG8_MMA(1, 0, At, B0); PG8_MMA(1, 1, At, B1); PG8_BAR; PG8_SCHED;
	s_add_i32 s30, s61, s36
	v_lshl_add_u64 v[220:221], v[220:221], 0, s[18:19]
	s_mov_b32 m0, s30
	ds_read_b128 v[188:191], v175 offset:49152
	ds_read_b128 v[192:195], v175 offset:50176
	ds_read_b128 v[196:199], v175 offset:51200
	ds_read_b128 v[200:203], v175 offset:52224
	ds_read_b128 v[204:207], v175 offset:53248
	ds_read_b128 v[208:211], v175 offset:54272
	ds_read_b128 v[212:215], v175 offset:55296
	ds_read_b128 v[216:219], v175 offset:56320
	global_load_lds_dwordx4 v[220:221], off
	s_add_i32 m0, s30, 0x2000
	s_add_u32 s8, s8, 0x80080
	v_lshl_add_u64 v[220:221], v[222:223], 0, s[18:19]
	s_addc_u32 s9, s9, 0
	s_add_i32 s30, s62, s36
	global_load_lds_dwordx4 v[220:221], off
	v_lshl_add_u64 v[220:221], s[8:9], 0, v[148:149]
	s_mov_b32 m0, s30
	s_nop 0
	global_load_lds_dwordx4 v[220:221], off
	v_lshl_add_u64 v[220:221], s[8:9], 0, v[144:145]
	s_add_i32 m0, s30, 0x2000
	s_nop 0
	global_load_lds_dwordx4 v[220:221], off
	v_lshl_add_u64 v[220:221], v[224:225], 0, s[18:19]
	s_mov_b32 m0, s45
	s_nop 0
	global_load_lds_dwordx4 v[220:221], off
	v_lshl_add_u64 v[220:221], v[226:227], 0, s[18:19]
	s_mov_b32 m0, s46
	s_nop 0
	global_load_lds_dwordx4 v[220:221], off
	s_waitcnt vmcnt(8)
	s_waitcnt lgkmcnt(0)
	s_barrier
	s_setprio 1
	s_waitcnt lgkmcnt(0)
	v_mfma_f32_16x16x32_bf16 v[60:63], v[128:131], v[188:191], v[60:63]
	v_mfma_f32_16x16x32_bf16 v[44:47], v[128:131], v[196:199], v[44:47]
	v_mfma_f32_16x16x32_bf16 v[28:31], v[128:131], v[204:207], v[28:31]
	v_mfma_f32_16x16x32_bf16 v[12:15], v[128:131], v[212:215], v[12:15]
	v_mfma_f32_16x16x32_bf16 v[8:11], v[136:139], v[212:215], v[8:11]
	v_mfma_f32_16x16x32_bf16 v[24:27], v[136:139], v[204:207], v[24:27]
	v_mfma_f32_16x16x32_bf16 v[40:43], v[136:139], v[196:199], v[40:43]
	v_mfma_f32_16x16x32_bf16 v[56:59], v[136:139], v[188:191], v[56:59]
	v_mfma_f32_16x16x32_bf16 v[60:63], v[132:135], v[192:195], v[60:63]
	v_mfma_f32_16x16x32_bf16 v[44:47], v[132:135], v[200:203], v[44:47]
	v_mfma_f32_16x16x32_bf16 v[28:31], v[132:135], v[208:211], v[28:31]
	v_mfma_f32_16x16x32_bf16 v[12:15], v[132:135], v[216:219], v[12:15]
	v_mfma_f32_16x16x32_bf16 v[8:11], v[140:143], v[216:219], v[8:11]
	v_mfma_f32_16x16x32_bf16 v[24:27], v[140:143], v[208:211], v[24:27]
	v_mfma_f32_16x16x32_bf16 v[40:43], v[140:143], v[200:203], v[40:43]
	v_mfma_f32_16x16x32_bf16 v[56:59], v[140:143], v[192:195], v[56:59]
	s_setprio 0
	s_setprio 1
	v_mfma_f32_16x16x32_bf16 v[52:55], v[160:163], v[188:191], v[52:55]
	v_mfma_f32_16x16x32_bf16 v[36:39], v[160:163], v[196:199], v[36:39]
	v_mfma_f32_16x16x32_bf16 v[20:23], v[160:163], v[204:207], v[20:23]
	v_mfma_f32_16x16x32_bf16 v[4:7], v[160:163], v[212:215], v[4:7]
	v_mfma_f32_16x16x32_bf16 v[0:3], v[180:183], v[212:215], v[0:3]
	v_mfma_f32_16x16x32_bf16 v[16:19], v[180:183], v[204:207], v[16:19]
	v_mfma_f32_16x16x32_bf16 v[32:35], v[180:183], v[196:199], v[32:35]
	v_mfma_f32_16x16x32_bf16 v[48:51], v[180:183], v[188:191], v[48:51]
	v_mfma_f32_16x16x32_bf16 v[52:55], v[164:167], v[192:195], v[52:55]
	v_mfma_f32_16x16x32_bf16 v[36:39], v[164:167], v[200:203], v[36:39]
	v_mfma_f32_16x16x32_bf16 v[20:23], v[164:167], v[208:211], v[20:23]
	v_mfma_f32_16x16x32_bf16 v[4:7], v[164:167], v[216:219], v[4:7]
	v_mfma_f32_16x16x32_bf16 v[0:3], v[184:187], v[216:219], v[0:3]
	v_mfma_f32_16x16x32_bf16 v[16:19], v[184:187], v[208:211], v[16:19]
	v_mfma_f32_16x16x32_bf16 v[32:35], v[184:187], v[200:203], v[32:35]
	v_mfma_f32_16x16x32_bf16 v[48:51], v[184:187], v[192:195], v[48:51]
	s_setprio 0
	s_barrier
	s_add_i32 s60, s60, 2
	s_add_u32 s58, s58, 0x100
	s_addc_u32 s59, s59, 0
	s_add_u32 s6, s6, 0x100
	s_addc_u32 s7, s7, 0
	s_cmp_gt_u32 s60, 29
	s_cbranch_scc0 .LBB0_1385
	s_and_b64 vcc, exec, s[20:21]
	s_cbranch_vccz .LBB0_1388
	s_barrier

; #define PG8_STAGE(bufoff, gbase, voff) do { _Pragma("unroll") for (int _i = 0; _i < 2; ++_i) \
;         __builtin_amdgcn_global_load_lds((const unsigned*)((const char*)(gbase) + (voff)[_i]), (PG8_LAS unsigned*)(lds + (bufoff) + ldsw + _i * 8192), 16, 0, 0); } while (0)
; #define PG8_LDA(dst, b, h) do { _Pragma("unroll") for (int m = 0; m < 4; ++m) _Pragma("unroll") for (int k = 0; k < 2; ++k) dst[m][k] = *(const PG8_LAS bf16x8*)(lds + PG8_SA(b, h) + aoff + m * 2048 + k * 1024); } while (0)
; #define PG8_LDB(dst, b, h) do { _Pragma("unroll") for (int n = 0; n < 2; ++n) _Pragma("unroll") for (int k = 0; k < 2; ++k) dst[n][k] = *(const PG8_LAS bf16x8*)(lds + PG8_SB(b, h) + boff + n * 2048 + k * 1024); } while (0)
; #define PG8_MMA(ai, bj, At, Bt) do { __builtin_amdgcn_s_setprio(1); _Pragma("unroll") for (int m = 0; m < 4; ++m) _Pragma("unroll") for (int n = 0; n < 2; ++n) _Pragma("unroll") for (int k = 0; k < 2; ++k) \
;         acc[ai][bj][m][n] = __builtin_amdgcn_mfma_f32_16x16x32_bf16(Bt[n][k], At[m][k], acc[ai][bj][m][n], 0, 0, 0); __builtin_amdgcn_s_setprio(0); } while (0)
; #define PG8_WAIT_V(n) asm volatile("s_waitcnt vmcnt(" #n ")" ::: "memory")
; #define PG8_WAIT_L(n) asm volatile("s_waitcnt lgkmcnt(" #n ")" ::: "memory")
; #define PG8_BAR __builtin_amdgcn_s_barrier()
; #define PG8_SCHED __builtin_amdgcn_sched_barrier(0)
; template <class Epi, class Sched, bool ALIGN_EPI = false, bool SP2 = false>
; __device__ __forceinline__ void gemm_phase(PG8_LAS unsigned char* lds, const Gemm g, const Sched& S, const Epi& E, const int wid) {
;     ...
;             PG8_LDB(B0, 0, 0); PG8_LDB(B1, 0, 1); PG8_SCHED; PG8_LDA(At, 0, 0); PG8_STAGE(PG8_SA(1, 1), a1 + hsA, voffA);
;             PG8_WAIT_V(8); PG8_WAIT_L(0); PG8_BAR; PG8_MMA(0, 0, At, B0); PG8_MMA(0, 1, At, B1); PG8_BAR; PG8_SCHED;
;             PG8_LDA(At, 0, 1); PG8_STAGE(PG8_SB(0, 0), b2, voffB); PG8_STAGE(PG8_SB(0, 1), b2 + hsB, voffB); PG8_STAGE(PG8_SA(0, 0), a2, voffA);
;             PG8_WAIT_V(8); PG8_WAIT_L(0); PG8_BAR; PG8_MMA(1, 0, At, B0); PG8_MMA(1, 1, At, B1); PG8_BAR; PG8_SCHED;
.LBB0_1462:
	ds_read_b128 v[128:131], v163
	ds_read_b128 v[132:135], v163 offset:1024
	ds_read_b128 v[136:139], v163 offset:2048
	ds_read_b128 v[140:143], v163 offset:3072
	ds_read_b128 v[156:159], v164
	ds_read_b128 v[166:169], v164 offset:1024
	ds_read_b128 v[170:173], v164 offset:2048
	ds_read_b128 v[174:177], v164 offset:3072
	s_add_u32 s28, s26, 0x100
	s_addc_u32 s29, s27, 0
	s_cmpk_eq_i32 s58, 0x54
	s_cselect_b32 s35, s5, s29
	s_cselect_b32 s34, s4, s28
	s_cselect_b32 s31, s25, s57
	s_cselect_b32 s30, s24, s56
	v_lshl_add_u64 v[160:161], s[26:27], 0, v[150:151]
	s_add_i32 m0, s40, 0xc000
	ds_read_b128 v[178:181], v165
	ds_read_b128 v[182:185], v165 offset:1024
	ds_read_b128 v[186:189], v165 offset:2048
	ds_read_b128 v[190:193], v165 offset:3072
	ds_read_b128 v[194:197], v165 offset:4096
	ds_read_b128 v[198:201], v165 offset:5120
	ds_read_b128 v[202:205], v165 offset:6144
	ds_read_b128 v[206:209], v165 offset:7168
	global_load_lds_dwordx4 v[160:161], off
	v_lshl_add_u64 v[160:161], s[26:27], 0, v[148:149]
	s_add_i32 m0, s40, 0xe000
	s_nop 0
	global_load_lds_dwordx4 v[160:161], off
	s_waitcnt vmcnt(8)
	s_waitcnt lgkmcnt(0)
	s_barrier
	s_setprio 1
	s_waitcnt lgkmcnt(0)
	v_mfma_f32_16x16x32_bf16 v[124:127], v[128:131], v[178:181], v[124:127]
	v_mfma_f32_16x16x32_bf16 v[116:119], v[128:131], v[186:189], v[116:119]
	v_mfma_f32_16x16x32_bf16 v[92:95], v[128:131], v[194:197], v[92:95]
	v_mfma_f32_16x16x32_bf16 v[84:87], v[128:131], v[202:205], v[84:87]
	v_mfma_f32_16x16x32_bf16 v[80:83], v[136:139], v[202:205], v[80:83]
	v_mfma_f32_16x16x32_bf16 v[88:91], v[136:139], v[194:197], v[88:91]
	v_mfma_f32_16x16x32_bf16 v[112:115], v[136:139], v[186:189], v[112:115]
	v_mfma_f32_16x16x32_bf16 v[120:123], v[136:139], v[178:181], v[120:123]
	v_mfma_f32_16x16x32_bf16 v[124:127], v[132:135], v[182:185], v[124:127]
	v_mfma_f32_16x16x32_bf16 v[116:119], v[132:135], v[190:193], v[116:119]
	v_mfma_f32_16x16x32_bf16 v[92:95], v[132:135], v[198:201], v[92:95]
	v_mfma_f32_16x16x32_bf16 v[84:87], v[132:135], v[206:209], v[84:87]
	v_mfma_f32_16x16x32_bf16 v[80:83], v[140:143], v[206:209], v[80:83]
	v_mfma_f32_16x16x32_bf16 v[88:91], v[140:143], v[198:201], v[88:91]
	v_mfma_f32_16x16x32_bf16 v[112:115], v[140:143], v[190:193], v[112:115]
	v_mfma_f32_16x16x32_bf16 v[120:123], v[140:143], v[182:185], v[120:123]
	s_setprio 0
	s_setprio 1
	v_mfma_f32_16x16x32_bf16 v[108:111], v[156:159], v[178:181], v[108:111]
	v_mfma_f32_16x16x32_bf16 v[100:103], v[156:159], v[186:189], v[100:103]
	v_mfma_f32_16x16x32_bf16 v[76:79], v[156:159], v[194:197], v[76:79]
	v_mfma_f32_16x16x32_bf16 v[68:71], v[156:159], v[202:205], v[68:71]
	v_mfma_f32_16x16x32_bf16 v[64:67], v[170:173], v[202:205], v[64:67]
	v_mfma_f32_16x16x32_bf16 v[72:75], v[170:173], v[194:197], v[72:75]
	v_mfma_f32_16x16x32_bf16 v[96:99], v[170:173], v[186:189], v[96:99]
	v_mfma_f32_16x16x32_bf16 v[104:107], v[170:173], v[178:181], v[104:107]
	v_mfma_f32_16x16x32_bf16 v[108:111], v[166:169], v[182:185], v[108:111]
	v_mfma_f32_16x16x32_bf16 v[100:103], v[166:169], v[190:193], v[100:103]
	v_mfma_f32_16x16x32_bf16 v[76:79], v[166:169], v[198:201], v[76:79]
	v_mfma_f32_16x16x32_bf16 v[68:71], v[166:169], v[206:209], v[68:71]
	v_mfma_f32_16x16x32_bf16 v[64:67], v[174:177], v[206:209], v[64:67]
	v_mfma_f32_16x16x32_bf16 v[72:75], v[174:177], v[198:201], v[72:75]
	v_mfma_f32_16x16x32_bf16 v[96:99], v[174:177], v[190:193], v[96:99]
	v_mfma_f32_16x16x32_bf16 v[104:107], v[174:177], v[182:185], v[104:107]
	s_setprio 0
	s_barrier
	s_add_i32 s26, s50, s39
	v_lshl_add_u64 v[160:161], s[30:31], 0, v[144:145]
	s_mov_b32 m0, s26
	ds_read_b128 v[178:181], v165 offset:16384
	ds_read_b128 v[182:185], v165 offset:17408
	ds_read_b128 v[186:189], v165 offset:18432
	ds_read_b128 v[190:193], v165 offset:19456
	ds_read_b128 v[194:197], v165 offset:20480
	ds_read_b128 v[198:201], v165 offset:21504
	ds_read_b128 v[202:205], v165 offset:22528
	ds_read_b128 v[206:209], v165 offset:23552
	global_load_lds_dwordx4 v[160:161], off
	s_add_i32 m0, s26, 0x2000
	s_add_u32 s26, s30, 0x160000
	v_lshl_add_u64 v[210:211], s[30:31], 0, v[146:147]
	s_addc_u32 s27, s31, 0
	s_add_i32 s59, s51, s39
	global_load_lds_dwordx4 v[210:211], off
	v_lshl_add_u64 v[212:213], s[26:27], 0, v[144:145]
	s_mov_b32 m0, s59
	v_lshl_add_u64 v[214:215], s[34:35], 0, v[146:147]
	global_load_lds_dwordx4 v[212:213], off
	v_lshl_add_u64 v[212:213], s[26:27], 0, v[146:147]
	s_add_i32 m0, s59, 0x2000
	s_nop 0
	global_load_lds_dwordx4 v[212:213], off
	v_lshl_add_u64 v[212:213], s[34:35], 0, v[144:145]
	s_mov_b32 m0, s40
	s_nop 0
	global_load_lds_dwordx4 v[212:213], off
	s_mov_b32 m0, s41
	s_nop 0
	global_load_lds_dwordx4 v[214:215], off
	s_waitcnt vmcnt(8)
	s_waitcnt lgkmcnt(0)
	s_barrier
; #define PG8_STAGE(bufoff, gbase, voff) do { _Pragma("unroll") for (int _i = 0; _i < 2; ++_i) \
;         __builtin_amdgcn_global_load_lds((const unsigned*)((const char*)(gbase) + (voff)[_i]), (PG8_LAS unsigned*)(lds + (bufoff) + ldsw + _i * 8192), 16, 0, 0); } while (0)
; #define PG8_LDA(dst, b, h) do { _Pragma("unroll") for (int m = 0; m < 4; ++m) _Pragma("unroll") for (int k = 0; k < 2; ++k) dst[m][k] = *(const PG8_LAS bf16x8*)(lds + PG8_SA(b, h) + aoff + m * 2048 + k * 1024); } while (0)
; #define PG8_LDB(dst, b, h) do { _Pragma("unroll") for (int n = 0; n < 2; ++n) _Pragma("unroll") for (int k = 0; k < 2; ++k) dst[n][k] = *(const PG8_LAS bf16x8*)(lds + PG8_SB(b, h) + boff + n * 2048 + k * 1024); } while (0)
; #define PG8_MMA(ai, bj, At, Bt) do { __builtin_amdgcn_s_setprio(1); _Pragma("unroll") for (int m = 0; m < 4; ++m) _Pragma("unroll") for (int n = 0; n < 2; ++n) _Pragma("unroll") for (int k = 0; k < 2; ++k) \
;         acc[ai][bj][m][n] = __builtin_amdgcn_mfma_f32_16x16x32_bf16(Bt[n][k], At[m][k], acc[ai][bj][m][n], 0, 0, 0); __builtin_amdgcn_s_setprio(0); } while (0)
; #define PG8_WAIT_V(n) asm volatile("s_waitcnt vmcnt(" #n ")" ::: "memory")
; #define PG8_WAIT_L(n) asm volatile("s_waitcnt lgkmcnt(" #n ")" ::: "memory")
; #define PG8_BAR __builtin_amdgcn_s_barrier()
; #define PG8_SCHED __builtin_amdgcn_sched_barrier(0)
; template <class Epi, class Sched, bool ALIGN_EPI = false, bool SP2 = false>
; __device__ __forceinline__ void gemm_phase(PG8_LAS unsigned char* lds, const Gemm g, const Sched& S, const Epi& E, const int wid) {
;     ...
;             PG8_WAIT_V(8); PG8_WAIT_L(0); PG8_BAR; PG8_MMA(1, 0, At, B0); PG8_MMA(1, 1, At, B1); PG8_BAR; PG8_SCHED;
;             PG8_LDB(B0, 1, 0); PG8_LDB(B1, 1, 1); PG8_SCHED; PG8_LDA(At, 1, 0); PG8_STAGE(PG8_SA(0, 1), a2 + hsA, voffA);
;             PG8_WAIT_V(8); PG8_WAIT_L(0); PG8_BAR; PG8_MMA(0, 0, At, B0); PG8_MMA(0, 1, At, B1); PG8_BAR; PG8_SCHED;
	s_setprio 1
	s_waitcnt lgkmcnt(0)
	v_mfma_f32_16x16x32_bf16 v[60:63], v[128:131], v[178:181], v[60:63]
	v_mfma_f32_16x16x32_bf16 v[52:55], v[128:131], v[186:189], v[52:55]
	v_mfma_f32_16x16x32_bf16 v[28:31], v[128:131], v[194:197], v[28:31]
	v_mfma_f32_16x16x32_bf16 v[20:23], v[128:131], v[202:205], v[20:23]
	v_mfma_f32_16x16x32_bf16 v[16:19], v[136:139], v[202:205], v[16:19]
	v_mfma_f32_16x16x32_bf16 v[24:27], v[136:139], v[194:197], v[24:27]
	v_mfma_f32_16x16x32_bf16 v[48:51], v[136:139], v[186:189], v[48:51]
	v_mfma_f32_16x16x32_bf16 v[56:59], v[136:139], v[178:181], v[56:59]
	v_mfma_f32_16x16x32_bf16 v[60:63], v[132:135], v[182:185], v[60:63]
	v_mfma_f32_16x16x32_bf16 v[52:55], v[132:135], v[190:193], v[52:55]
	v_mfma_f32_16x16x32_bf16 v[28:31], v[132:135], v[198:201], v[28:31]
	v_mfma_f32_16x16x32_bf16 v[20:23], v[132:135], v[206:209], v[20:23]
	v_mfma_f32_16x16x32_bf16 v[16:19], v[140:143], v[206:209], v[16:19]
	v_mfma_f32_16x16x32_bf16 v[24:27], v[140:143], v[198:201], v[24:27]
	v_mfma_f32_16x16x32_bf16 v[48:51], v[140:143], v[190:193], v[48:51]
	v_mfma_f32_16x16x32_bf16 v[56:59], v[140:143], v[182:185], v[56:59]
	s_setprio 0
	s_setprio 1
	v_mfma_f32_16x16x32_bf16 v[44:47], v[156:159], v[178:181], v[44:47]
	v_mfma_f32_16x16x32_bf16 v[36:39], v[156:159], v[186:189], v[36:39]
	v_mfma_f32_16x16x32_bf16 v[12:15], v[156:159], v[194:197], v[12:15]
	v_mfma_f32_16x16x32_bf16 v[4:7], v[156:159], v[202:205], v[4:7]
	v_mfma_f32_16x16x32_bf16 v[0:3], v[170:173], v[202:205], v[0:3]
	v_mfma_f32_16x16x32_bf16 v[8:11], v[170:173], v[194:197], v[8:11]
	v_mfma_f32_16x16x32_bf16 v[32:35], v[170:173], v[186:189], v[32:35]
	v_mfma_f32_16x16x32_bf16 v[40:43], v[170:173], v[178:181], v[40:43]
	v_mfma_f32_16x16x32_bf16 v[44:47], v[166:169], v[182:185], v[44:47]
	v_mfma_f32_16x16x32_bf16 v[36:39], v[166:169], v[190:193], v[36:39]
	v_mfma_f32_16x16x32_bf16 v[12:15], v[166:169], v[198:201], v[12:15]
	v_mfma_f32_16x16x32_bf16 v[4:7], v[166:169], v[206:209], v[4:7]
	v_mfma_f32_16x16x32_bf16 v[0:3], v[174:177], v[206:209], v[0:3]
	v_mfma_f32_16x16x32_bf16 v[8:11], v[174:177], v[198:201], v[8:11]
	v_mfma_f32_16x16x32_bf16 v[32:35], v[174:177], v[190:193], v[32:35]
	v_mfma_f32_16x16x32_bf16 v[40:43], v[174:177], v[182:185], v[40:43]
	s_setprio 0
	s_barrier
	s_add_i32 s59, 0, 0x18000
	s_add_i32 s60, 0, 0x1c000
	v_add_u32_e32 v140, s59, v162
	v_add_u32_e32 v174, s60, v162
	ds_read_b128 v[128:131], v140
	ds_read_b128 v[132:135], v140 offset:1024
	ds_read_b128 v[136:139], v140 offset:2048
	ds_read_b128 v[140:143], v140 offset:3072
	ds_read_b128 v[156:159], v174
	ds_read_b128 v[166:169], v174 offset:1024
	ds_read_b128 v[170:173], v174 offset:2048
	ds_read_b128 v[174:177], v174 offset:3072
	s_add_u32 s26, s34, 0x160000
	s_addc_u32 s27, s35, 0
	s_mov_b32 m0, s42
	v_lshl_add_u64 v[216:217], s[26:27], 0, v[144:145]
	ds_read_b128 v[178:181], v165 offset:32768
	ds_read_b128 v[182:185], v165 offset:33792
	ds_read_b128 v[186:189], v165 offset:34816
	ds_read_b128 v[190:193], v165 offset:35840
	ds_read_b128 v[194:197], v165 offset:36864
	ds_read_b128 v[198:201], v165 offset:37888
	ds_read_b128 v[202:205], v165 offset:38912
	ds_read_b128 v[206:209], v165 offset:39936
	global_load_lds_dwordx4 v[216:217], off
	v_lshl_add_u64 v[216:217], s[26:27], 0, v[146:147]
	s_mov_b32 m0, s43
	s_nop 0
	global_load_lds_dwordx4 v[216:217], off
	s_waitcnt vmcnt(8)
	s_waitcnt lgkmcnt(0)
	s_barrier
	s_setprio 1
	s_waitcnt lgkmcnt(0)
	v_mfma_f32_16x16x32_bf16 v[124:127], v[128:131], v[178:181], v[124:127]
	v_mfma_f32_16x16x32_bf16 v[116:119], v[128:131], v[186:189], v[116:119]
	v_mfma_f32_16x16x32_bf16 v[92:95], v[128:131], v[194:197], v[92:95]
	v_mfma_f32_16x16x32_bf16 v[84:87], v[128:131], v[202:205], v[84:87]
	v_mfma_f32_16x16x32_bf16 v[80:83], v[136:139], v[202:205], v[80:83]
	v_mfma_f32_16x16x32_bf16 v[88:91], v[136:139], v[194:197], v[88:91]
	v_mfma_f32_16x16x32_bf16 v[112:115], v[136:139], v[186:189], v[112:115]
	v_mfma_f32_16x16x32_bf16 v[120:123], v[136:139], v[178:181], v[120:123]
	v_mfma_f32_16x16x32_bf16 v[124:127], v[132:135], v[182:185], v[124:127]
	v_mfma_f32_16x16x32_bf16 v[116:119], v[132:135], v[190:193], v[116:119]
	v_mfma_f32_16x16x32_bf16 v[92:95], v[132:135], v[198:201], v[92:95]
	v_mfma_f32_16x16x32_bf16 v[84:87], v[132:135], v[206:209], v[84:87]
	v_mfma_f32_16x16x32_bf16 v[80:83], v[140:143], v[206:209], v[80:83]
	v_mfma_f32_16x16x32_bf16 v[88:91], v[140:143], v[198:201], v[88:91]
	v_mfma_f32_16x16x32_bf16 v[112:115], v[140:143], v[190:193], v[112:115]
	v_mfma_f32_16x16x32_bf16 v[120:123], v[140:143], v[182:185], v[120:123]
	s_setprio 0
	s_setprio 1
	v_mfma_f32_16x16x32_bf16 v[108:111], v[156:159], v[178:181], v[108:111]
	v_mfma_f32_16x16x32_bf16 v[100:103], v[156:159], v[186:189], v[100:103]
	v_mfma_f32_16x16x32_bf16 v[76:79], v[156:159], v[194:197], v[76:79]
	v_mfma_f32_16x16x32_bf16 v[68:71], v[156:159], v[202:205], v[68:71]
	v_mfma_f32_16x16x32_bf16 v[64:67], v[170:173], v[202:205], v[64:67]
	v_mfma_f32_16x16x32_bf16 v[72:75], v[170:173], v[194:197], v[72:75]
	v_mfma_f32_16x16x32_bf16 v[96:99], v[170:173], v[186:189], v[96:99]
	v_mfma_f32_16x16x32_bf16 v[104:107], v[170:173], v[178:181], v[104:107]
	v_mfma_f32_16x16x32_bf16 v[108:111], v[166:169], v[182:185], v[108:111]
	v_mfma_f32_16x16x32_bf16 v[100:103], v[166:169], v[190:193], v[100:103]
	v_mfma_f32_16x16x32_bf16 v[76:79], v[166:169], v[198:201], v[76:79]
	v_mfma_f32_16x16x32_bf16 v[68:71], v[166:169], v[206:209], v[68:71]
	v_mfma_f32_16x16x32_bf16 v[64:67], v[174:177], v[206:209], v[64:67]
	v_mfma_f32_16x16x32_bf16 v[72:75], v[174:177], v[198:201], v[72:75]
	v_mfma_f32_16x16x32_bf16 v[96:99], v[174:177], v[190:193], v[96:99]
	v_mfma_f32_16x16x32_bf16 v[104:107], v[174:177], v[182:185], v[104:107]
	s_setprio 0
	s_barrier
; #define PG8_STAGE(bufoff, gbase, voff) do { _Pragma("unroll") for (int _i = 0; _i < 2; ++_i) \
;         __builtin_amdgcn_global_load_lds((const unsigned*)((const char*)(gbase) + (voff)[_i]), (PG8_LAS unsigned*)(lds + (bufoff) + ldsw + _i * 8192), 16, 0, 0); } while (0)
; #define PG8_LDA(dst, b, h) do { _Pragma("unroll") for (int m = 0; m < 4; ++m) _Pragma("unroll") for (int k = 0; k < 2; ++k) dst[m][k] = *(const PG8_LAS bf16x8*)(lds + PG8_SA(b, h) + aoff + m * 2048 + k * 1024); } while (0)
; #define PG8_MMA(ai, bj, At, Bt) do { __builtin_amdgcn_s_setprio(1); _Pragma("unroll") for (int m = 0; m < 4; ++m) _Pragma("unroll") for (int n = 0; n < 2; ++n) _Pragma("unroll") for (int k = 0; k < 2; ++k) \
;         acc[ai][bj][m][n] = __builtin_amdgcn_mfma_f32_16x16x32_bf16(Bt[n][k], At[m][k], acc[ai][bj][m][n], 0, 0, 0); __builtin_amdgcn_s_setprio(0); } while (0)
; #define PG8_WAIT_V(n) asm volatile("s_waitcnt vmcnt(" #n ")" ::: "memory")
; #define PG8_WAIT_L(n) asm volatile("s_waitcnt lgkmcnt(" #n ")" ::: "memory")
; #define PG8_BAR __builtin_amdgcn_s_barrier()
; #define PG8_SCHED __builtin_amdgcn_sched_barrier(0)
; template <class Epi, class Sched, bool ALIGN_EPI = false, bool SP2 = false>
; __device__ __forceinline__ void gemm_phase(PG8_LAS unsigned char* lds, const Gemm g, const Sched& S, const Epi& E, const int wid) {
;     ...
;         for (int t = 0; t < nt; t += 2) {
;     ...
;             PG8_LDA(At, 1, 1); PG8_STAGE(PG8_SB(1, 0), b3, voffB); PG8_STAGE(PG8_SB(1, 1), b3 + hsB, voffB); PG8_STAGE(PG8_SA(1, 0), a3, voffA);
;             PG8_WAIT_V(8); PG8_WAIT_L(0); PG8_BAR; PG8_MMA(1, 0, At, B0); PG8_MMA(1, 1, At, B1); PG8_BAR; PG8_SCHED;
	s_add_i32 s26, s59, s39
	v_lshl_add_u64 v[160:161], v[160:161], 0, s[14:15]
	s_mov_b32 m0, s26
	ds_read_b128 v[178:181], v165 offset:49152
	ds_read_b128 v[182:185], v165 offset:50176
	ds_read_b128 v[186:189], v165 offset:51200
	ds_read_b128 v[190:193], v165 offset:52224
	ds_read_b128 v[194:197], v165 offset:53248
	ds_read_b128 v[198:201], v165 offset:54272
	ds_read_b128 v[202:205], v165 offset:55296
	ds_read_b128 v[206:209], v165 offset:56320
	global_load_lds_dwordx4 v[160:161], off
	s_add_i32 m0, s26, 0x2000
	s_add_u32 s26, s30, 0x160080
	v_lshl_add_u64 v[160:161], v[210:211], 0, s[14:15]
	s_addc_u32 s27, s31, 0
	s_add_i32 s30, s60, s39
	global_load_lds_dwordx4 v[160:161], off
	v_lshl_add_u64 v[160:161], s[26:27], 0, v[144:145]
	s_mov_b32 m0, s30
	s_nop 0
	global_load_lds_dwordx4 v[160:161], off
	v_lshl_add_u64 v[160:161], s[26:27], 0, v[146:147]
	s_add_i32 m0, s30, 0x2000
	s_nop 0
	global_load_lds_dwordx4 v[160:161], off
	v_lshl_add_u64 v[160:161], v[212:213], 0, s[14:15]
	s_mov_b32 m0, s47
	s_nop 0
	global_load_lds_dwordx4 v[160:161], off
	v_lshl_add_u64 v[160:161], v[214:215], 0, s[14:15]
	s_mov_b32 m0, s48
	s_nop 0
	global_load_lds_dwordx4 v[160:161], off
	s_waitcnt vmcnt(8)
	s_waitcnt lgkmcnt(0)
	s_barrier
	s_setprio 1
	s_waitcnt lgkmcnt(0)
	v_mfma_f32_16x16x32_bf16 v[60:63], v[128:131], v[178:181], v[60:63]
	v_mfma_f32_16x16x32_bf16 v[52:55], v[128:131], v[186:189], v[52:55]
	v_mfma_f32_16x16x32_bf16 v[28:31], v[128:131], v[194:197], v[28:31]
	v_mfma_f32_16x16x32_bf16 v[20:23], v[128:131], v[202:205], v[20:23]
	v_mfma_f32_16x16x32_bf16 v[16:19], v[136:139], v[202:205], v[16:19]
	v_mfma_f32_16x16x32_bf16 v[24:27], v[136:139], v[194:197], v[24:27]
	v_mfma_f32_16x16x32_bf16 v[48:51], v[136:139], v[186:189], v[48:51]
	v_mfma_f32_16x16x32_bf16 v[56:59], v[136:139], v[178:181], v[56:59]
	v_mfma_f32_16x16x32_bf16 v[60:63], v[132:135], v[182:185], v[60:63]
	v_mfma_f32_16x16x32_bf16 v[52:55], v[132:135], v[190:193], v[52:55]
	v_mfma_f32_16x16x32_bf16 v[28:31], v[132:135], v[198:201], v[28:31]
	v_mfma_f32_16x16x32_bf16 v[20:23], v[132:135], v[206:209], v[20:23]
	v_mfma_f32_16x16x32_bf16 v[16:19], v[140:143], v[206:209], v[16:19]
	v_mfma_f32_16x16x32_bf16 v[24:27], v[140:143], v[198:201], v[24:27]
	v_mfma_f32_16x16x32_bf16 v[48:51], v[140:143], v[190:193], v[48:51]
	v_mfma_f32_16x16x32_bf16 v[56:59], v[140:143], v[182:185], v[56:59]
	s_setprio 0
	s_setprio 1
	v_mfma_f32_16x16x32_bf16 v[44:47], v[156:159], v[178:181], v[44:47]
	v_mfma_f32_16x16x32_bf16 v[36:39], v[156:159], v[186:189], v[36:39]
	v_mfma_f32_16x16x32_bf16 v[12:15], v[156:159], v[194:197], v[12:15]
	v_mfma_f32_16x16x32_bf16 v[4:7], v[156:159], v[202:205], v[4:7]
	v_mfma_f32_16x16x32_bf16 v[0:3], v[170:173], v[202:205], v[0:3]
	v_mfma_f32_16x16x32_bf16 v[8:11], v[170:173], v[194:197], v[8:11]
	v_mfma_f32_16x16x32_bf16 v[32:35], v[170:173], v[186:189], v[32:35]
	v_mfma_f32_16x16x32_bf16 v[40:43], v[170:173], v[178:181], v[40:43]
	v_mfma_f32_16x16x32_bf16 v[44:47], v[166:169], v[182:185], v[44:47]
	v_mfma_f32_16x16x32_bf16 v[36:39], v[166:169], v[190:193], v[36:39]
	v_mfma_f32_16x16x32_bf16 v[12:15], v[166:169], v[198:201], v[12:15]
	v_mfma_f32_16x16x32_bf16 v[4:7], v[166:169], v[206:209], v[4:7]
	v_mfma_f32_16x16x32_bf16 v[0:3], v[174:177], v[206:209], v[0:3]
	v_mfma_f32_16x16x32_bf16 v[8:11], v[174:177], v[198:201], v[8:11]
	v_mfma_f32_16x16x32_bf16 v[32:35], v[174:177], v[190:193], v[32:35]
	v_mfma_f32_16x16x32_bf16 v[40:43], v[174:177], v[182:185], v[40:43]
	s_setprio 0
	s_barrier
	s_add_i32 s58, s58, 2
	s_add_u32 s56, s56, 0x100
	s_addc_u32 s57, s57, 0
	s_cmpk_gt_u32 s58, 0x55
	s_mov_b64 s[26:27], s[28:29]
	s_cbranch_scc0 .LBB0_1462
	s_and_b64 vcc, exec, s[16:17]
	s_cbranch_vccz .LBB0_1465
	s_barrier
